# full stack + sc0 (L1-bypass scope) on all 222 LDS-DMA operand loads of the GEMM phases
# baseline (speedup 1.0000x reference)
; #define PG8_STAGE(bufoff, gbase, voff) do { _Pragma("unroll") for (int _i = 0; _i < 2; ++_i) \
;         __builtin_amdgcn_global_load_lds((const unsigned*)((const char*)(gbase) + (voff)[_i]), (LAS unsigned*)(lds + (bufoff) + ldsw + _i * 8192), 16, 0, 0); } while (0)
; #define PG8_WAIT_V(n) asm volatile("s_waitcnt vmcnt(" #n ")" ::: "memory")
; #define PG8_BAR __builtin_amdgcn_s_barrier()
; template <class Epi, class Order = StaticOrder, bool HALFN = false>
; __device__ __forceinline__ void gemm_phase(LAS unsigned char* lds, const Gemm g, const Epi& E) {
;     ...
;     Order S; S.init(g.nM, g.nN, (int)gridDim.x, (int)blockIdx.x); S.lx = g.lx; S.lr = g.lr;
;     unsigned voffA[2], voffB[2];
; #pragma unroll
;     for (int i = 0; i < 2; ++i) { int R, C; stage_rc(tid * 16 + i * 8192, R, C); const int Rb = (R & ~31) + perm32(R & 31);
;         voffA[i] = (unsigned)(R * g.lda + C) * 2u; voffB[i] = (unsigned)(Rb * g.ldb + C) * 2u; }
;     const size_t kstep = (size_t)(BK * 2);
;     const size_t hstepA = (size_t)HALF * g.lda * 2, hstepB = (size_t)HALF * g.ldb * 2;
;     const size_t tstepA = 2 * hstepA, tstepB = 2 * hstepB;
;     const unsigned ldsw = (unsigned)wid * 1024u;
;     const int aoff = lds_byte(wr * 64 + fr, fq * 8), boff = lds_byte(wc * 32 + fr, fq * 8);
;     ...
;     Unit cur, nxt; int ui = 0;
;     if (!S.next(0, cur)) return;
;     f32x4 acc[2][2][4][2];
;     if constexpr (Epi::INIT) E.init(acc, cur, wr, wc, fr, fq);
;     else {
; #pragma unroll
;     for (int a = 0; a < 2; ++a)
; #pragma unroll
;         for (int b = 0; b < 2; ++b)
; #pragma unroll
;             for (int m = 0; m < 4; ++m)
; #pragma unroll
;                 for (int n = 0; n < 2; ++n) acc[a][b][m][n] = (f32x4){0.f, 0.f, 0.f, 0.f};
;     }
;     bf16x8 At[4][2], B0[2][2], B1[2][2];
;     const char* cA = (const char*)g.A + (size_t)cur.pm * tstepA + (size_t)cur.pn * g.a_pn_off * 2; const char* cB = (const char*)g.Bt + (size_t)cur.pn * tstepB + (HALFN ? (size_t)(cur.half - 1) * hstepB : (size_t)0);
;     PG8_STAGE(PG8_SB(0, 0), cB, voffB); PG8_STAGE(PG8_SB(0, 1), cB + hstepB, voffB); PG8_STAGE(PG8_SA(0, 0), cA, voffA); PG8_STAGE(PG8_SA(0, 1), cA + hstepA, voffA);
;     if (wr == 1) PG8_BAR;
;     PG8_WAIT_V(2); PG8_BAR;
;     PG8_STAGE(PG8_SB(1, 0), cB + kstep, voffB); PG8_STAGE(PG8_SA(1, 0), cA + kstep, voffA); PG8_STAGE(PG8_SB(1, 1), cB + hstepB + kstep, voffB);
;     PG8_WAIT_V(6); PG8_BAR;
.LBB0_180:
	s_mul_i32 s6, s78, 0x3c00000
	v_readlane_b32 s7, v252, 36
	s_add_u32 s10, s7, s6
	v_readlane_b32 s6, v252, 37
	s_addc_u32 s11, s6, 0
	s_lshl_b32 s56, s78, 13
	v_readlane_b32 s16, v251, 39
	s_lshl_b64 s[6:7], s[56:57], 2
	v_readlane_b32 s18, v251, 41
	v_readlane_b32 s19, v251, 42
	s_add_u32 s44, s18, s6
	s_addc_u32 s45, s19, s7
	s_andn2_b64 vcc, exec, s[4:5]
	v_readlane_b32 s17, v251, 40
	s_cbranch_vccnz .LBB0_225
	v_ashrrev_i32_e32 v2, 31, v10
	v_lshrrev_b32_e32 v2, 26, v2
	v_add_u32_e32 v2, v10, v2
	v_ashrrev_i32_e32 v11, 6, v2
	v_bfe_i32 v2, v10, 27, 1
	v_lshlrev_b32_e32 v1, 4, v10
	v_lshrrev_b32_e32 v2, 22, v2
	v_add_u32_e32 v2, v1, v2
	v_and_b32_e32 v2, 0xfffffc00, v2
	v_sub_u32_e32 v2, v1, v2
	s_waitcnt lgkmcnt(0)
	v_lshrrev_b32_e32 v3, 4, v2
	v_bitop3_b32 v2, v3, v2, 32 bitop3:0x6c
	v_ashrrev_i32_e32 v4, 31, v2
	v_lshrrev_b32_e32 v4, 26, v4
	v_add_u32_e32 v4, v2, v4
	v_lshlrev_b32_e32 v3, 3, v11
	v_ashrrev_i32_e32 v12, 6, v4
	v_and_b32_e32 v4, 0xc0, v4
	v_and_b32_e32 v3, -16, v3
	v_sub_u32_e32 v2, v2, v4
	v_add_u32_e32 v3, v12, v3
	v_ashrrev_i16_sdwa v2, v190, sext(v2) dst_sel:DWORD dst_unused:UNUSED_PAD src0_sel:DWORD src1_sel:BYTE_0
	v_lshlrev_b32_e32 v5, 5, v11
	v_bfe_i32 v13, v2, 0, 16
	v_lshlrev_b32_e32 v2, 1, v3
	v_lshrrev_b32_e32 v4, 2, v3
	v_and_b32_e32 v6, 3, v12
	s_mov_b32 s4, 0xfffe0
	v_and_b32_e32 v5, 32, v5
	v_and_b32_e32 v2, 24, v2
	v_and_b32_e32 v4, 4, v4
	v_and_or_b32 v6, v3, s4, v6
	v_or3_b32 v2, v6, v4, v2
	v_add_lshl_u32 v4, v5, v13, 1
	v_add_u32_e32 v1, 0x2000, v1
	v_lshl_add_u32 v132, v2, 12, v4
	v_ashrrev_i32_e32 v2, 31, v1
	v_lshrrev_b32_e32 v2, 22, v2
	v_add_u32_e32 v2, v1, v2
	v_ashrrev_i32_e32 v14, 10, v2
	v_mul_i32_i24_e32 v2, 0x400, v14
	v_sub_u32_e32 v1, v1, v2
	v_lshrrev_b32_e32 v2, 4, v1
	v_bitop3_b32 v1, v2, v1, 32 bitop3:0x6c
	v_lshl_add_u32 v130, v3, 12, v4
	v_ashrrev_i32_e32 v3, 31, v1
	v_lshrrev_b32_e32 v3, 26, v3
	v_lshlrev_b32_e32 v2, 3, v14
	v_add_u32_e32 v3, v1, v3
	v_and_b32_e32 v2, -16, v2
	v_ashrrev_i32_e32 v15, 6, v3
	v_add_u32_e32 v2, v15, v2
	v_and_b32_e32 v3, 0xc0, v3
	v_and_b32_e32 v5, 3, v15
	s_ashr_i32 s7, s8, 6
	s_ashr_i32 s95, s94, 31
	s_ashr_i32 s53, s52, 31
	s_ashr_i32 s6, s8, 8
	v_sub_u32_e32 v1, v1, v3
	v_and_or_b32 v5, v2, s4, v5
	s_lshl_b32 s56, s7, 10
	s_lshl_b64 s[16:17], s[94:95], 20
	s_lshl_b64 s[4:5], s[52:53], 20
	v_ashrrev_i16_sdwa v1, v190, sext(v1) dst_sel:DWORD dst_unused:UNUSED_PAD src0_sel:DWORD src1_sel:BYTE_0
	s_add_u32 s4, s10, s4
	v_lshlrev_b32_e32 v4, 5, v14
	v_bfe_i32 v16, v1, 0, 16
	v_lshlrev_b32_e32 v1, 1, v2
	v_lshrrev_b32_e32 v3, 2, v2
	s_addc_u32 s5, s11, s5
	s_add_i32 s53, s56, 0
	v_and_b32_e32 v4, 32, v4
	v_and_b32_e32 v1, 24, v1
	v_and_b32_e32 v3, 4, v3
	s_add_i32 m0, s53, 0x10000
	v_or3_b32 v1, v5, v3, v1
	v_add_lshl_u32 v3, v4, v16, 1
	global_load_lds_dwordx4 v132, s[4:5] sc0
	s_add_i32 m0, s53, 0x12000
	v_lshl_add_u32 v136, v1, 12, v3
	s_add_u32 s18, s4, 0x80000
	global_load_lds_dwordx4 v136, s[4:5] sc0
	s_addc_u32 s19, s5, 0
	s_add_i32 m0, s53, 0x14000
	v_lshl_add_u32 v134, v2, 12, v3
	global_load_lds_dwordx4 v132, s[18:19] sc0
	s_add_i32 m0, s53, 0x16000
	s_add_u32 s62, s0, s16
	s_addc_u32 s63, s1, s17
	s_add_i32 s80, s53, 0x2000
	global_load_lds_dwordx4 v136, s[18:19] sc0
	s_mov_b32 m0, s53
	s_add_u32 s16, s62, 0x80000
	global_load_lds_dwordx4 v130, s[62:63] sc0
	s_mov_b32 m0, s80
	s_addc_u32 s17, s63, 0
	s_add_i32 s81, s53, 0x4000
	global_load_lds_dwordx4 v134, s[62:63] sc0
	s_mov_b32 m0, s81
	s_add_i32 s82, s53, 0x6000
	global_load_lds_dwordx4 v130, s[16:17] sc0
	s_mov_b32 m0, s82
	v_mov_b32_e32 v133, v0
	global_load_lds_dwordx4 v134, s[16:17] sc0
	v_mov_b32_e32 v137, v0
	v_mov_b32_e32 v131, v0
	v_mov_b32_e32 v135, v0
	s_cmp_eq_u32 s6, 1
	v_lshl_add_u64 v[8:9], s[4:5], 0, v[132:133]
	v_lshl_add_u64 v[6:7], s[4:5], 0, v[136:137]
	v_lshl_add_u64 v[2:3], s[62:63], 0, v[130:131]
	s_cselect_b64 s[40:41], -1, 0
	s_cmp_lg_u32 s6, 1
	v_lshl_add_u64 v[4:5], s[62:63], 0, v[134:135]
	s_cbranch_scc1 .LBB0_183
	s_barrier
.LBB0_183:
	s_lshl_b32 s83, s6, 6
	s_lshl_b32 s9, s6, 13
	s_lshl_b32 s6, s7, 5
	s_and_b32 s89, s6, 0x60
	s_add_i32 m0, s53, 0x18000
	v_lshl_add_u64 v[8:9], v[8:9], 0, s[60:61]
	s_lshl_b32 s16, s89, 7
	s_waitcnt vmcnt(2)
	s_barrier
	global_load_lds_dwordx4 v[8:9], off sc0
	v_lshl_add_u64 v[6:7], v[6:7], 0, s[60:61]
	s_add_i32 m0, s53, 0x1a000
	s_add_i32 s95, s53, 0x8000
	s_add_i32 s15, s53, 0xa000
	global_load_lds_dwordx4 v[6:7], off sc0
	v_lshl_add_u64 v[2:3], v[2:3], 0, s[60:61]
	s_mov_b32 m0, s95
	s_add_u32 s6, s4, 0x80080
	global_load_lds_dwordx4 v[2:3], off sc0
	v_lshl_add_u64 v[2:3], v[4:5], 0, s[60:61]
	s_mov_b32 m0, s15
	s_addc_u32 s7, s5, 0
	global_load_lds_dwordx4 v[2:3], off sc0
	s_add_i32 m0, s53, 0x1c000
	v_lshl_add_u64 v[2:3], s[6:7], 0, v[132:133]
	global_load_lds_dwordx4 v[2:3], off sc0
	v_lshl_add_u64 v[2:3], s[6:7], 0, v[136:137]
	s_add_i32 m0, s53, 0x1e000
	v_bfe_u32 v143, v10, 4, 2
	global_load_lds_dwordx4 v[2:3], off sc0
	v_and_b32_e32 v1, 15, v10
	v_lshlrev_b32_e32 v2, 4, v143
	v_lshlrev_b32_e32 v3, 2, v10
	v_lshl_or_b32 v2, v1, 6, v2
	v_and_b32_e32 v3, 32, v3
	v_bitop3_b32 v4, v2, s9, v3 bitop3:0xde
	v_bitop3_b32 v145, v2, s16, v3 bitop3:0xde
	v_lshlrev_b32_e32 v2, 15, v11
	v_and_b32_e32 v2, 0xffff0000, v2
	v_lshl_add_u32 v2, v12, 12, v2
	v_and_b32_e32 v3, 1, v11
	v_lshl_or_b32 v2, v3, 6, v2
	v_lshl_add_u32 v138, v13, 1, v2
	v_lshlrev_b32_e32 v2, 15, v14
	v_and_b32_e32 v2, 0xffff0000, v2
	s_waitcnt vmcnt(6)
	v_lshl_add_u32 v2, v15, 12, v2
	v_and_b32_e32 v3, 1, v14
	s_cmpk_lt_u32 s8, 0x100
	v_lshl_or_b32 v2, v3, 6, v2
	s_cselect_b64 s[46:47], -1, 0
	s_or_b32 s27, s89, 0xffffdc00
	s_or_b32 s28, s89, 0xfffff400
	s_or_b32 s29, s89, 0x400
	s_or_b32 s16, s89, 0xfffff800
	v_mov_b32_e32 v139, v0
	v_lshl_add_u32 v140, v16, 1, v2
	v_mov_b32_e32 v141, v0
	s_mov_b32 s17, 0
	v_add_u32_e32 v147, 0, v4
	s_barrier
	s_branch .LBB0_186

; #define PG8_STAGE(bufoff, gbase, voff) do { _Pragma("unroll") for (int _i = 0; _i < 2; ++_i) \
;         __builtin_amdgcn_global_load_lds((const unsigned*)((const char*)(gbase) + (voff)[_i]), (LAS unsigned*)(lds + (bufoff) + ldsw + _i * 8192), 16, 0, 0); } while (0)
; #define PG8_LDA(dst, b, h) do { _Pragma("unroll") for (int m = 0; m < 4; ++m) _Pragma("unroll") for (int k = 0; k < 2; ++k) dst[m][k] = *(const LAS bf16x8*)(lds + PG8_SA(b, h) + aoff + m * 2048 + k * 1024); } while (0)
; #define PG8_LDB(dst, b, h) do { _Pragma("unroll") for (int n = 0; n < 2; ++n) _Pragma("unroll") for (int k = 0; k < 2; ++k) dst[n][k] = *(const LAS bf16x8*)(lds + PG8_SB(b, h) + boff + n * 2048 + k * 1024); } while (0)
; #define PG8_WAIT_V(n) asm volatile("s_waitcnt vmcnt(" #n ")" ::: "memory")
; template <class Epi, class Order = StaticOrder, bool HALFN = false>
; __device__ __forceinline__ void gemm_phase(LAS unsigned char* lds, const Gemm g, const Epi& E) {
;     ...
;         const bool has_next = S.next(ui + 1, nxt);
;         const char* nA = has_next ? (const char*)g.A + (size_t)nxt.pm * tstepA + (size_t)nxt.pn * g.a_pn_off * 2 : cA; const char* nB = has_next ? (const char*)g.Bt + (size_t)nxt.pn * tstepB + (HALFN ? (size_t)(nxt.half - 1) * hstepB : (size_t)0) : cB;
; #pragma unroll 1
;         for (int t = 0; t < nt; t += 2) {
;             const bool last = (t == nt - 2);
;             if constexpr (Epi::SEAMS) { if (t == Epi::SEAM0 || t == Epi::SEAM1) E.seam(acc, cur, t == Epi::SEAM0 ? 0 : 1, wr, wc, fr, fq); }
;             const char* a1 = cA + (size_t)(t + 1) * kstep;
;             const char* a2 = last ? nA : cA + (size_t)(t + 2) * kstep; const char* b2 = last ? nB : cB + (size_t)(t + 2) * kstep;
;             const char* a3 = a2 + kstep; const char* b3 = b2 + kstep;
;             PG8_LDB(B0, 0, 0); if constexpr (!HALFN) PG8_LDB(B1, 0, 1); PG8_SCHED; PG8_LDA(At, 0, 0); PG8_STAGE(PG8_SA(1, 1), a1 + hstepA, voffA);
;             PG8_WAIT_V(8); PG8_WAIT_L(0); PG8_BAR; PG8_MMA(0, 0, At, B0); if constexpr (!HALFN) PG8_MMA(0, 1, At, B1); PG8_BAR; PG8_SCHED;
;             PG8_LDA(At, 0, 1); PG8_STAGE(PG8_SB(0, 0), b2, voffB); PG8_STAGE(PG8_SB(0, 1), b2 + hstepB, voffB); PG8_STAGE(PG8_SA(0, 0), a2, voffA);
;             PG8_WAIT_V(8); PG8_WAIT_L(0); PG8_BAR; PG8_MMA(1, 0, At, B0); if constexpr (!HALFN) PG8_MMA(1, 1, At, B1); PG8_BAR; PG8_SCHED;
.LBB0_193:
	s_mov_b32 s48, s18
	s_ashr_i32 s49, s18, 31
	s_lshl_b64 s[6:7], s[48:49], 20
	s_add_u32 s74, s0, s6
	s_addc_u32 s75, s1, s7
	s_mov_b32 s50, s9
	s_and_b64 s[6:7], s[54:55], exec
	s_cselect_b32 s8, s75, s63
	s_cselect_b32 s9, s74, s62
	s_ashr_i32 s51, s50, 31
	s_lshl_b64 s[6:7], s[50:51], 20
	s_add_u32 s92, s10, s6
	s_addc_u32 s93, s11, s7
	s_and_b64 s[6:7], s[54:55], exec
	s_cselect_b32 s18, s93, s5
	s_cselect_b32 s19, s92, s4
	s_add_u32 s62, s62, 0x80080
	s_addc_u32 s63, s63, 0
	s_add_u32 s20, s4, 0x100
	s_addc_u32 s21, s5, 0
	s_mov_b32 s22, -2
	s_add_u32 s4, s62, 0xfff80080
	s_addc_u32 s5, s63, -1
	s_add_i32 s23, 0, 0x10000
	s_cmp_eq_u32 s22, 28
	s_cselect_b32 s7, s8, s5
	s_cselect_b32 s6, s9, s4
	v_add_u32_e32 v142, s23, v145
	s_cselect_b32 s5, s18, s21
	s_cselect_b32 s4, s19, s20
	s_add_i32 s26, 0, 0x14000
	ds_read_b128 v[148:151], v142
	ds_read_b128 v[152:155], v142 offset:1024
	ds_read_b128 v[156:159], v142 offset:2048
	ds_read_b128 v[168:171], v142 offset:3072
	v_add_u32_e32 v142, s26, v145
	ds_read_b128 v[172:175], v142
	ds_read_b128 v[176:179], v142 offset:1024
	ds_read_b128 v[180:183], v142 offset:2048
	ds_read_b128 v[184:187], v142 offset:3072
	v_lshl_add_u64 v[160:161], s[62:63], 0, v[138:139]
	s_add_i32 m0, s53, 0xc000
	ds_read_b128 v[208:211], v147
	ds_read_b128 v[212:215], v147 offset:1024
	ds_read_b128 v[216:219], v147 offset:2048
	ds_read_b128 v[220:223], v147 offset:3072
	ds_read_b128 v[224:227], v147 offset:4096
	ds_read_b128 v[228:231], v147 offset:5120
	ds_read_b128 v[232:235], v147 offset:6144
	ds_read_b128 v[236:239], v147 offset:7168
	global_load_lds_dwordx4 v[160:161], off sc0
	v_lshl_add_u64 v[160:161], s[62:63], 0, v[140:141]
	s_add_i32 m0, s53, 0xe000
	s_nop 0
	global_load_lds_dwordx4 v[160:161], off sc0
	s_waitcnt vmcnt(8)
	s_waitcnt lgkmcnt(0)
	s_barrier
	s_setprio 1
	s_waitcnt lgkmcnt(0)
	v_mfma_f32_16x16x32_bf16 v[126:129], v[148:151], v[208:211], 0
	v_mfma_f32_16x16x32_bf16 v[122:125], v[156:159], v[208:211], 0
	v_mfma_f32_16x16x32_bf16 v[114:117], v[148:151], v[216:219], 0
	v_mfma_f32_16x16x32_bf16 v[106:109], v[156:159], v[216:219], 0
	v_mfma_f32_16x16x32_bf16 v[102:105], v[148:151], v[224:227], 0
	v_mfma_f32_16x16x32_bf16 v[94:97], v[156:159], v[224:227], 0
	v_mfma_f32_16x16x32_bf16 v[86:89], v[148:151], v[232:235], 0
	v_mfma_f32_16x16x32_bf16 v[78:81], v[156:159], v[232:235], 0
	v_mfma_f32_16x16x32_bf16 v[126:129], v[152:155], v[212:215], v[126:129]
	v_mfma_f32_16x16x32_bf16 v[122:125], v[168:171], v[212:215], v[122:125]
	v_mfma_f32_16x16x32_bf16 v[114:117], v[152:155], v[220:223], v[114:117]
	v_mfma_f32_16x16x32_bf16 v[106:109], v[168:171], v[220:223], v[106:109]
	v_mfma_f32_16x16x32_bf16 v[102:105], v[152:155], v[228:231], v[102:105]
	v_mfma_f32_16x16x32_bf16 v[94:97], v[168:171], v[228:231], v[94:97]
	v_mfma_f32_16x16x32_bf16 v[86:89], v[152:155], v[236:239], v[86:89]
	v_mfma_f32_16x16x32_bf16 v[78:81], v[168:171], v[236:239], v[78:81]
	s_setprio 0
	s_setprio 1
	v_mfma_f32_16x16x32_bf16 v[118:121], v[172:175], v[208:211], 0
	v_mfma_f32_16x16x32_bf16 v[110:113], v[180:183], v[208:211], 0
	v_mfma_f32_16x16x32_bf16 v[98:101], v[172:175], v[216:219], 0
	v_mfma_f32_16x16x32_bf16 v[90:93], v[180:183], v[216:219], 0
	v_mfma_f32_16x16x32_bf16 v[82:85], v[172:175], v[224:227], 0
	v_mfma_f32_16x16x32_bf16 v[74:77], v[180:183], v[224:227], 0
	v_mfma_f32_16x16x32_bf16 v[70:73], v[172:175], v[232:235], 0
	v_mfma_f32_16x16x32_bf16 v[66:69], v[180:183], v[232:235], 0
	v_mfma_f32_16x16x32_bf16 v[118:121], v[176:179], v[212:215], v[118:121]
	v_mfma_f32_16x16x32_bf16 v[110:113], v[184:187], v[212:215], v[110:113]
	v_mfma_f32_16x16x32_bf16 v[98:101], v[176:179], v[220:223], v[98:101]
	v_mfma_f32_16x16x32_bf16 v[90:93], v[184:187], v[220:223], v[90:93]
	v_mfma_f32_16x16x32_bf16 v[82:85], v[176:179], v[228:231], v[82:85]
	v_mfma_f32_16x16x32_bf16 v[74:77], v[184:187], v[228:231], v[74:77]
	v_mfma_f32_16x16x32_bf16 v[70:73], v[176:179], v[236:239], v[70:73]
	v_mfma_f32_16x16x32_bf16 v[66:69], v[184:187], v[236:239], v[66:69]
	s_setprio 0
	s_barrier
	s_add_i32 s23, s23, s56
	v_lshl_add_u64 v[160:161], s[4:5], 0, v[132:133]
	s_mov_b32 m0, s23
	ds_read_b128 v[208:211], v147 offset:16384
	ds_read_b128 v[212:215], v147 offset:17408
	ds_read_b128 v[216:219], v147 offset:18432
	ds_read_b128 v[220:223], v147 offset:19456
	ds_read_b128 v[224:227], v147 offset:20480
	ds_read_b128 v[228:231], v147 offset:21504
	ds_read_b128 v[232:235], v147 offset:22528
	ds_read_b128 v[236:239], v147 offset:23552
	global_load_lds_dwordx4 v[160:161], off sc0
	s_add_i32 m0, s23, 0x2000
	s_add_u32 s24, s4, 0x80000
	v_lshl_add_u64 v[240:241], s[4:5], 0, v[136:137]
	s_addc_u32 s25, s5, 0
	s_add_i32 s23, s26, s56
	global_load_lds_dwordx4 v[240:241], off sc0
	v_lshl_add_u64 v[242:243], s[24:25], 0, v[132:133]
	s_mov_b32 m0, s23
	v_lshl_add_u64 v[244:245], s[6:7], 0, v[134:135]
	global_load_lds_dwordx4 v[242:243], off sc0
	v_lshl_add_u64 v[242:243], s[24:25], 0, v[136:137]
	s_add_i32 m0, s23, 0x2000
	s_nop 0
	global_load_lds_dwordx4 v[242:243], off sc0
	v_lshl_add_u64 v[242:243], s[6:7], 0, v[130:131]
	s_mov_b32 m0, s53
	s_nop 0
	global_load_lds_dwordx4 v[242:243], off sc0
	s_mov_b32 m0, s80
	s_nop 0
	global_load_lds_dwordx4 v[244:245], off sc0
	s_waitcnt vmcnt(8)
	s_waitcnt lgkmcnt(0)
	s_barrier
; #define PG8_STAGE(bufoff, gbase, voff) do { _Pragma("unroll") for (int _i = 0; _i < 2; ++_i) \
;         __builtin_amdgcn_global_load_lds((const unsigned*)((const char*)(gbase) + (voff)[_i]), (LAS unsigned*)(lds + (bufoff) + ldsw + _i * 8192), 16, 0, 0); } while (0)
; #define PG8_LDA(dst, b, h) do { _Pragma("unroll") for (int m = 0; m < 4; ++m) _Pragma("unroll") for (int k = 0; k < 2; ++k) dst[m][k] = *(const LAS bf16x8*)(lds + PG8_SA(b, h) + aoff + m * 2048 + k * 1024); } while (0)
; #define PG8_LDB(dst, b, h) do { _Pragma("unroll") for (int n = 0; n < 2; ++n) _Pragma("unroll") for (int k = 0; k < 2; ++k) dst[n][k] = *(const LAS bf16x8*)(lds + PG8_SB(b, h) + boff + n * 2048 + k * 1024); } while (0)
; #define PG8_MMA(ai, bj, At, Bt) do { __builtin_amdgcn_s_setprio(1); _Pragma("unroll") for (int m = 0; m < 4; ++m) _Pragma("unroll") for (int n = 0; n < 2; ++n) _Pragma("unroll") for (int k = 0; k < 2; ++k) \
;         acc[ai][bj][m][n] = __builtin_amdgcn_mfma_f32_16x16x32_bf16(Bt[n][k], At[m][k], acc[ai][bj][m][n], 0, 0, 0); __builtin_amdgcn_s_setprio(0); } while (0)
; #define PG8_WAIT_V(n) asm volatile("s_waitcnt vmcnt(" #n ")" ::: "memory")
; #define PG8_WAIT_L(n) asm volatile("s_waitcnt lgkmcnt(" #n ")" ::: "memory")
; #define PG8_BAR __builtin_amdgcn_s_barrier()
; #define PG8_SCHED __builtin_amdgcn_sched_barrier(0)
; template <class Epi, class Order = StaticOrder, bool HALFN = false>
; __device__ __forceinline__ void gemm_phase(LAS unsigned char* lds, const Gemm g, const Epi& E) {
;     ...
;             PG8_WAIT_V(8); PG8_WAIT_L(0); PG8_BAR; PG8_MMA(0, 0, At, B0); if constexpr (!HALFN) PG8_MMA(0, 1, At, B1); PG8_BAR; PG8_SCHED;
;             PG8_LDA(At, 0, 1); PG8_STAGE(PG8_SB(0, 0), b2, voffB); PG8_STAGE(PG8_SB(0, 1), b2 + hstepB, voffB); PG8_STAGE(PG8_SA(0, 0), a2, voffA);
;             PG8_WAIT_V(8); PG8_WAIT_L(0); PG8_BAR; PG8_MMA(1, 0, At, B0); if constexpr (!HALFN) PG8_MMA(1, 1, At, B1); PG8_BAR; PG8_SCHED;
;             PG8_LDB(B0, 1, 0); if constexpr (!HALFN) PG8_LDB(B1, 1, 1); PG8_SCHED; PG8_LDA(At, 1, 0); PG8_STAGE(PG8_SA(0, 1), a2 + hstepA, voffA);
;             PG8_WAIT_V(8); PG8_WAIT_L(0); PG8_BAR; PG8_MMA(0, 0, At, B0); if constexpr (!HALFN) PG8_MMA(0, 1, At, B1); PG8_BAR; PG8_SCHED;
	s_setprio 1
	s_waitcnt lgkmcnt(0)
	v_mfma_f32_16x16x32_bf16 v[62:65], v[148:151], v[208:211], 0
	v_mfma_f32_16x16x32_bf16 v[58:61], v[156:159], v[208:211], 0
	v_mfma_f32_16x16x32_bf16 v[54:57], v[148:151], v[216:219], 0
	v_mfma_f32_16x16x32_bf16 v[46:49], v[156:159], v[216:219], 0
	v_mfma_f32_16x16x32_bf16 v[38:41], v[148:151], v[224:227], 0
	v_mfma_f32_16x16x32_bf16 v[30:33], v[156:159], v[224:227], 0
	v_mfma_f32_16x16x32_bf16 v[22:25], v[148:151], v[232:235], 0
	v_mfma_f32_16x16x32_bf16 v[14:17], v[156:159], v[232:235], 0
	v_mfma_f32_16x16x32_bf16 v[62:65], v[152:155], v[212:215], v[62:65]
	v_mfma_f32_16x16x32_bf16 v[58:61], v[168:171], v[212:215], v[58:61]
	v_mfma_f32_16x16x32_bf16 v[54:57], v[152:155], v[220:223], v[54:57]
	v_mfma_f32_16x16x32_bf16 v[46:49], v[168:171], v[220:223], v[46:49]
	v_mfma_f32_16x16x32_bf16 v[38:41], v[152:155], v[228:231], v[38:41]
	v_mfma_f32_16x16x32_bf16 v[30:33], v[168:171], v[228:231], v[30:33]
	v_mfma_f32_16x16x32_bf16 v[22:25], v[152:155], v[236:239], v[22:25]
	v_mfma_f32_16x16x32_bf16 v[14:17], v[168:171], v[236:239], v[14:17]
	s_setprio 0
	s_setprio 1
	v_mfma_f32_16x16x32_bf16 v[50:53], v[172:175], v[208:211], 0
	v_mfma_f32_16x16x32_bf16 v[42:45], v[180:183], v[208:211], 0
	v_mfma_f32_16x16x32_bf16 v[34:37], v[172:175], v[216:219], 0
	v_mfma_f32_16x16x32_bf16 v[26:29], v[180:183], v[216:219], 0
	v_mfma_f32_16x16x32_bf16 v[18:21], v[172:175], v[224:227], 0
	v_mfma_f32_16x16x32_bf16 v[10:13], v[180:183], v[224:227], 0
	v_mfma_f32_16x16x32_bf16 v[6:9], v[172:175], v[232:235], 0
	v_mfma_f32_16x16x32_bf16 v[2:5], v[180:183], v[232:235], 0
	v_mfma_f32_16x16x32_bf16 v[50:53], v[176:179], v[212:215], v[50:53]
	v_mfma_f32_16x16x32_bf16 v[42:45], v[184:187], v[212:215], v[42:45]
	v_mfma_f32_16x16x32_bf16 v[34:37], v[176:179], v[220:223], v[34:37]
	v_mfma_f32_16x16x32_bf16 v[26:29], v[184:187], v[220:223], v[26:29]
	v_mfma_f32_16x16x32_bf16 v[18:21], v[176:179], v[228:231], v[18:21]
	v_mfma_f32_16x16x32_bf16 v[10:13], v[184:187], v[228:231], v[10:13]
	v_mfma_f32_16x16x32_bf16 v[6:9], v[176:179], v[236:239], v[6:9]
	v_mfma_f32_16x16x32_bf16 v[2:5], v[184:187], v[236:239], v[2:5]
	s_setprio 0
	s_barrier
	s_add_i32 s23, 0, 0x18000
	v_add_u32_e32 v142, s23, v145
	s_add_i32 s24, 0, 0x1c000
	ds_read_b128 v[148:151], v142
	ds_read_b128 v[152:155], v142 offset:1024
	ds_read_b128 v[156:159], v142 offset:2048
	ds_read_b128 v[168:171], v142 offset:3072
	v_add_u32_e32 v142, s24, v145
	ds_read_b128 v[172:175], v142
	ds_read_b128 v[176:179], v142 offset:1024
	ds_read_b128 v[180:183], v142 offset:2048
	ds_read_b128 v[184:187], v142 offset:3072
	s_add_u32 s6, s6, 0x80000
	s_addc_u32 s7, s7, 0
	s_mov_b32 m0, s81
	v_lshl_add_u64 v[246:247], s[6:7], 0, v[130:131]
	ds_read_b128 v[208:211], v147 offset:32768
	ds_read_b128 v[212:215], v147 offset:33792
	ds_read_b128 v[216:219], v147 offset:34816
	ds_read_b128 v[220:223], v147 offset:35840
	ds_read_b128 v[224:227], v147 offset:36864
	ds_read_b128 v[228:231], v147 offset:37888
	ds_read_b128 v[232:235], v147 offset:38912
	ds_read_b128 v[236:239], v147 offset:39936
	global_load_lds_dwordx4 v[246:247], off sc0
	v_lshl_add_u64 v[246:247], s[6:7], 0, v[134:135]
	s_mov_b32 m0, s82
	s_nop 0
	global_load_lds_dwordx4 v[246:247], off sc0
	s_waitcnt vmcnt(8)
	s_waitcnt lgkmcnt(0)
	s_barrier
	s_setprio 1
	s_waitcnt lgkmcnt(0)
	v_mfma_f32_16x16x32_bf16 v[126:129], v[148:151], v[208:211], v[126:129]
	v_mfma_f32_16x16x32_bf16 v[122:125], v[156:159], v[208:211], v[122:125]
	v_mfma_f32_16x16x32_bf16 v[114:117], v[148:151], v[216:219], v[114:117]
	v_mfma_f32_16x16x32_bf16 v[106:109], v[156:159], v[216:219], v[106:109]
	v_mfma_f32_16x16x32_bf16 v[102:105], v[148:151], v[224:227], v[102:105]
	v_mfma_f32_16x16x32_bf16 v[94:97], v[156:159], v[224:227], v[94:97]
	v_mfma_f32_16x16x32_bf16 v[86:89], v[148:151], v[232:235], v[86:89]
	v_mfma_f32_16x16x32_bf16 v[78:81], v[156:159], v[232:235], v[78:81]
	v_mfma_f32_16x16x32_bf16 v[126:129], v[152:155], v[212:215], v[126:129]
	v_mfma_f32_16x16x32_bf16 v[122:125], v[168:171], v[212:215], v[122:125]
	v_mfma_f32_16x16x32_bf16 v[114:117], v[152:155], v[220:223], v[114:117]
	v_mfma_f32_16x16x32_bf16 v[106:109], v[168:171], v[220:223], v[106:109]
	v_mfma_f32_16x16x32_bf16 v[102:105], v[152:155], v[228:231], v[102:105]
	v_mfma_f32_16x16x32_bf16 v[94:97], v[168:171], v[228:231], v[94:97]
	v_mfma_f32_16x16x32_bf16 v[86:89], v[152:155], v[236:239], v[86:89]
	v_mfma_f32_16x16x32_bf16 v[78:81], v[168:171], v[236:239], v[78:81]
	s_setprio 0
	s_setprio 1
	v_mfma_f32_16x16x32_bf16 v[118:121], v[172:175], v[208:211], v[118:121]
	v_mfma_f32_16x16x32_bf16 v[110:113], v[180:183], v[208:211], v[110:113]
	v_mfma_f32_16x16x32_bf16 v[98:101], v[172:175], v[216:219], v[98:101]
	v_mfma_f32_16x16x32_bf16 v[90:93], v[180:183], v[216:219], v[90:93]
	v_mfma_f32_16x16x32_bf16 v[82:85], v[172:175], v[224:227], v[82:85]
	v_mfma_f32_16x16x32_bf16 v[74:77], v[180:183], v[224:227], v[74:77]
	v_mfma_f32_16x16x32_bf16 v[70:73], v[172:175], v[232:235], v[70:73]
	v_mfma_f32_16x16x32_bf16 v[66:69], v[180:183], v[232:235], v[66:69]
	v_mfma_f32_16x16x32_bf16 v[118:121], v[176:179], v[212:215], v[118:121]
	v_mfma_f32_16x16x32_bf16 v[110:113], v[184:187], v[212:215], v[110:113]
	v_mfma_f32_16x16x32_bf16 v[98:101], v[176:179], v[220:223], v[98:101]
	v_mfma_f32_16x16x32_bf16 v[90:93], v[184:187], v[220:223], v[90:93]
	v_mfma_f32_16x16x32_bf16 v[82:85], v[176:179], v[228:231], v[82:85]
	v_mfma_f32_16x16x32_bf16 v[74:77], v[184:187], v[228:231], v[74:77]
	v_mfma_f32_16x16x32_bf16 v[70:73], v[176:179], v[236:239], v[70:73]
	v_mfma_f32_16x16x32_bf16 v[66:69], v[184:187], v[236:239], v[66:69]
	s_setprio 0
	s_barrier
; #define PG8_STAGE(bufoff, gbase, voff) do { _Pragma("unroll") for (int _i = 0; _i < 2; ++_i) \
;         __builtin_amdgcn_global_load_lds((const unsigned*)((const char*)(gbase) + (voff)[_i]), (LAS unsigned*)(lds + (bufoff) + ldsw + _i * 8192), 16, 0, 0); } while (0)
; #define PG8_LDA(dst, b, h) do { _Pragma("unroll") for (int m = 0; m < 4; ++m) _Pragma("unroll") for (int k = 0; k < 2; ++k) dst[m][k] = *(const LAS bf16x8*)(lds + PG8_SA(b, h) + aoff + m * 2048 + k * 1024); } while (0)
; #define PG8_LDB(dst, b, h) do { _Pragma("unroll") for (int n = 0; n < 2; ++n) _Pragma("unroll") for (int k = 0; k < 2; ++k) dst[n][k] = *(const LAS bf16x8*)(lds + PG8_SB(b, h) + boff + n * 2048 + k * 1024); } while (0)
; #define PG8_WAIT_V(n) asm volatile("s_waitcnt vmcnt(" #n ")" ::: "memory")
; #define PG8_BAR __builtin_amdgcn_s_barrier()
; template <class Epi, class Order = StaticOrder, bool HALFN = false>
; __device__ __forceinline__ void gemm_phase(LAS unsigned char* lds, const Gemm g, const Epi& E) {
;     ...
;         for (int t = 0; t < nt; t += 2) {
;             const bool last = (t == nt - 2);
;             if constexpr (Epi::SEAMS) { if (t == Epi::SEAM0 || t == Epi::SEAM1) E.seam(acc, cur, t == Epi::SEAM0 ? 0 : 1, wr, wc, fr, fq); }
;             const char* a1 = cA + (size_t)(t + 1) * kstep;
;             const char* a2 = last ? nA : cA + (size_t)(t + 2) * kstep; const char* b2 = last ? nB : cB + (size_t)(t + 2) * kstep;
;             const char* a3 = a2 + kstep; const char* b3 = b2 + kstep;
;             PG8_LDB(B0, 0, 0); if constexpr (!HALFN) PG8_LDB(B1, 0, 1); PG8_SCHED; PG8_LDA(At, 0, 0); PG8_STAGE(PG8_SA(1, 1), a1 + hstepA, voffA);
;             PG8_WAIT_V(8); PG8_WAIT_L(0); PG8_BAR; PG8_MMA(0, 0, At, B0); if constexpr (!HALFN) PG8_MMA(0, 1, At, B1); PG8_BAR; PG8_SCHED;
;     ...
;             PG8_LDB(B0, 1, 0); if constexpr (!HALFN) PG8_LDB(B1, 1, 1); PG8_SCHED; PG8_LDA(At, 1, 0); PG8_STAGE(PG8_SA(0, 1), a2 + hstepA, voffA);
;             PG8_WAIT_V(8); PG8_WAIT_L(0); PG8_BAR; PG8_MMA(0, 0, At, B0); if constexpr (!HALFN) PG8_MMA(0, 1, At, B1); PG8_BAR; PG8_SCHED;
;             PG8_LDA(At, 1, 1); PG8_STAGE(PG8_SB(1, 0), b3, voffB); PG8_STAGE(PG8_SB(1, 1), b3 + hstepB, voffB); PG8_STAGE(PG8_SA(1, 0), a3, voffA);
;             PG8_WAIT_V(8); PG8_WAIT_L(0); PG8_BAR; PG8_MMA(1, 0, At, B0); if constexpr (!HALFN) PG8_MMA(1, 1, At, B1); PG8_BAR; PG8_SCHED;
	s_add_i32 s6, s23, s56
	v_lshl_add_u64 v[160:161], v[160:161], 0, s[60:61]
	s_mov_b32 m0, s6
	ds_read_b128 v[208:211], v147 offset:49152
	ds_read_b128 v[212:215], v147 offset:50176
	ds_read_b128 v[216:219], v147 offset:51200
	ds_read_b128 v[220:223], v147 offset:52224
	ds_read_b128 v[224:227], v147 offset:53248
	ds_read_b128 v[228:231], v147 offset:54272
	ds_read_b128 v[232:235], v147 offset:55296
	ds_read_b128 v[236:239], v147 offset:56320
	global_load_lds_dwordx4 v[160:161], off sc0
	s_add_i32 m0, s6, 0x2000
	s_add_u32 s4, s4, 0x80080
	v_lshl_add_u64 v[160:161], v[240:241], 0, s[60:61]
	s_addc_u32 s5, s5, 0
	s_add_i32 s6, s24, s56
	global_load_lds_dwordx4 v[160:161], off sc0
	v_lshl_add_u64 v[160:161], s[4:5], 0, v[132:133]
	s_mov_b32 m0, s6
	s_nop 0
	global_load_lds_dwordx4 v[160:161], off sc0
	v_lshl_add_u64 v[160:161], s[4:5], 0, v[136:137]
	s_add_i32 m0, s6, 0x2000
	s_nop 0
	global_load_lds_dwordx4 v[160:161], off sc0
	v_lshl_add_u64 v[160:161], v[242:243], 0, s[60:61]
	s_mov_b32 m0, s95
	s_nop 0
	global_load_lds_dwordx4 v[160:161], off sc0
	v_lshl_add_u64 v[160:161], v[244:245], 0, s[60:61]
	s_mov_b32 m0, s15
	s_nop 0
	global_load_lds_dwordx4 v[160:161], off sc0
	s_waitcnt vmcnt(8)
	s_waitcnt lgkmcnt(0)
	s_barrier
	s_setprio 1
	s_waitcnt lgkmcnt(0)
	v_mfma_f32_16x16x32_bf16 v[62:65], v[148:151], v[208:211], v[62:65]
	v_mfma_f32_16x16x32_bf16 v[58:61], v[156:159], v[208:211], v[58:61]
	v_mfma_f32_16x16x32_bf16 v[54:57], v[148:151], v[216:219], v[54:57]
	v_mfma_f32_16x16x32_bf16 v[46:49], v[156:159], v[216:219], v[46:49]
	v_mfma_f32_16x16x32_bf16 v[38:41], v[148:151], v[224:227], v[38:41]
	v_mfma_f32_16x16x32_bf16 v[30:33], v[156:159], v[224:227], v[30:33]
	v_mfma_f32_16x16x32_bf16 v[22:25], v[148:151], v[232:235], v[22:25]
	v_mfma_f32_16x16x32_bf16 v[14:17], v[156:159], v[232:235], v[14:17]
	v_mfma_f32_16x16x32_bf16 v[62:65], v[152:155], v[212:215], v[62:65]
	v_mfma_f32_16x16x32_bf16 v[58:61], v[168:171], v[212:215], v[58:61]
	v_mfma_f32_16x16x32_bf16 v[54:57], v[152:155], v[220:223], v[54:57]
	v_mfma_f32_16x16x32_bf16 v[46:49], v[168:171], v[220:223], v[46:49]
	v_mfma_f32_16x16x32_bf16 v[38:41], v[152:155], v[228:231], v[38:41]
	v_mfma_f32_16x16x32_bf16 v[30:33], v[168:171], v[228:231], v[30:33]
	v_mfma_f32_16x16x32_bf16 v[22:25], v[152:155], v[236:239], v[22:25]
	v_mfma_f32_16x16x32_bf16 v[14:17], v[168:171], v[236:239], v[14:17]
	s_setprio 0
	s_setprio 1
	v_mfma_f32_16x16x32_bf16 v[50:53], v[172:175], v[208:211], v[50:53]
	v_mfma_f32_16x16x32_bf16 v[42:45], v[180:183], v[208:211], v[42:45]
	v_mfma_f32_16x16x32_bf16 v[34:37], v[172:175], v[216:219], v[34:37]
	v_mfma_f32_16x16x32_bf16 v[26:29], v[180:183], v[216:219], v[26:29]
	v_mfma_f32_16x16x32_bf16 v[18:21], v[172:175], v[224:227], v[18:21]
	v_mfma_f32_16x16x32_bf16 v[10:13], v[180:183], v[224:227], v[10:13]
	v_mfma_f32_16x16x32_bf16 v[6:9], v[172:175], v[232:235], v[6:9]
	v_mfma_f32_16x16x32_bf16 v[2:5], v[180:183], v[232:235], v[2:5]
	v_mfma_f32_16x16x32_bf16 v[50:53], v[176:179], v[212:215], v[50:53]
	v_mfma_f32_16x16x32_bf16 v[42:45], v[184:187], v[212:215], v[42:45]
	v_mfma_f32_16x16x32_bf16 v[34:37], v[176:179], v[220:223], v[34:37]
	v_mfma_f32_16x16x32_bf16 v[26:29], v[184:187], v[220:223], v[26:29]
	v_mfma_f32_16x16x32_bf16 v[18:21], v[176:179], v[228:231], v[18:21]
	v_mfma_f32_16x16x32_bf16 v[10:13], v[184:187], v[228:231], v[10:13]
	v_mfma_f32_16x16x32_bf16 v[6:9], v[176:179], v[236:239], v[6:9]
	v_mfma_f32_16x16x32_bf16 v[2:5], v[184:187], v[236:239], v[2:5]
	s_setprio 0
	s_barrier
	s_add_i32 s22, s22, 2
	s_add_u32 s62, s62, 0x100
	s_addc_u32 s63, s63, 0
	s_add_u32 s20, s20, 0x100
	s_addc_u32 s21, s21, 0
	s_cmp_gt_u32 s22, 29
.LBB0_194:
	s_add_u32 s4, s62, 0xfff80080
	s_addc_u32 s5, s63, -1
	s_add_i32 s23, 0, 0x10000
	s_cmp_eq_u32 s22, 28
	s_cselect_b32 s7, s8, s5
	s_cselect_b32 s6, s9, s4
	v_add_u32_e32 v142, s23, v145
	s_cselect_b32 s5, s18, s21
	s_cselect_b32 s4, s19, s20
	s_add_i32 s26, 0, 0x14000
	ds_read_b128 v[148:151], v142
	ds_read_b128 v[152:155], v142 offset:1024
	ds_read_b128 v[156:159], v142 offset:2048
	ds_read_b128 v[168:171], v142 offset:3072
	v_add_u32_e32 v142, s26, v145
	ds_read_b128 v[172:175], v142
	ds_read_b128 v[176:179], v142 offset:1024
	ds_read_b128 v[180:183], v142 offset:2048
	ds_read_b128 v[184:187], v142 offset:3072
	v_lshl_add_u64 v[160:161], s[62:63], 0, v[138:139]
	s_add_i32 m0, s53, 0xc000
	ds_read_b128 v[208:211], v147
	ds_read_b128 v[212:215], v147 offset:1024
	ds_read_b128 v[216:219], v147 offset:2048
	ds_read_b128 v[220:223], v147 offset:3072
	ds_read_b128 v[224:227], v147 offset:4096
	ds_read_b128 v[228:231], v147 offset:5120
	ds_read_b128 v[232:235], v147 offset:6144
	ds_read_b128 v[236:239], v147 offset:7168
	global_load_lds_dwordx4 v[160:161], off sc0
	v_lshl_add_u64 v[160:161], s[62:63], 0, v[140:141]
	s_add_i32 m0, s53, 0xe000
	s_nop 0
	global_load_lds_dwordx4 v[160:161], off sc0
	s_waitcnt vmcnt(8)
	s_waitcnt lgkmcnt(0)
	s_barrier
; #define PG8_STAGE(bufoff, gbase, voff) do { _Pragma("unroll") for (int _i = 0; _i < 2; ++_i) \
;         __builtin_amdgcn_global_load_lds((const unsigned*)((const char*)(gbase) + (voff)[_i]), (LAS unsigned*)(lds + (bufoff) + ldsw + _i * 8192), 16, 0, 0); } while (0)
; #define PG8_LDA(dst, b, h) do { _Pragma("unroll") for (int m = 0; m < 4; ++m) _Pragma("unroll") for (int k = 0; k < 2; ++k) dst[m][k] = *(const LAS bf16x8*)(lds + PG8_SA(b, h) + aoff + m * 2048 + k * 1024); } while (0)
; #define PG8_MMA(ai, bj, At, Bt) do { __builtin_amdgcn_s_setprio(1); _Pragma("unroll") for (int m = 0; m < 4; ++m) _Pragma("unroll") for (int n = 0; n < 2; ++n) _Pragma("unroll") for (int k = 0; k < 2; ++k) \
;         acc[ai][bj][m][n] = __builtin_amdgcn_mfma_f32_16x16x32_bf16(Bt[n][k], At[m][k], acc[ai][bj][m][n], 0, 0, 0); __builtin_amdgcn_s_setprio(0); } while (0)
; #define PG8_WAIT_V(n) asm volatile("s_waitcnt vmcnt(" #n ")" ::: "memory")
; #define PG8_WAIT_L(n) asm volatile("s_waitcnt lgkmcnt(" #n ")" ::: "memory")
; #define PG8_BAR __builtin_amdgcn_s_barrier()
; #define PG8_SCHED __builtin_amdgcn_sched_barrier(0)
; template <class Epi, class Order = StaticOrder, bool HALFN = false>
; __device__ __forceinline__ void gemm_phase(LAS unsigned char* lds, const Gemm g, const Epi& E) {
;     ...
;             PG8_WAIT_V(8); PG8_WAIT_L(0); PG8_BAR; PG8_MMA(0, 0, At, B0); if constexpr (!HALFN) PG8_MMA(0, 1, At, B1); PG8_BAR; PG8_SCHED;
;             PG8_LDA(At, 0, 1); PG8_STAGE(PG8_SB(0, 0), b2, voffB); PG8_STAGE(PG8_SB(0, 1), b2 + hstepB, voffB); PG8_STAGE(PG8_SA(0, 0), a2, voffA);
;             PG8_WAIT_V(8); PG8_WAIT_L(0); PG8_BAR; PG8_MMA(1, 0, At, B0); if constexpr (!HALFN) PG8_MMA(1, 1, At, B1); PG8_BAR; PG8_SCHED;
	s_setprio 1
	s_waitcnt lgkmcnt(0)
	v_mfma_f32_16x16x32_bf16 v[126:129], v[148:151], v[208:211], v[126:129]
	v_mfma_f32_16x16x32_bf16 v[122:125], v[156:159], v[208:211], v[122:125]
	v_mfma_f32_16x16x32_bf16 v[114:117], v[148:151], v[216:219], v[114:117]
	v_mfma_f32_16x16x32_bf16 v[106:109], v[156:159], v[216:219], v[106:109]
	v_mfma_f32_16x16x32_bf16 v[102:105], v[148:151], v[224:227], v[102:105]
	v_mfma_f32_16x16x32_bf16 v[94:97], v[156:159], v[224:227], v[94:97]
	v_mfma_f32_16x16x32_bf16 v[86:89], v[148:151], v[232:235], v[86:89]
	v_mfma_f32_16x16x32_bf16 v[78:81], v[156:159], v[232:235], v[78:81]
	v_mfma_f32_16x16x32_bf16 v[126:129], v[152:155], v[212:215], v[126:129]
	v_mfma_f32_16x16x32_bf16 v[122:125], v[168:171], v[212:215], v[122:125]
	v_mfma_f32_16x16x32_bf16 v[114:117], v[152:155], v[220:223], v[114:117]
	v_mfma_f32_16x16x32_bf16 v[106:109], v[168:171], v[220:223], v[106:109]
	v_mfma_f32_16x16x32_bf16 v[102:105], v[152:155], v[228:231], v[102:105]
	v_mfma_f32_16x16x32_bf16 v[94:97], v[168:171], v[228:231], v[94:97]
	v_mfma_f32_16x16x32_bf16 v[86:89], v[152:155], v[236:239], v[86:89]
	v_mfma_f32_16x16x32_bf16 v[78:81], v[168:171], v[236:239], v[78:81]
	s_setprio 0
	s_setprio 1
	v_mfma_f32_16x16x32_bf16 v[118:121], v[172:175], v[208:211], v[118:121]
	v_mfma_f32_16x16x32_bf16 v[110:113], v[180:183], v[208:211], v[110:113]
	v_mfma_f32_16x16x32_bf16 v[98:101], v[172:175], v[216:219], v[98:101]
	v_mfma_f32_16x16x32_bf16 v[90:93], v[180:183], v[216:219], v[90:93]
	v_mfma_f32_16x16x32_bf16 v[82:85], v[172:175], v[224:227], v[82:85]
	v_mfma_f32_16x16x32_bf16 v[74:77], v[180:183], v[224:227], v[74:77]
	v_mfma_f32_16x16x32_bf16 v[70:73], v[172:175], v[232:235], v[70:73]
	v_mfma_f32_16x16x32_bf16 v[66:69], v[180:183], v[232:235], v[66:69]
	v_mfma_f32_16x16x32_bf16 v[118:121], v[176:179], v[212:215], v[118:121]
	v_mfma_f32_16x16x32_bf16 v[110:113], v[184:187], v[212:215], v[110:113]
	v_mfma_f32_16x16x32_bf16 v[98:101], v[176:179], v[220:223], v[98:101]
	v_mfma_f32_16x16x32_bf16 v[90:93], v[184:187], v[220:223], v[90:93]
	v_mfma_f32_16x16x32_bf16 v[82:85], v[176:179], v[228:231], v[82:85]
	v_mfma_f32_16x16x32_bf16 v[74:77], v[184:187], v[228:231], v[74:77]
	v_mfma_f32_16x16x32_bf16 v[70:73], v[176:179], v[236:239], v[70:73]
	v_mfma_f32_16x16x32_bf16 v[66:69], v[184:187], v[236:239], v[66:69]
	s_setprio 0
	s_barrier
	s_add_i32 s23, s23, s56
	v_lshl_add_u64 v[160:161], s[4:5], 0, v[132:133]
	s_mov_b32 m0, s23
	ds_read_b128 v[208:211], v147 offset:16384
	ds_read_b128 v[212:215], v147 offset:17408
	ds_read_b128 v[216:219], v147 offset:18432
	ds_read_b128 v[220:223], v147 offset:19456
	ds_read_b128 v[224:227], v147 offset:20480
	ds_read_b128 v[228:231], v147 offset:21504
	ds_read_b128 v[232:235], v147 offset:22528
	ds_read_b128 v[236:239], v147 offset:23552
	global_load_lds_dwordx4 v[160:161], off sc0
	s_add_i32 m0, s23, 0x2000
	s_add_u32 s24, s4, 0x80000
	v_lshl_add_u64 v[240:241], s[4:5], 0, v[136:137]
	s_addc_u32 s25, s5, 0
	s_add_i32 s23, s26, s56
	global_load_lds_dwordx4 v[240:241], off sc0
	v_lshl_add_u64 v[242:243], s[24:25], 0, v[132:133]
	s_mov_b32 m0, s23
	v_lshl_add_u64 v[244:245], s[6:7], 0, v[134:135]
	global_load_lds_dwordx4 v[242:243], off sc0
	v_lshl_add_u64 v[242:243], s[24:25], 0, v[136:137]
	s_add_i32 m0, s23, 0x2000
	s_nop 0
	global_load_lds_dwordx4 v[242:243], off sc0
	v_lshl_add_u64 v[242:243], s[6:7], 0, v[130:131]
	s_mov_b32 m0, s53
	s_nop 0
	global_load_lds_dwordx4 v[242:243], off sc0
	s_mov_b32 m0, s80
	s_nop 0
	global_load_lds_dwordx4 v[244:245], off sc0
	s_waitcnt vmcnt(8)
	s_waitcnt lgkmcnt(0)
	s_barrier
	s_setprio 1
	s_waitcnt lgkmcnt(0)
	v_mfma_f32_16x16x32_bf16 v[62:65], v[148:151], v[208:211], v[62:65]
	v_mfma_f32_16x16x32_bf16 v[58:61], v[156:159], v[208:211], v[58:61]
	v_mfma_f32_16x16x32_bf16 v[54:57], v[148:151], v[216:219], v[54:57]
	v_mfma_f32_16x16x32_bf16 v[46:49], v[156:159], v[216:219], v[46:49]
	v_mfma_f32_16x16x32_bf16 v[38:41], v[148:151], v[224:227], v[38:41]
	v_mfma_f32_16x16x32_bf16 v[30:33], v[156:159], v[224:227], v[30:33]
	v_mfma_f32_16x16x32_bf16 v[22:25], v[148:151], v[232:235], v[22:25]
	v_mfma_f32_16x16x32_bf16 v[14:17], v[156:159], v[232:235], v[14:17]
	v_mfma_f32_16x16x32_bf16 v[62:65], v[152:155], v[212:215], v[62:65]
	v_mfma_f32_16x16x32_bf16 v[58:61], v[168:171], v[212:215], v[58:61]
	v_mfma_f32_16x16x32_bf16 v[54:57], v[152:155], v[220:223], v[54:57]
	v_mfma_f32_16x16x32_bf16 v[46:49], v[168:171], v[220:223], v[46:49]
	v_mfma_f32_16x16x32_bf16 v[38:41], v[152:155], v[228:231], v[38:41]
	v_mfma_f32_16x16x32_bf16 v[30:33], v[168:171], v[228:231], v[30:33]
	v_mfma_f32_16x16x32_bf16 v[22:25], v[152:155], v[236:239], v[22:25]
	v_mfma_f32_16x16x32_bf16 v[14:17], v[168:171], v[236:239], v[14:17]
	s_setprio 0
	s_setprio 1
	v_mfma_f32_16x16x32_bf16 v[50:53], v[172:175], v[208:211], v[50:53]
	v_mfma_f32_16x16x32_bf16 v[42:45], v[180:183], v[208:211], v[42:45]
	v_mfma_f32_16x16x32_bf16 v[34:37], v[172:175], v[216:219], v[34:37]
	v_mfma_f32_16x16x32_bf16 v[26:29], v[180:183], v[216:219], v[26:29]
	v_mfma_f32_16x16x32_bf16 v[18:21], v[172:175], v[224:227], v[18:21]
	v_mfma_f32_16x16x32_bf16 v[10:13], v[180:183], v[224:227], v[10:13]
	v_mfma_f32_16x16x32_bf16 v[6:9], v[172:175], v[232:235], v[6:9]
	v_mfma_f32_16x16x32_bf16 v[2:5], v[180:183], v[232:235], v[2:5]
	v_mfma_f32_16x16x32_bf16 v[50:53], v[176:179], v[212:215], v[50:53]
	v_mfma_f32_16x16x32_bf16 v[42:45], v[184:187], v[212:215], v[42:45]
	v_mfma_f32_16x16x32_bf16 v[34:37], v[176:179], v[220:223], v[34:37]
	v_mfma_f32_16x16x32_bf16 v[26:29], v[184:187], v[220:223], v[26:29]
	v_mfma_f32_16x16x32_bf16 v[18:21], v[176:179], v[228:231], v[18:21]
	v_mfma_f32_16x16x32_bf16 v[10:13], v[184:187], v[228:231], v[10:13]
	v_mfma_f32_16x16x32_bf16 v[6:9], v[176:179], v[236:239], v[6:9]
	v_mfma_f32_16x16x32_bf16 v[2:5], v[184:187], v[236:239], v[2:5]
	s_setprio 0
	s_barrier
; #define PG8_STAGE(bufoff, gbase, voff) do { _Pragma("unroll") for (int _i = 0; _i < 2; ++_i) \
;         __builtin_amdgcn_global_load_lds((const unsigned*)((const char*)(gbase) + (voff)[_i]), (LAS unsigned*)(lds + (bufoff) + ldsw + _i * 8192), 16, 0, 0); } while (0)
; #define PG8_LDA(dst, b, h) do { _Pragma("unroll") for (int m = 0; m < 4; ++m) _Pragma("unroll") for (int k = 0; k < 2; ++k) dst[m][k] = *(const LAS bf16x8*)(lds + PG8_SA(b, h) + aoff + m * 2048 + k * 1024); } while (0)
; #define PG8_LDB(dst, b, h) do { _Pragma("unroll") for (int n = 0; n < 2; ++n) _Pragma("unroll") for (int k = 0; k < 2; ++k) dst[n][k] = *(const LAS bf16x8*)(lds + PG8_SB(b, h) + boff + n * 2048 + k * 1024); } while (0)
; #define PG8_MMA(ai, bj, At, Bt) do { __builtin_amdgcn_s_setprio(1); _Pragma("unroll") for (int m = 0; m < 4; ++m) _Pragma("unroll") for (int n = 0; n < 2; ++n) _Pragma("unroll") for (int k = 0; k < 2; ++k) \
;         acc[ai][bj][m][n] = __builtin_amdgcn_mfma_f32_16x16x32_bf16(Bt[n][k], At[m][k], acc[ai][bj][m][n], 0, 0, 0); __builtin_amdgcn_s_setprio(0); } while (0)
; #define PG8_WAIT_V(n) asm volatile("s_waitcnt vmcnt(" #n ")" ::: "memory")
; #define PG8_WAIT_L(n) asm volatile("s_waitcnt lgkmcnt(" #n ")" ::: "memory")
; #define PG8_BAR __builtin_amdgcn_s_barrier()
; #define PG8_SCHED __builtin_amdgcn_sched_barrier(0)
; template <class Epi, class Order = StaticOrder, bool HALFN = false>
; __device__ __forceinline__ void gemm_phase(LAS unsigned char* lds, const Gemm g, const Epi& E) {
;     ...
;             PG8_LDB(B0, 1, 0); if constexpr (!HALFN) PG8_LDB(B1, 1, 1); PG8_SCHED; PG8_LDA(At, 1, 0); PG8_STAGE(PG8_SA(0, 1), a2 + hstepA, voffA);
;             PG8_WAIT_V(8); PG8_WAIT_L(0); PG8_BAR; PG8_MMA(0, 0, At, B0); if constexpr (!HALFN) PG8_MMA(0, 1, At, B1); PG8_BAR; PG8_SCHED;
	s_add_i32 s23, 0, 0x18000
	v_add_u32_e32 v142, s23, v145
	s_add_i32 s24, 0, 0x1c000
	ds_read_b128 v[148:151], v142
	ds_read_b128 v[152:155], v142 offset:1024
	ds_read_b128 v[156:159], v142 offset:2048
	ds_read_b128 v[168:171], v142 offset:3072
	v_add_u32_e32 v142, s24, v145
	ds_read_b128 v[172:175], v142
	ds_read_b128 v[176:179], v142 offset:1024
	ds_read_b128 v[180:183], v142 offset:2048
	ds_read_b128 v[184:187], v142 offset:3072
	s_add_u32 s6, s6, 0x80000
	s_addc_u32 s7, s7, 0
	s_mov_b32 m0, s81
	v_lshl_add_u64 v[246:247], s[6:7], 0, v[130:131]
	ds_read_b128 v[208:211], v147 offset:32768
	ds_read_b128 v[212:215], v147 offset:33792
	ds_read_b128 v[216:219], v147 offset:34816
	ds_read_b128 v[220:223], v147 offset:35840
	ds_read_b128 v[224:227], v147 offset:36864
	ds_read_b128 v[228:231], v147 offset:37888
	ds_read_b128 v[232:235], v147 offset:38912
	ds_read_b128 v[236:239], v147 offset:39936
	global_load_lds_dwordx4 v[246:247], off sc0
	v_lshl_add_u64 v[246:247], s[6:7], 0, v[134:135]
	s_mov_b32 m0, s82
	s_nop 0
	global_load_lds_dwordx4 v[246:247], off sc0
	s_waitcnt vmcnt(8)
	s_waitcnt lgkmcnt(0)
	s_barrier
	s_setprio 1
	s_waitcnt lgkmcnt(0)
	v_mfma_f32_16x16x32_bf16 v[126:129], v[148:151], v[208:211], v[126:129]
	v_mfma_f32_16x16x32_bf16 v[122:125], v[156:159], v[208:211], v[122:125]
	v_mfma_f32_16x16x32_bf16 v[114:117], v[148:151], v[216:219], v[114:117]
	v_mfma_f32_16x16x32_bf16 v[106:109], v[156:159], v[216:219], v[106:109]
	v_mfma_f32_16x16x32_bf16 v[102:105], v[148:151], v[224:227], v[102:105]
	v_mfma_f32_16x16x32_bf16 v[94:97], v[156:159], v[224:227], v[94:97]
	v_mfma_f32_16x16x32_bf16 v[86:89], v[148:151], v[232:235], v[86:89]
	v_mfma_f32_16x16x32_bf16 v[78:81], v[156:159], v[232:235], v[78:81]
	v_mfma_f32_16x16x32_bf16 v[126:129], v[152:155], v[212:215], v[126:129]
	v_mfma_f32_16x16x32_bf16 v[122:125], v[168:171], v[212:215], v[122:125]
	v_mfma_f32_16x16x32_bf16 v[114:117], v[152:155], v[220:223], v[114:117]
	v_mfma_f32_16x16x32_bf16 v[106:109], v[168:171], v[220:223], v[106:109]
	v_mfma_f32_16x16x32_bf16 v[102:105], v[152:155], v[228:231], v[102:105]
	v_mfma_f32_16x16x32_bf16 v[94:97], v[168:171], v[228:231], v[94:97]
	v_mfma_f32_16x16x32_bf16 v[86:89], v[152:155], v[236:239], v[86:89]
	v_mfma_f32_16x16x32_bf16 v[78:81], v[168:171], v[236:239], v[78:81]
	s_setprio 0
	s_setprio 1
	v_mfma_f32_16x16x32_bf16 v[118:121], v[172:175], v[208:211], v[118:121]
	v_mfma_f32_16x16x32_bf16 v[110:113], v[180:183], v[208:211], v[110:113]
	v_mfma_f32_16x16x32_bf16 v[98:101], v[172:175], v[216:219], v[98:101]
	v_mfma_f32_16x16x32_bf16 v[90:93], v[180:183], v[216:219], v[90:93]
	v_mfma_f32_16x16x32_bf16 v[82:85], v[172:175], v[224:227], v[82:85]
	v_mfma_f32_16x16x32_bf16 v[74:77], v[180:183], v[224:227], v[74:77]
	v_mfma_f32_16x16x32_bf16 v[70:73], v[172:175], v[232:235], v[70:73]
	v_mfma_f32_16x16x32_bf16 v[66:69], v[180:183], v[232:235], v[66:69]
	v_mfma_f32_16x16x32_bf16 v[118:121], v[176:179], v[212:215], v[118:121]
	v_mfma_f32_16x16x32_bf16 v[110:113], v[184:187], v[212:215], v[110:113]
	v_mfma_f32_16x16x32_bf16 v[98:101], v[176:179], v[220:223], v[98:101]
	v_mfma_f32_16x16x32_bf16 v[90:93], v[184:187], v[220:223], v[90:93]
	v_mfma_f32_16x16x32_bf16 v[82:85], v[176:179], v[228:231], v[82:85]
	v_mfma_f32_16x16x32_bf16 v[74:77], v[184:187], v[228:231], v[74:77]
	v_mfma_f32_16x16x32_bf16 v[70:73], v[176:179], v[236:239], v[70:73]
	v_mfma_f32_16x16x32_bf16 v[66:69], v[184:187], v[236:239], v[66:69]
	s_setprio 0
	s_barrier
; #define PG8_STAGE(bufoff, gbase, voff) do { _Pragma("unroll") for (int _i = 0; _i < 2; ++_i) \
;         __builtin_amdgcn_global_load_lds((const unsigned*)((const char*)(gbase) + (voff)[_i]), (LAS unsigned*)(lds + (bufoff) + ldsw + _i * 8192), 16, 0, 0); } while (0)
; #define PG8_LDA(dst, b, h) do { _Pragma("unroll") for (int m = 0; m < 4; ++m) _Pragma("unroll") for (int k = 0; k < 2; ++k) dst[m][k] = *(const LAS bf16x8*)(lds + PG8_SA(b, h) + aoff + m * 2048 + k * 1024); } while (0)
; #define PG8_MMA(ai, bj, At, Bt) do { __builtin_amdgcn_s_setprio(1); _Pragma("unroll") for (int m = 0; m < 4; ++m) _Pragma("unroll") for (int n = 0; n < 2; ++n) _Pragma("unroll") for (int k = 0; k < 2; ++k) \
;         acc[ai][bj][m][n] = __builtin_amdgcn_mfma_f32_16x16x32_bf16(Bt[n][k], At[m][k], acc[ai][bj][m][n], 0, 0, 0); __builtin_amdgcn_s_setprio(0); } while (0)
; #define PG8_WAIT_V(n) asm volatile("s_waitcnt vmcnt(" #n ")" ::: "memory")
; #define PG8_WAIT_L(n) asm volatile("s_waitcnt lgkmcnt(" #n ")" ::: "memory")
; #define PG8_BAR __builtin_amdgcn_s_barrier()
; #define PG8_SCHED __builtin_amdgcn_sched_barrier(0)
; template <class Epi, class Order = StaticOrder, bool HALFN = false>
; __device__ __forceinline__ void gemm_phase(LAS unsigned char* lds, const Gemm g, const Epi& E) {
;     ...
;             PG8_LDA(At, 1, 1); PG8_STAGE(PG8_SB(1, 0), b3, voffB); PG8_STAGE(PG8_SB(1, 1), b3 + hstepB, voffB); PG8_STAGE(PG8_SA(1, 0), a3, voffA);
;             PG8_WAIT_V(8); PG8_WAIT_L(0); PG8_BAR; PG8_MMA(1, 0, At, B0); if constexpr (!HALFN) PG8_MMA(1, 1, At, B1); PG8_BAR; PG8_SCHED;
;         }
;         if (wr == 0) PG8_BAR;
	s_add_i32 s6, s23, s56
	v_lshl_add_u64 v[160:161], v[160:161], 0, s[60:61]
	s_mov_b32 m0, s6
	ds_read_b128 v[208:211], v147 offset:49152
	ds_read_b128 v[212:215], v147 offset:50176
	ds_read_b128 v[216:219], v147 offset:51200
	ds_read_b128 v[220:223], v147 offset:52224
	ds_read_b128 v[224:227], v147 offset:53248
	ds_read_b128 v[228:231], v147 offset:54272
	ds_read_b128 v[232:235], v147 offset:55296
	ds_read_b128 v[236:239], v147 offset:56320
	global_load_lds_dwordx4 v[160:161], off sc0
	s_add_i32 m0, s6, 0x2000
	s_add_u32 s4, s4, 0x80080
	v_lshl_add_u64 v[160:161], v[240:241], 0, s[60:61]
	s_addc_u32 s5, s5, 0
	s_add_i32 s6, s24, s56
	global_load_lds_dwordx4 v[160:161], off sc0
	v_lshl_add_u64 v[160:161], s[4:5], 0, v[132:133]
	s_mov_b32 m0, s6
	s_nop 0
	global_load_lds_dwordx4 v[160:161], off sc0
	v_lshl_add_u64 v[160:161], s[4:5], 0, v[136:137]
	s_add_i32 m0, s6, 0x2000
	s_nop 0
	global_load_lds_dwordx4 v[160:161], off sc0
	v_lshl_add_u64 v[160:161], v[242:243], 0, s[60:61]
	s_mov_b32 m0, s95
	s_nop 0
	global_load_lds_dwordx4 v[160:161], off sc0
	v_lshl_add_u64 v[160:161], v[244:245], 0, s[60:61]
	s_mov_b32 m0, s15
	s_nop 0
	global_load_lds_dwordx4 v[160:161], off sc0
	s_waitcnt vmcnt(8)
	s_waitcnt lgkmcnt(0)
	s_barrier
	s_setprio 1
	s_waitcnt lgkmcnt(0)
	v_mfma_f32_16x16x32_bf16 v[62:65], v[148:151], v[208:211], v[62:65]
	v_mfma_f32_16x16x32_bf16 v[58:61], v[156:159], v[208:211], v[58:61]
	v_mfma_f32_16x16x32_bf16 v[54:57], v[148:151], v[216:219], v[54:57]
	v_mfma_f32_16x16x32_bf16 v[46:49], v[156:159], v[216:219], v[46:49]
	v_mfma_f32_16x16x32_bf16 v[38:41], v[148:151], v[224:227], v[38:41]
	v_mfma_f32_16x16x32_bf16 v[30:33], v[156:159], v[224:227], v[30:33]
	v_mfma_f32_16x16x32_bf16 v[22:25], v[148:151], v[232:235], v[22:25]
	v_mfma_f32_16x16x32_bf16 v[14:17], v[156:159], v[232:235], v[14:17]
	v_mfma_f32_16x16x32_bf16 v[62:65], v[152:155], v[212:215], v[62:65]
	v_mfma_f32_16x16x32_bf16 v[58:61], v[168:171], v[212:215], v[58:61]
	v_mfma_f32_16x16x32_bf16 v[54:57], v[152:155], v[220:223], v[54:57]
	v_mfma_f32_16x16x32_bf16 v[46:49], v[168:171], v[220:223], v[46:49]
	v_mfma_f32_16x16x32_bf16 v[38:41], v[152:155], v[228:231], v[38:41]
	v_mfma_f32_16x16x32_bf16 v[30:33], v[168:171], v[228:231], v[30:33]
	v_mfma_f32_16x16x32_bf16 v[22:25], v[152:155], v[236:239], v[22:25]
	v_mfma_f32_16x16x32_bf16 v[14:17], v[168:171], v[236:239], v[14:17]
	s_setprio 0
	s_setprio 1
	v_mfma_f32_16x16x32_bf16 v[50:53], v[172:175], v[208:211], v[50:53]
	v_mfma_f32_16x16x32_bf16 v[42:45], v[180:183], v[208:211], v[42:45]
	v_mfma_f32_16x16x32_bf16 v[34:37], v[172:175], v[216:219], v[34:37]
	v_mfma_f32_16x16x32_bf16 v[26:29], v[180:183], v[216:219], v[26:29]
	v_mfma_f32_16x16x32_bf16 v[18:21], v[172:175], v[224:227], v[18:21]
	v_mfma_f32_16x16x32_bf16 v[10:13], v[180:183], v[224:227], v[10:13]
	v_mfma_f32_16x16x32_bf16 v[6:9], v[172:175], v[232:235], v[6:9]
	v_mfma_f32_16x16x32_bf16 v[2:5], v[180:183], v[232:235], v[2:5]
	v_mfma_f32_16x16x32_bf16 v[50:53], v[176:179], v[212:215], v[50:53]
	v_mfma_f32_16x16x32_bf16 v[42:45], v[184:187], v[212:215], v[42:45]
	v_mfma_f32_16x16x32_bf16 v[34:37], v[176:179], v[220:223], v[34:37]
	v_mfma_f32_16x16x32_bf16 v[26:29], v[184:187], v[220:223], v[26:29]
	v_mfma_f32_16x16x32_bf16 v[18:21], v[176:179], v[228:231], v[18:21]
	v_mfma_f32_16x16x32_bf16 v[10:13], v[184:187], v[228:231], v[10:13]
	v_mfma_f32_16x16x32_bf16 v[6:9], v[176:179], v[236:239], v[6:9]
	v_mfma_f32_16x16x32_bf16 v[2:5], v[184:187], v[236:239], v[2:5]
	s_setprio 0
	s_barrier
	s_add_i32 s22, s22, 2
	s_add_u32 s62, s62, 0x100
	s_addc_u32 s63, s63, 0
	s_add_u32 s20, s20, 0x100
	s_addc_u32 s21, s21, 0
	s_cmp_gt_u32 s22, 29
	s_cbranch_scc0 .LBB0_194
	s_and_b64 vcc, exec, s[46:47]
	s_cbranch_vccz .LBB0_197
	s_barrier

; #define PG8_STAGE(bufoff, gbase, voff) do { _Pragma("unroll") for (int _i = 0; _i < 2; ++_i) \
;         __builtin_amdgcn_global_load_lds((const unsigned*)((const char*)(gbase) + (voff)[_i]), (LAS unsigned*)(lds + (bufoff) + ldsw + _i * 8192), 16, 0, 0); } while (0)
; #define PG8_WAIT_V(n) asm volatile("s_waitcnt vmcnt(" #n ")" ::: "memory")
; #define PG8_BAR __builtin_amdgcn_s_barrier()
; template <class Epi, class Order = StaticOrder, bool HALFN = false>
; __device__ __forceinline__ void gemm_phase(LAS unsigned char* lds, const Gemm g, const Epi& E) {
;     ...
;     for (int i = 0; i < 2; ++i) { int R, C; stage_rc(tid * 16 + i * 8192, R, C); const int Rb = (R & ~31) + perm32(R & 31);
;         voffA[i] = (unsigned)(R * g.lda + C) * 2u; voffB[i] = (unsigned)(Rb * g.ldb + C) * 2u; }
;     const size_t kstep = (size_t)(BK * 2);
;     const size_t hstepA = (size_t)HALF * g.lda * 2, hstepB = (size_t)HALF * g.ldb * 2;
;     const size_t tstepA = 2 * hstepA, tstepB = 2 * hstepB;
;     const unsigned ldsw = (unsigned)wid * 1024u;
;     const int aoff = lds_byte(wr * 64 + fr, fq * 8), boff = lds_byte(wc * 32 + fr, fq * 8);
;     ...
;     const char* cA = (const char*)g.A + (size_t)cur.pm * tstepA + (size_t)cur.pn * g.a_pn_off * 2; const char* cB = (const char*)g.Bt + (size_t)cur.pn * tstepB + (HALFN ? (size_t)(cur.half - 1) * hstepB : (size_t)0);
;     PG8_STAGE(PG8_SB(0, 0), cB, voffB); PG8_STAGE(PG8_SB(0, 1), cB + hstepB, voffB); PG8_STAGE(PG8_SA(0, 0), cA, voffA); PG8_STAGE(PG8_SA(0, 1), cA + hstepA, voffA);
;     if (wr == 1) PG8_BAR;
;     PG8_WAIT_V(2); PG8_BAR;
;     PG8_STAGE(PG8_SB(1, 0), cB + kstep, voffB); PG8_STAGE(PG8_SA(1, 0), cA + kstep, voffA); PG8_STAGE(PG8_SB(1, 1), cB + hstepB + kstep, voffB);
;     PG8_WAIT_V(6); PG8_BAR;
.LBB0_229:
	s_andn2_b64 vcc, exec, s[4:5]
	s_cbranch_vccnz .LBB0_270
	v_ashrrev_i32_e32 v2, 31, v14
	v_lshrrev_b32_e32 v2, 26, v2
	v_add_u32_e32 v2, v14, v2
	v_ashrrev_i32_e32 v10, 6, v2
	v_bfe_i32 v2, v14, 27, 1
	v_lshlrev_b32_e32 v1, 4, v14
	v_lshrrev_b32_e32 v2, 22, v2
	v_add_u32_e32 v2, v1, v2
	v_and_b32_e32 v2, 0xfffffc00, v2
	v_sub_u32_e32 v2, v1, v2
	s_waitcnt lgkmcnt(0)
	v_lshrrev_b32_e32 v3, 4, v2
	v_bitop3_b32 v2, v3, v2, 32 bitop3:0x6c
	v_ashrrev_i32_e32 v4, 31, v2
	v_lshrrev_b32_e32 v4, 26, v4
	v_add_u32_e32 v4, v2, v4
	v_lshlrev_b32_e32 v3, 3, v10
	v_ashrrev_i32_e32 v11, 6, v4
	v_and_b32_e32 v4, 0xc0, v4
	v_and_b32_e32 v3, -16, v3
	v_sub_u32_e32 v2, v2, v4
	v_add_u32_e32 v3, v11, v3
	v_ashrrev_i16_sdwa v2, v190, sext(v2) dst_sel:DWORD dst_unused:UNUSED_PAD src0_sel:DWORD src1_sel:BYTE_0
	v_lshlrev_b32_e32 v5, 5, v10
	v_bfe_i32 v12, v2, 0, 16
	v_lshlrev_b32_e32 v2, 1, v3
	v_lshrrev_b32_e32 v4, 2, v3
	v_and_b32_e32 v6, 3, v11
	s_mov_b32 s4, 0xfffe0
	v_and_b32_e32 v5, 32, v5
	v_and_b32_e32 v2, 24, v2
	v_and_b32_e32 v4, 4, v4
	v_and_or_b32 v6, v3, s4, v6
	v_or3_b32 v2, v6, v4, v2
	v_add_lshl_u32 v4, v5, v12, 1
	v_add_u32_e32 v1, 0x2000, v1
	v_lshl_add_u32 v68, v2, 12, v4
	v_ashrrev_i32_e32 v2, 31, v1
	v_lshrrev_b32_e32 v2, 22, v2
	v_add_u32_e32 v2, v1, v2
	v_ashrrev_i32_e32 v13, 10, v2
	v_mul_i32_i24_e32 v2, 0x400, v13
	v_sub_u32_e32 v1, v1, v2
	v_lshrrev_b32_e32 v2, 4, v1
	v_bitop3_b32 v1, v2, v1, 32 bitop3:0x6c
	v_lshl_add_u32 v66, v3, 12, v4
	v_ashrrev_i32_e32 v3, 31, v1
	v_lshrrev_b32_e32 v3, 26, v3
	v_lshlrev_b32_e32 v2, 3, v13
	v_add_u32_e32 v3, v1, v3
	s_add_u32 s10, s10, 0x3800000
	v_and_b32_e32 v2, -16, v2
	v_ashrrev_i32_e32 v15, 6, v3
	s_addc_u32 s11, s11, 0
	v_add_u32_e32 v2, v15, v2
	v_and_b32_e32 v5, 3, v15
	s_ashr_i32 s8, s6, 6
	s_ashr_i32 s51, s50, 31
	s_ashr_i32 s53, s52, 31
	s_ashr_i32 s7, s6, 8
	v_and_or_b32 v5, v2, s4, v5
	s_lshl_b32 s15, s8, 10
	s_lshl_b64 s[20:21], s[50:51], 20
	s_lshl_b64 s[4:5], s[52:53], 20
	s_add_u32 s9, s10, s4
	s_addc_u32 s16, s11, s5
	s_ashr_i32 s81, s80, 31
	v_and_b32_e32 v3, 0xc0, v3
	s_lshl_b64 s[4:5], s[80:81], 19
	v_sub_u32_e32 v1, v1, v3
	s_add_u32 s22, s9, s4
	v_ashrrev_i16_sdwa v1, v190, sext(v1) dst_sel:DWORD dst_unused:UNUSED_PAD src0_sel:DWORD src1_sel:BYTE_0
	s_addc_u32 s23, s16, s5
	v_lshlrev_b32_e32 v4, 5, v13
	v_bfe_i32 v16, v1, 0, 16
	v_lshlrev_b32_e32 v1, 1, v2
	v_lshrrev_b32_e32 v3, 2, v2
	s_add_u32 s4, s22, 0xfff80000
	v_and_b32_e32 v4, 32, v4
	v_and_b32_e32 v1, 24, v1
	v_and_b32_e32 v3, 4, v3
	s_addc_u32 s5, s23, -1
	s_add_i32 s16, s15, 0
	v_or3_b32 v1, v5, v3, v1
	v_add_lshl_u32 v3, v4, v16, 1
	s_add_i32 m0, s16, 0x10000
	v_lshl_add_u32 v72, v1, 12, v3
	global_load_lds_dwordx4 v68, s[4:5] sc0
	s_add_i32 m0, s16, 0x12000
	s_add_i32 s17, s16, 0x14000
	s_add_i32 s18, s16, 0x16000
	global_load_lds_dwordx4 v72, s[4:5] sc0
	s_mov_b32 m0, s17
	s_add_u32 s92, s0, s20
	global_load_lds_dwordx4 v68, s[22:23] sc0
	s_mov_b32 m0, s18
	s_addc_u32 s93, s1, s21
	s_add_i32 s19, s16, 0x2000
	global_load_lds_dwordx4 v72, s[22:23] sc0
	s_mov_b32 m0, s16
	s_add_u32 s22, s92, 0x80000
	v_lshl_add_u32 v70, v2, 12, v3
	global_load_lds_dwordx4 v66, s[92:93] sc0
	s_mov_b32 m0, s19
	s_addc_u32 s23, s93, 0
	s_add_i32 s20, s16, 0x4000
	global_load_lds_dwordx4 v70, s[92:93] sc0
	s_mov_b32 m0, s20
	s_add_i32 s21, s16, 0x6000
	global_load_lds_dwordx4 v66, s[22:23] sc0
	s_mov_b32 m0, s21
	v_mov_b32_e32 v69, v0
	global_load_lds_dwordx4 v70, s[22:23] sc0
	v_mov_b32_e32 v73, v0
	v_mov_b32_e32 v67, v0
	v_mov_b32_e32 v71, v0
	s_cmp_eq_u32 s7, 1
	v_lshl_add_u64 v[8:9], s[4:5], 0, v[68:69]
	v_lshl_add_u64 v[6:7], s[4:5], 0, v[72:73]
	v_lshl_add_u64 v[2:3], s[92:93], 0, v[66:67]
	s_cselect_b64 s[46:47], -1, 0
	s_cmp_lg_u32 s7, 1
	v_lshl_add_u64 v[4:5], s[92:93], 0, v[70:71]
	s_cbranch_scc1 .LBB0_232
	s_barrier
.LBB0_232:
	v_bfe_u32 v79, v14, 4, 2
	v_and_b32_e32 v1, 15, v14
	v_lshlrev_b32_e32 v17, 4, v79
	v_lshlrev_b32_e32 v14, 2, v14
	s_lshl_b32 s22, s7, 6
	v_lshl_or_b32 v17, v1, 6, v17
	s_lshl_b32 s7, s7, 13
	v_and_b32_e32 v14, 32, v14
	v_bitop3_b32 v18, v17, s7, v14 bitop3:0xde
	s_lshl_b32 s7, s8, 5
	s_and_b32 s23, s7, 0x60
	s_add_i32 m0, s16, 0x18000
	v_lshl_add_u64 v[8:9], v[8:9], 0, s[60:61]
	s_lshl_b32 s7, s23, 7
	s_waitcnt vmcnt(2)
	s_barrier
	global_load_lds_dwordx4 v[8:9], off sc0
	v_lshl_add_u64 v[6:7], v[6:7], 0, s[60:61]
	s_add_i32 m0, s16, 0x1a000
	s_add_i32 s51, s16, 0x8000
	s_add_i32 s53, s16, 0xa000
	global_load_lds_dwordx4 v[6:7], off sc0
	v_lshl_add_u64 v[2:3], v[2:3], 0, s[60:61]
	s_mov_b32 m0, s51
	s_add_u32 s8, s4, 0x80080
	global_load_lds_dwordx4 v[2:3], off sc0
	v_lshl_add_u64 v[2:3], v[4:5], 0, s[60:61]
	s_mov_b32 m0, s53
	s_addc_u32 s9, s5, 0
	s_add_i32 s56, s16, 0x1c000
	global_load_lds_dwordx4 v[2:3], off sc0
	v_lshl_add_u64 v[2:3], s[8:9], 0, v[68:69]
	s_mov_b32 m0, s56
	s_add_i32 s81, s16, 0x1e000
	global_load_lds_dwordx4 v[2:3], off sc0
	v_lshl_add_u64 v[2:3], s[8:9], 0, v[72:73]
	s_mov_b32 m0, s81
	s_cmpk_lt_u32 s6, 0x100
	global_load_lds_dwordx4 v[2:3], off sc0
	v_lshlrev_b32_e32 v2, 15, v10
	v_and_b32_e32 v2, 0xffff0000, v2
	v_lshl_add_u32 v2, v11, 12, v2
	v_and_b32_e32 v3, 1, v10
	v_lshl_or_b32 v2, v3, 6, v2
	v_lshl_add_u32 v74, v12, 1, v2
	v_lshlrev_b32_e32 v2, 15, v13
	v_and_b32_e32 v2, 0xffff0000, v2
	s_waitcnt vmcnt(6)
	v_lshl_add_u32 v2, v15, 12, v2
	v_and_b32_e32 v3, 1, v13
	v_lshl_or_b32 v2, v3, 6, v2
	v_bitop3_b32 v81, v17, s7, v14 bitop3:0xde
	s_cselect_b64 s[48:49], -1, 0
	s_or_b32 s36, s23, 0xfffff400
	s_or_b32 s37, s23, 0x400
	s_or_b32 s89, s23, 0xfffff800
	s_or_b32 s79, s23, 0xffffdc00
	v_mov_b32_e32 v75, v0
	v_lshl_add_u32 v76, v16, 1, v2
	v_mov_b32_e32 v77, v0
	s_mov_b32 s24, 0
	v_add_u32_e32 v83, 0, v18
	s_barrier
	s_branch .LBB0_235

; #define PG8_STAGE(bufoff, gbase, voff) do { _Pragma("unroll") for (int _i = 0; _i < 2; ++_i) \
;         __builtin_amdgcn_global_load_lds((const unsigned*)((const char*)(gbase) + (voff)[_i]), (LAS unsigned*)(lds + (bufoff) + ldsw + _i * 8192), 16, 0, 0); } while (0)
; #define PG8_LDA(dst, b, h) do { _Pragma("unroll") for (int m = 0; m < 4; ++m) _Pragma("unroll") for (int k = 0; k < 2; ++k) dst[m][k] = *(const LAS bf16x8*)(lds + PG8_SA(b, h) + aoff + m * 2048 + k * 1024); } while (0)
; #define PG8_LDB(dst, b, h) do { _Pragma("unroll") for (int n = 0; n < 2; ++n) _Pragma("unroll") for (int k = 0; k < 2; ++k) dst[n][k] = *(const LAS bf16x8*)(lds + PG8_SB(b, h) + boff + n * 2048 + k * 1024); } while (0)
; #define PG8_MMA(ai, bj, At, Bt) do { __builtin_amdgcn_s_setprio(1); _Pragma("unroll") for (int m = 0; m < 4; ++m) _Pragma("unroll") for (int n = 0; n < 2; ++n) _Pragma("unroll") for (int k = 0; k < 2; ++k) \
;         acc[ai][bj][m][n] = __builtin_amdgcn_mfma_f32_16x16x32_bf16(Bt[n][k], At[m][k], acc[ai][bj][m][n], 0, 0, 0); __builtin_amdgcn_s_setprio(0); } while (0)
; #define PG8_WAIT_V(n) asm volatile("s_waitcnt vmcnt(" #n ")" ::: "memory")
; #define PG8_WAIT_L(n) asm volatile("s_waitcnt lgkmcnt(" #n ")" ::: "memory")
; #define PG8_BAR __builtin_amdgcn_s_barrier()
; #define PG8_SCHED __builtin_amdgcn_sched_barrier(0)
; template <class Epi, class Order = StaticOrder, bool HALFN = false>
; __device__ __forceinline__ void gemm_phase(LAS unsigned char* lds, const Gemm g, const Epi& E) {
;     ...
;             PG8_LDB(B0, 0, 0); if constexpr (!HALFN) PG8_LDB(B1, 0, 1); PG8_SCHED; PG8_LDA(At, 0, 0); PG8_STAGE(PG8_SA(1, 1), a1 + hstepA, voffA);
;             PG8_WAIT_V(8); PG8_WAIT_L(0); PG8_BAR; PG8_MMA(0, 0, At, B0); if constexpr (!HALFN) PG8_MMA(0, 1, At, B1); PG8_BAR; PG8_SCHED;
;             PG8_LDA(At, 0, 1); PG8_STAGE(PG8_SB(0, 0), b2, voffB); PG8_STAGE(PG8_SB(0, 1), b2 + hstepB, voffB); PG8_STAGE(PG8_SA(0, 0), a2, voffA);
;             PG8_WAIT_V(8); PG8_WAIT_L(0); PG8_BAR; PG8_MMA(1, 0, At, B0); if constexpr (!HALFN) PG8_MMA(1, 1, At, B1); PG8_BAR; PG8_SCHED;
.LBB0_239:
	s_add_u32 s4, vcc_lo, 0xfff80080
	s_addc_u32 s5, vcc_hi, -1
	s_add_i32 s34, 0, 0x10000
	v_add_u32_e32 v78, s34, v81
	ds_read_b128 v[84:87], v78
	ds_read_b128 v[88:91], v78 offset:1024
	ds_read_b128 v[92:95], v78 offset:2048
	ds_read_b128 v[96:99], v78 offset:3072
	s_cmp_eq_u32 s31, 28
	s_cselect_b32 s9, s25, s5
	s_cselect_b32 s8, s26, s4
	s_cselect_b32 s5, s27, s30
	s_cselect_b32 s4, s28, s29
	v_lshl_add_u64 v[132:133], vcc, 0, v[74:75]
	s_add_i32 m0, s16, 0xc000
	ds_read_b128 v[100:103], v83
	ds_read_b128 v[104:107], v83 offset:1024
	ds_read_b128 v[108:111], v83 offset:2048
	ds_read_b128 v[112:115], v83 offset:3072
	ds_read_b128 v[116:119], v83 offset:4096
	ds_read_b128 v[120:123], v83 offset:5120
	ds_read_b128 v[124:127], v83 offset:6144
	ds_read_b128 v[128:131], v83 offset:7168
	global_load_lds_dwordx4 v[132:133], off sc0
	v_lshl_add_u64 v[132:133], vcc, 0, v[76:77]
	s_add_i32 m0, s16, 0xe000
	s_nop 0
	global_load_lds_dwordx4 v[132:133], off sc0
	s_waitcnt vmcnt(6)
	s_waitcnt lgkmcnt(0)
	s_barrier
	s_setprio 1
	s_waitcnt lgkmcnt(0)
	v_mfma_f32_16x16x32_bf16 v[62:65], v[84:87], v[100:103], v[62:65]
	v_mfma_f32_16x16x32_bf16 v[58:61], v[92:95], v[100:103], v[58:61]
	v_mfma_f32_16x16x32_bf16 v[54:57], v[84:87], v[108:111], v[54:57]
	v_mfma_f32_16x16x32_bf16 v[50:53], v[92:95], v[108:111], v[50:53]
	v_mfma_f32_16x16x32_bf16 v[46:49], v[84:87], v[116:119], v[46:49]
	v_mfma_f32_16x16x32_bf16 v[42:45], v[92:95], v[116:119], v[42:45]
	v_mfma_f32_16x16x32_bf16 v[38:41], v[84:87], v[124:127], v[38:41]
	v_mfma_f32_16x16x32_bf16 v[34:37], v[92:95], v[124:127], v[34:37]
	v_mfma_f32_16x16x32_bf16 v[62:65], v[88:91], v[104:107], v[62:65]
	v_mfma_f32_16x16x32_bf16 v[58:61], v[96:99], v[104:107], v[58:61]
	v_mfma_f32_16x16x32_bf16 v[54:57], v[88:91], v[112:115], v[54:57]
	v_mfma_f32_16x16x32_bf16 v[50:53], v[96:99], v[112:115], v[50:53]
	v_mfma_f32_16x16x32_bf16 v[46:49], v[88:91], v[120:123], v[46:49]
	v_mfma_f32_16x16x32_bf16 v[42:45], v[96:99], v[120:123], v[42:45]
	v_mfma_f32_16x16x32_bf16 v[38:41], v[88:91], v[128:131], v[38:41]
	v_mfma_f32_16x16x32_bf16 v[34:37], v[96:99], v[128:131], v[34:37]
	s_setprio 0
	s_barrier
	s_add_i32 s34, s34, s15
	v_lshl_add_u64 v[132:133], s[4:5], 0, v[68:69]
	s_mov_b32 m0, s34
	ds_read_b128 v[100:103], v83 offset:16384
	ds_read_b128 v[104:107], v83 offset:17408
	ds_read_b128 v[108:111], v83 offset:18432
	ds_read_b128 v[112:115], v83 offset:19456
	ds_read_b128 v[116:119], v83 offset:20480
	ds_read_b128 v[120:123], v83 offset:21504
	ds_read_b128 v[124:127], v83 offset:22528
	ds_read_b128 v[128:131], v83 offset:23552
	global_load_lds_dwordx4 v[132:133], off sc0
	s_add_i32 m0, s34, 0x2000
	s_add_u32 s34, s4, 0x80000
	v_lshl_add_u64 v[134:135], s[4:5], 0, v[72:73]
	s_addc_u32 s35, s5, 0
	global_load_lds_dwordx4 v[134:135], off sc0
	v_lshl_add_u64 v[138:139], s[8:9], 0, v[70:71]
	v_lshl_add_u64 v[136:137], s[8:9], 0, v[66:67]
	s_mov_b32 m0, s16
	s_nop 0
	global_load_lds_dwordx4 v[136:137], off sc0
	s_mov_b32 m0, s19
	s_nop 0
	global_load_lds_dwordx4 v[138:139], off sc0
	s_waitcnt vmcnt(6)
	s_waitcnt lgkmcnt(0)
	s_barrier
	s_setprio 1
	s_waitcnt lgkmcnt(0)
	v_mfma_f32_16x16x32_bf16 v[30:33], v[84:87], v[100:103], v[30:33]
	v_mfma_f32_16x16x32_bf16 v[26:29], v[92:95], v[100:103], v[26:29]
	v_mfma_f32_16x16x32_bf16 v[22:25], v[84:87], v[108:111], v[22:25]
	v_mfma_f32_16x16x32_bf16 v[18:21], v[92:95], v[108:111], v[18:21]
	v_mfma_f32_16x16x32_bf16 v[14:17], v[84:87], v[116:119], v[14:17]
	v_mfma_f32_16x16x32_bf16 v[10:13], v[92:95], v[116:119], v[10:13]
	v_mfma_f32_16x16x32_bf16 v[6:9], v[84:87], v[124:127], v[6:9]
	v_mfma_f32_16x16x32_bf16 v[2:5], v[92:95], v[124:127], v[2:5]
	v_mfma_f32_16x16x32_bf16 v[30:33], v[88:91], v[104:107], v[30:33]
	v_mfma_f32_16x16x32_bf16 v[26:29], v[96:99], v[104:107], v[26:29]
	v_mfma_f32_16x16x32_bf16 v[22:25], v[88:91], v[112:115], v[22:25]
	v_mfma_f32_16x16x32_bf16 v[18:21], v[96:99], v[112:115], v[18:21]
	v_mfma_f32_16x16x32_bf16 v[14:17], v[88:91], v[120:123], v[14:17]
	v_mfma_f32_16x16x32_bf16 v[10:13], v[96:99], v[120:123], v[10:13]
	v_mfma_f32_16x16x32_bf16 v[6:9], v[88:91], v[128:131], v[6:9]
	v_mfma_f32_16x16x32_bf16 v[2:5], v[96:99], v[128:131], v[2:5]
	s_setprio 0
	s_barrier
; #define PG8_STAGE(bufoff, gbase, voff) do { _Pragma("unroll") for (int _i = 0; _i < 2; ++_i) \
;         __builtin_amdgcn_global_load_lds((const unsigned*)((const char*)(gbase) + (voff)[_i]), (LAS unsigned*)(lds + (bufoff) + ldsw + _i * 8192), 16, 0, 0); } while (0)
; #define PG8_LDA(dst, b, h) do { _Pragma("unroll") for (int m = 0; m < 4; ++m) _Pragma("unroll") for (int k = 0; k < 2; ++k) dst[m][k] = *(const LAS bf16x8*)(lds + PG8_SA(b, h) + aoff + m * 2048 + k * 1024); } while (0)
; #define PG8_LDB(dst, b, h) do { _Pragma("unroll") for (int n = 0; n < 2; ++n) _Pragma("unroll") for (int k = 0; k < 2; ++k) dst[n][k] = *(const LAS bf16x8*)(lds + PG8_SB(b, h) + boff + n * 2048 + k * 1024); } while (0)
; #define PG8_MMA(ai, bj, At, Bt) do { __builtin_amdgcn_s_setprio(1); _Pragma("unroll") for (int m = 0; m < 4; ++m) _Pragma("unroll") for (int n = 0; n < 2; ++n) _Pragma("unroll") for (int k = 0; k < 2; ++k) \
;         acc[ai][bj][m][n] = __builtin_amdgcn_mfma_f32_16x16x32_bf16(Bt[n][k], At[m][k], acc[ai][bj][m][n], 0, 0, 0); __builtin_amdgcn_s_setprio(0); } while (0)
; #define PG8_WAIT_V(n) asm volatile("s_waitcnt vmcnt(" #n ")" ::: "memory")
; #define PG8_WAIT_L(n) asm volatile("s_waitcnt lgkmcnt(" #n ")" ::: "memory")
; #define PG8_BAR __builtin_amdgcn_s_barrier()
; #define PG8_SCHED __builtin_amdgcn_sched_barrier(0)
; template <class Epi, class Order = StaticOrder, bool HALFN = false>
; __device__ __forceinline__ void gemm_phase(LAS unsigned char* lds, const Gemm g, const Epi& E) {
;     ...
;             PG8_LDB(B0, 1, 0); if constexpr (!HALFN) PG8_LDB(B1, 1, 1); PG8_SCHED; PG8_LDA(At, 1, 0); PG8_STAGE(PG8_SA(0, 1), a2 + hstepA, voffA);
;             PG8_WAIT_V(8); PG8_WAIT_L(0); PG8_BAR; PG8_MMA(0, 0, At, B0); if constexpr (!HALFN) PG8_MMA(0, 1, At, B1); PG8_BAR; PG8_SCHED;
;             PG8_LDA(At, 1, 1); PG8_STAGE(PG8_SB(1, 0), b3, voffB); PG8_STAGE(PG8_SB(1, 1), b3 + hstepB, voffB); PG8_STAGE(PG8_SA(1, 0), a3, voffA);
;             PG8_WAIT_V(8); PG8_WAIT_L(0); PG8_BAR; PG8_MMA(1, 0, At, B0); if constexpr (!HALFN) PG8_MMA(1, 1, At, B1); PG8_BAR; PG8_SCHED;
;         }
;         if (wr == 0) PG8_BAR;
	s_add_i32 s34, 0, 0x18000
	v_add_u32_e32 v78, s34, v81
	ds_read_b128 v[84:87], v78
	ds_read_b128 v[88:91], v78 offset:1024
	ds_read_b128 v[92:95], v78 offset:2048
	ds_read_b128 v[96:99], v78 offset:3072
	s_add_u32 s8, s8, 0x80000
	s_addc_u32 s9, s9, 0
	s_mov_b32 m0, s20
	v_lshl_add_u64 v[140:141], s[8:9], 0, v[66:67]
	ds_read_b128 v[100:103], v83 offset:32768
	ds_read_b128 v[104:107], v83 offset:33792
	ds_read_b128 v[108:111], v83 offset:34816
	ds_read_b128 v[112:115], v83 offset:35840
	ds_read_b128 v[116:119], v83 offset:36864
	ds_read_b128 v[120:123], v83 offset:37888
	ds_read_b128 v[124:127], v83 offset:38912
	ds_read_b128 v[128:131], v83 offset:39936
	global_load_lds_dwordx4 v[140:141], off sc0
	v_lshl_add_u64 v[140:141], s[8:9], 0, v[70:71]
	s_mov_b32 m0, s21
	s_nop 0
	global_load_lds_dwordx4 v[140:141], off sc0
	s_waitcnt vmcnt(6)
	s_waitcnt lgkmcnt(0)
	s_barrier
	s_setprio 1
	s_waitcnt lgkmcnt(0)
	v_mfma_f32_16x16x32_bf16 v[62:65], v[84:87], v[100:103], v[62:65]
	v_mfma_f32_16x16x32_bf16 v[58:61], v[92:95], v[100:103], v[58:61]
	v_mfma_f32_16x16x32_bf16 v[54:57], v[84:87], v[108:111], v[54:57]
	v_mfma_f32_16x16x32_bf16 v[50:53], v[92:95], v[108:111], v[50:53]
	v_mfma_f32_16x16x32_bf16 v[46:49], v[84:87], v[116:119], v[46:49]
	v_mfma_f32_16x16x32_bf16 v[42:45], v[92:95], v[116:119], v[42:45]
	v_mfma_f32_16x16x32_bf16 v[38:41], v[84:87], v[124:127], v[38:41]
	v_mfma_f32_16x16x32_bf16 v[34:37], v[92:95], v[124:127], v[34:37]
	v_mfma_f32_16x16x32_bf16 v[62:65], v[88:91], v[104:107], v[62:65]
	v_mfma_f32_16x16x32_bf16 v[58:61], v[96:99], v[104:107], v[58:61]
	v_mfma_f32_16x16x32_bf16 v[54:57], v[88:91], v[112:115], v[54:57]
	v_mfma_f32_16x16x32_bf16 v[50:53], v[96:99], v[112:115], v[50:53]
	v_mfma_f32_16x16x32_bf16 v[46:49], v[88:91], v[120:123], v[46:49]
	v_mfma_f32_16x16x32_bf16 v[42:45], v[96:99], v[120:123], v[42:45]
	v_mfma_f32_16x16x32_bf16 v[38:41], v[88:91], v[128:131], v[38:41]
	v_mfma_f32_16x16x32_bf16 v[34:37], v[96:99], v[128:131], v[34:37]
	s_setprio 0
	s_barrier
	s_add_i32 s8, s34, s15
	v_lshl_add_u64 v[132:133], v[132:133], 0, s[60:61]
	s_mov_b32 m0, s8
	ds_read_b128 v[100:103], v83 offset:49152
	ds_read_b128 v[104:107], v83 offset:50176
	ds_read_b128 v[108:111], v83 offset:51200
	ds_read_b128 v[112:115], v83 offset:52224
	ds_read_b128 v[116:119], v83 offset:53248
	ds_read_b128 v[120:123], v83 offset:54272
	ds_read_b128 v[124:127], v83 offset:55296
	ds_read_b128 v[128:131], v83 offset:56320
	global_load_lds_dwordx4 v[132:133], off sc0
	s_add_i32 m0, s8, 0x2000
	s_add_u32 s4, s4, 0x80080
	v_lshl_add_u64 v[132:133], v[134:135], 0, s[60:61]
	s_addc_u32 s5, s5, 0
	global_load_lds_dwordx4 v[132:133], off sc0
	v_lshl_add_u64 v[132:133], v[136:137], 0, s[60:61]
	s_mov_b32 m0, s51
	s_nop 0
	global_load_lds_dwordx4 v[132:133], off sc0
	v_lshl_add_u64 v[132:133], v[138:139], 0, s[60:61]
	s_mov_b32 m0, s53
	s_nop 0
	global_load_lds_dwordx4 v[132:133], off sc0
	s_waitcnt vmcnt(6)
	s_waitcnt lgkmcnt(0)
	s_barrier
	s_setprio 1
	s_waitcnt lgkmcnt(0)
	v_mfma_f32_16x16x32_bf16 v[30:33], v[84:87], v[100:103], v[30:33]
	v_mfma_f32_16x16x32_bf16 v[26:29], v[92:95], v[100:103], v[26:29]
	v_mfma_f32_16x16x32_bf16 v[22:25], v[84:87], v[108:111], v[22:25]
	v_mfma_f32_16x16x32_bf16 v[18:21], v[92:95], v[108:111], v[18:21]
	v_mfma_f32_16x16x32_bf16 v[14:17], v[84:87], v[116:119], v[14:17]
	v_mfma_f32_16x16x32_bf16 v[10:13], v[92:95], v[116:119], v[10:13]
	v_mfma_f32_16x16x32_bf16 v[6:9], v[84:87], v[124:127], v[6:9]
	v_mfma_f32_16x16x32_bf16 v[2:5], v[92:95], v[124:127], v[2:5]
	v_mfma_f32_16x16x32_bf16 v[30:33], v[88:91], v[104:107], v[30:33]
	v_mfma_f32_16x16x32_bf16 v[26:29], v[96:99], v[104:107], v[26:29]
	v_mfma_f32_16x16x32_bf16 v[22:25], v[88:91], v[112:115], v[22:25]
	v_mfma_f32_16x16x32_bf16 v[18:21], v[96:99], v[112:115], v[18:21]
	v_mfma_f32_16x16x32_bf16 v[14:17], v[88:91], v[120:123], v[14:17]
	v_mfma_f32_16x16x32_bf16 v[10:13], v[96:99], v[120:123], v[10:13]
	v_mfma_f32_16x16x32_bf16 v[6:9], v[88:91], v[128:131], v[6:9]
	v_mfma_f32_16x16x32_bf16 v[2:5], v[96:99], v[128:131], v[2:5]
	s_setprio 0
	s_barrier
	s_add_i32 s31, s31, 2
	s_add_u32 vcc_lo, vcc_lo, 0x100
	s_addc_u32 vcc_hi, vcc_hi, 0
	s_add_u32 s29, s29, 0x100
	s_addc_u32 s30, s30, 0
	s_cmp_gt_u32 s31, 29
	s_cbranch_scc0 .LBB0_239
	s_and_b64 vcc, exec, s[48:49]
	s_cbranch_vccz .LBB0_242
	s_barrier

; #define PG8_STAGE(bufoff, gbase, voff) do { _Pragma("unroll") for (int _i = 0; _i < 2; ++_i) \
;         __builtin_amdgcn_global_load_lds((const unsigned*)((const char*)(gbase) + (voff)[_i]), (LAS unsigned*)(lds + (bufoff) + ldsw + _i * 8192), 16, 0, 0); } while (0)
; #define PG8_WAIT_V(n) asm volatile("s_waitcnt vmcnt(" #n ")" ::: "memory")
; #define PG8_BAR __builtin_amdgcn_s_barrier()
; template <class Epi, class Order = StaticOrder, bool HALFN = false>
; __device__ __forceinline__ void gemm_phase(LAS unsigned char* lds, const Gemm g, const Epi& E) {
;     ...
;     for (int i = 0; i < 2; ++i) { int R, C; stage_rc(tid * 16 + i * 8192, R, C); const int Rb = (R & ~31) + perm32(R & 31);
;         voffA[i] = (unsigned)(R * g.lda + C) * 2u; voffB[i] = (unsigned)(Rb * g.ldb + C) * 2u; }
;     const size_t kstep = (size_t)(BK * 2);
;     const size_t hstepA = (size_t)HALF * g.lda * 2, hstepB = (size_t)HALF * g.ldb * 2;
;     const size_t tstepA = 2 * hstepA, tstepB = 2 * hstepB;
;     const unsigned ldsw = (unsigned)wid * 1024u;
;     const int aoff = lds_byte(wr * 64 + fr, fq * 8), boff = lds_byte(wc * 32 + fr, fq * 8);
;     ...
;     const char* cA = (const char*)g.A + (size_t)cur.pm * tstepA + (size_t)cur.pn * g.a_pn_off * 2; const char* cB = (const char*)g.Bt + (size_t)cur.pn * tstepB + (HALFN ? (size_t)(cur.half - 1) * hstepB : (size_t)0);
;     PG8_STAGE(PG8_SB(0, 0), cB, voffB); PG8_STAGE(PG8_SB(0, 1), cB + hstepB, voffB); PG8_STAGE(PG8_SA(0, 0), cA, voffA); PG8_STAGE(PG8_SA(0, 1), cA + hstepA, voffA);
;     if (wr == 1) PG8_BAR;
;     PG8_WAIT_V(2); PG8_BAR;
;     PG8_STAGE(PG8_SB(1, 0), cB + kstep, voffB); PG8_STAGE(PG8_SA(1, 0), cA + kstep, voffA); PG8_STAGE(PG8_SB(1, 1), cB + hstepB + kstep, voffB);
;     PG8_WAIT_V(6); PG8_BAR;
.LBB0_471:
	s_andn2_b64 vcc, exec, s[4:5]
	s_mov_b32 s79, s57
	s_cbranch_vccnz .LBB0_496
	s_waitcnt lgkmcnt(0)
	v_bfe_i32 v3, v10, 27, 1
	v_lshlrev_b32_e32 v1, 4, v10
	v_lshrrev_b32_e32 v3, 22, v3
	v_add_u32_e32 v3, v1, v3
	v_and_b32_e32 v3, 0xfffffc00, v3
	v_sub_u32_e32 v3, v1, v3
	v_ashrrev_i32_e32 v2, 31, v10
	v_lshrrev_b32_e32 v4, 4, v3
	v_lshrrev_b32_e32 v2, 26, v2
	v_bitop3_b32 v3, v4, v3, 32 bitop3:0x6c
	v_add_u32_e32 v2, v10, v2
	v_ashrrev_i32_e32 v5, 31, v3
	v_ashrrev_i32_e32 v2, 6, v2
	v_lshrrev_b32_e32 v5, 26, v5
	v_lshlrev_b32_e32 v4, 3, v2
	v_add_u32_e32 v5, v3, v5
	v_and_b32_e32 v4, -16, v4
	v_ashrrev_i32_e32 v6, 6, v5
	v_and_b32_e32 v5, 0xc0, v5
	v_add_u32_e32 v4, v6, v4
	v_sub_u32_e32 v3, v3, v5
	v_lshlrev_b32_e32 v2, 5, v2
	v_ashrrev_i16_sdwa v3, v190, sext(v3) dst_sel:DWORD dst_unused:UNUSED_PAD src0_sel:DWORD src1_sel:BYTE_0
	v_lshlrev_b32_e32 v5, 1, v4
	v_lshrrev_b32_e32 v7, 2, v4
	v_and_b32_e32 v6, 3, v6
	v_and_b32_e32 v2, 32, v2
	v_bfe_i32 v3, v3, 0, 16
	v_and_b32_e32 v5, 24, v5
	v_and_b32_e32 v7, 4, v7
	v_and_or_b32 v6, v4, s59, v6
	v_or3_b32 v5, v6, v7, v5
	v_add_lshl_u32 v2, v2, v3, 1
	v_add_u32_e32 v1, 0x2000, v1
	v_lshl_add_u32 v158, v4, 11, v2
	v_lshl_add_u32 v160, v5, 9, v2
	v_ashrrev_i32_e32 v2, 31, v1
	v_lshrrev_b32_e32 v2, 22, v2
	v_add_u32_e32 v2, v1, v2
	v_ashrrev_i32_e32 v2, 10, v2
	v_mul_i32_i24_e32 v3, 0x400, v2
	v_sub_u32_e32 v1, v1, v3
	v_lshrrev_b32_e32 v3, 4, v1
	v_bitop3_b32 v1, v3, v1, 32 bitop3:0x6c
	v_writelane_b32 v250, s78, 2
	s_lshl_b64 s[4:5], s[78:79], 19
	v_readlane_b32 s6, v251, 11
	v_ashrrev_i32_e32 v4, 31, v1
	s_add_u32 s15, s6, s4
	v_readlane_b32 s4, v251, 12
	v_lshrrev_b32_e32 v4, 26, v4
	s_addc_u32 s89, s4, s5
	v_lshlrev_b32_e32 v3, 3, v2
	v_add_u32_e32 v4, v1, v4
	s_ashr_i32 s5, s8, 6
	s_ashr_i32 s93, s92, 31
	s_ashr_i32 s83, s82, 31
	s_ashr_i32 s4, s8, 8
	v_and_b32_e32 v3, -16, v3
	v_ashrrev_i32_e32 v5, 6, v4
	s_lshl_b32 s96, s5, 10
	s_lshl_b64 s[6:7], s[92:93], 19
	s_lshl_b64 s[10:11], s[82:83], 9
	s_lshl_b64 s[18:19], s[82:83], 17
	v_add_u32_e32 v3, v5, v3
	v_and_b32_e32 v5, 3, v5
	s_add_u32 s94, s15, s18
	v_and_b32_e32 v4, 0xc0, v4
	v_and_or_b32 v5, v3, s59, v5
	s_addc_u32 s95, s89, s19
	s_add_i32 s59, s96, 0
	v_sub_u32_e32 v1, v1, v4
	s_add_i32 m0, s59, 0x10000
	v_lshlrev_b32_e32 v2, 5, v2
	v_ashrrev_i16_sdwa v1, v190, sext(v1) dst_sel:DWORD dst_unused:UNUSED_PAD src0_sel:DWORD src1_sel:BYTE_0
	v_lshlrev_b32_e32 v4, 1, v3
	v_lshrrev_b32_e32 v6, 2, v3
	global_load_lds_dwordx4 v160, s[94:95] sc0
	s_add_i32 m0, s59, 0x12000
	v_readlane_b32 s16, v251, 5
	v_and_b32_e32 v2, 32, v2
	v_bfe_i32 v1, v1, 0, 16
	v_and_b32_e32 v4, 24, v4
	v_and_b32_e32 v6, 4, v6
	v_readlane_b32 s17, v251, 6
	s_add_u32 s9, s16, s6
	v_or3_b32 v4, v5, v6, v4
	v_add_lshl_u32 v1, v2, v1, 1
	s_addc_u32 s19, s17, s7
	v_lshl_add_u32 v170, v4, 9, v1
	s_add_u32 s6, s94, 0x10000
	global_load_lds_dwordx4 v170, s[94:95] sc0
	s_addc_u32 s7, s95, 0
	s_add_i32 m0, s59, 0x14000
	v_writelane_b32 v250, s79, 3
	global_load_lds_dwordx4 v160, s[6:7] sc0
	s_add_i32 m0, s59, 0x16000
	s_add_u32 s54, s9, s10
	s_addc_u32 s55, s19, s11
	s_add_i32 s97, s59, 0x2000
	global_load_lds_dwordx4 v170, s[6:7] sc0
	s_mov_b32 m0, s59
	s_add_u32 s6, s54, 0x40000
	v_lshl_add_u32 v168, v3, 11, v1
	global_load_lds_dwordx4 v158, s[54:55] sc0
	s_mov_b32 m0, s97
	s_addc_u32 s7, s55, 0
	s_add_i32 s78, s59, 0x4000
	global_load_lds_dwordx4 v168, s[54:55] sc0
	s_mov_b32 m0, s78
	s_add_i32 s79, s59, 0x6000
	global_load_lds_dwordx4 v158, s[6:7] sc0
	s_mov_b32 m0, s79
	v_mov_b32_e32 v161, v0
	global_load_lds_dwordx4 v168, s[6:7] sc0
	v_mov_b32_e32 v171, v0
	v_mov_b32_e32 v159, v0
	v_mov_b32_e32 v169, v0
	s_cmp_eq_u32 s4, 1
	v_lshl_add_u64 v[8:9], s[94:95], 0, v[160:161]
	v_lshl_add_u64 v[6:7], s[94:95], 0, v[170:171]
	v_lshl_add_u64 v[2:3], s[54:55], 0, v[158:159]
	s_cselect_b64 s[40:41], -1, 0
	s_cmp_lg_u32 s4, 1
	v_lshl_add_u64 v[4:5], s[54:55], 0, v[168:169]
	s_cbranch_scc1 .LBB0_474
	s_barrier
.LBB0_474:
	v_readlane_b32 s6, v250, 2
	v_readlane_b32 s7, v250, 3
	v_readlane_b32 s16, v252, 4
	s_lshl_b64 s[6:7], s[6:7], 12
	v_readlane_b32 s28, v252, 16
	v_bfe_u32 v180, v10, 4, 2
	v_readlane_b32 s22, v252, 10
	v_readlane_b32 s29, v252, 17
	s_add_u32 s44, s28, s6
	v_and_b32_e32 v1, 15, v10
	v_lshlrev_b32_e32 v11, 4, v180
	v_lshlrev_b32_e32 v10, 2, v10
	s_addc_u32 s45, s29, s7
	s_lshl_b32 s22, s4, 6
	v_lshl_or_b32 v11, v1, 6, v11
	s_lshl_b32 s4, s4, 13
	v_and_b32_e32 v10, 32, v10
	v_readlane_b32 s23, v252, 11
	v_bitop3_b32 v12, v11, s4, v10 bitop3:0xde
	s_lshl_b32 s4, s5, 5
	v_readlane_b32 s24, v252, 12
	v_readlane_b32 s25, v252, 13
	s_and_b32 s23, s4, 0x60
	s_add_i32 m0, s59, 0x18000
	v_lshl_add_u64 v[8:9], v[8:9], 0, s[60:61]
	s_lshl_b32 s4, s23, 7
	s_waitcnt vmcnt(2)
	s_barrier
	global_load_lds_dwordx4 v[8:9], off sc0
	v_lshl_add_u64 v[6:7], v[6:7], 0, s[60:61]
	s_add_i32 m0, s59, 0x1a000
	s_add_i32 s24, s59, 0x8000
	s_add_i32 s25, s59, 0xa000
	v_bitop3_b32 v181, v11, s4, v10 bitop3:0xde
	global_load_lds_dwordx4 v[6:7], off sc0
	v_lshl_add_u64 v[2:3], v[2:3], 0, s[60:61]
	s_mov_b32 m0, s24
	s_add_u32 s4, s94, 0x10080
	global_load_lds_dwordx4 v[2:3], off sc0
	v_lshl_add_u64 v[2:3], v[4:5], 0, s[60:61]
	s_mov_b32 m0, s25
	s_addc_u32 s5, s95, 0
	global_load_lds_dwordx4 v[2:3], off sc0
	s_add_i32 m0, s59, 0x1c000
	v_lshl_add_u64 v[2:3], s[4:5], 0, v[160:161]
	global_load_lds_dwordx4 v[2:3], off sc0
	v_lshl_add_u64 v[2:3], s[4:5], 0, v[170:171]
	s_add_i32 m0, s59, 0x1e000
	v_readlane_b32 s17, v252, 5
	global_load_lds_dwordx4 v[2:3], off sc0
	s_waitcnt vmcnt(6)
	s_cmpk_lt_u32 s8, 0x100
	v_readlane_b32 s16, v251, 5
	s_mov_b32 s56, 0
	s_cselect_b64 s[46:47], -1, 0
	v_add_u32_e32 v182, 0, v12
	v_readlane_b32 s17, v251, 6
	v_readlane_b32 s18, v252, 6
	v_readlane_b32 s19, v252, 7
	v_readlane_b32 s20, v252, 8
	v_readlane_b32 s21, v252, 9
	v_readlane_b32 s26, v252, 14
	v_readlane_b32 s27, v252, 15
	v_readlane_b32 s30, v252, 18
	v_readlane_b32 s31, v252, 19
	s_barrier
	s_branch .LBB0_477

; #define PG8_STAGE(bufoff, gbase, voff) do { _Pragma("unroll") for (int _i = 0; _i < 2; ++_i) \
;         __builtin_amdgcn_global_load_lds((const unsigned*)((const char*)(gbase) + (voff)[_i]), (LAS unsigned*)(lds + (bufoff) + ldsw + _i * 8192), 16, 0, 0); } while (0)
; #define PG8_LDA(dst, b, h) do { _Pragma("unroll") for (int m = 0; m < 4; ++m) _Pragma("unroll") for (int k = 0; k < 2; ++k) dst[m][k] = *(const LAS bf16x8*)(lds + PG8_SA(b, h) + aoff + m * 2048 + k * 1024); } while (0)
; #define PG8_LDB(dst, b, h) do { _Pragma("unroll") for (int n = 0; n < 2; ++n) _Pragma("unroll") for (int k = 0; k < 2; ++k) dst[n][k] = *(const LAS bf16x8*)(lds + PG8_SB(b, h) + boff + n * 2048 + k * 1024); } while (0)
; #define PG8_MMA(ai, bj, At, Bt) do { __builtin_amdgcn_s_setprio(1); _Pragma("unroll") for (int m = 0; m < 4; ++m) _Pragma("unroll") for (int n = 0; n < 2; ++n) _Pragma("unroll") for (int k = 0; k < 2; ++k) \
;         acc[ai][bj][m][n] = __builtin_amdgcn_mfma_f32_16x16x32_bf16(Bt[n][k], At[m][k], acc[ai][bj][m][n], 0, 0, 0); __builtin_amdgcn_s_setprio(0); } while (0)
; #define PG8_WAIT_V(n) asm volatile("s_waitcnt vmcnt(" #n ")" ::: "memory")
; #define PG8_WAIT_L(n) asm volatile("s_waitcnt lgkmcnt(" #n ")" ::: "memory")
; #define PG8_BAR __builtin_amdgcn_s_barrier()
; #define PG8_SCHED __builtin_amdgcn_sched_barrier(0)
; template <class Epi, class Order = StaticOrder, bool HALFN = false>
; __device__ __forceinline__ void gemm_phase(LAS unsigned char* lds, const Gemm g, const Epi& E) {
;     ...
;             const char* a1 = cA + (size_t)(t + 1) * kstep;
;             const char* a2 = last ? nA : cA + (size_t)(t + 2) * kstep; const char* b2 = last ? nB : cB + (size_t)(t + 2) * kstep;
;             const char* a3 = a2 + kstep; const char* b3 = b2 + kstep;
;             PG8_LDB(B0, 0, 0); if constexpr (!HALFN) PG8_LDB(B1, 0, 1); PG8_SCHED; PG8_LDA(At, 0, 0); PG8_STAGE(PG8_SA(1, 1), a1 + hstepA, voffA);
;             PG8_WAIT_V(8); PG8_WAIT_L(0); PG8_BAR; PG8_MMA(0, 0, At, B0); if constexpr (!HALFN) PG8_MMA(0, 1, At, B1); PG8_BAR; PG8_SCHED;
;             PG8_LDA(At, 0, 1); PG8_STAGE(PG8_SB(0, 0), b2, voffB); PG8_STAGE(PG8_SB(0, 1), b2 + hstepB, voffB); PG8_STAGE(PG8_SA(0, 0), a2, voffA);
;             PG8_WAIT_V(8); PG8_WAIT_L(0); PG8_BAR; PG8_MMA(1, 0, At, B0); if constexpr (!HALFN) PG8_MMA(1, 1, At, B1); PG8_BAR; PG8_SCHED;
.LBB0_489:
	s_add_u32 s8, s54, s4
	s_addc_u32 s9, s55, s5
	s_add_u32 s10, s8, 0x100
	s_addc_u32 s11, s9, 0
	s_and_b64 s[6:7], s[42:43], exec
	s_cselect_b32 s7, s26, s11
	s_cselect_b32 s6, s27, s10
	s_add_u32 s4, s94, s4
	s_addc_u32 s5, s95, s5
	s_add_u32 s10, s4, 0x100
	s_addc_u32 s11, s5, 0
	s_add_i32 s83, 0, 0x10000
	s_and_b64 s[4:5], s[42:43], exec
	s_cselect_b32 vcc_hi, s49, s11
	s_cselect_b32 vcc_lo, s51, s10
	s_add_i32 s5, 0, 0x14000
	s_add_u32 s10, s8, 0x40080
	s_addc_u32 s11, s9, 0
	s_add_i32 s37, s83, s96
	s_add_i32 m0, s59, 0xc000
	s_add_i32 s88, s59, 0xe000
	s_add_i32 s34, s37, 0x2000
	s_add_u32 s8, vcc_lo, 0x10000
	v_add_u32_e32 v142, s83, v181
	v_add_u32_e32 v172, s5, v181
	s_addc_u32 s9, vcc_hi, 0
	s_add_i32 s36, s5, s96
	ds_read_b128 v[118:121], v142
	ds_read_b128 v[126:129], v142 offset:1024
	ds_read_b128 v[138:141], v142 offset:2048
	ds_read_b128 v[142:145], v142 offset:3072
	ds_read_b128 v[146:149], v172
	ds_read_b128 v[150:153], v172 offset:1024
	ds_read_b128 v[154:157], v172 offset:2048
	ds_read_b128 v[172:175], v172 offset:3072
	s_add_i32 s35, s36, 0x2000
	s_add_i32 s31, 0, 0x18000
	s_add_i32 s30, 0, 0x1c000
	s_add_u32 s42, s6, 0x40000
	s_addc_u32 s43, s7, 0
	s_add_i32 s29, s31, s96
	s_add_i32 s28, s29, 0x2000
	s_add_u32 s4, vcc_lo, 0x10080
	s_addc_u32 s5, vcc_hi, 0
	s_add_i32 s93, s30, s96
	s_add_i32 s83, s93, 0x2000
	v_lshl_add_u64 v[232:233], s[10:11], 0, v[158:159]
	ds_read_b128 v[176:179], v182
	ds_read_b128 v[184:187], v182 offset:1024
	ds_read_b128 v[208:211], v182 offset:2048
	ds_read_b128 v[212:215], v182 offset:3072
	ds_read_b128 v[216:219], v182 offset:4096
	ds_read_b128 v[220:223], v182 offset:5120
	ds_read_b128 v[224:227], v182 offset:6144
	ds_read_b128 v[228:231], v182 offset:7168
	global_load_lds_dwordx4 v[232:233], off sc0
	v_lshl_add_u64 v[232:233], s[10:11], 0, v[168:169]
	s_mov_b32 m0, s88
	s_nop 0
	global_load_lds_dwordx4 v[232:233], off sc0
	s_waitcnt vmcnt(8)
	s_waitcnt lgkmcnt(0)
	s_barrier
	s_setprio 1
	s_waitcnt lgkmcnt(0)
	v_mfma_f32_16x16x32_bf16 v[134:137], v[118:121], v[176:179], v[134:137]
	v_mfma_f32_16x16x32_bf16 v[130:133], v[138:141], v[176:179], v[130:133]
	v_mfma_f32_16x16x32_bf16 v[110:113], v[118:121], v[208:211], v[110:113]
	v_mfma_f32_16x16x32_bf16 v[106:109], v[138:141], v[208:211], v[106:109]
	v_mfma_f32_16x16x32_bf16 v[94:97], v[118:121], v[216:219], v[94:97]
	v_mfma_f32_16x16x32_bf16 v[90:93], v[138:141], v[216:219], v[90:93]
	v_mfma_f32_16x16x32_bf16 v[78:81], v[118:121], v[224:227], v[78:81]
	v_mfma_f32_16x16x32_bf16 v[74:77], v[138:141], v[224:227], v[74:77]
	v_mfma_f32_16x16x32_bf16 v[134:137], v[126:129], v[184:187], v[134:137]
	v_mfma_f32_16x16x32_bf16 v[130:133], v[142:145], v[184:187], v[130:133]
	v_mfma_f32_16x16x32_bf16 v[110:113], v[126:129], v[212:215], v[110:113]
	v_mfma_f32_16x16x32_bf16 v[106:109], v[142:145], v[212:215], v[106:109]
	v_mfma_f32_16x16x32_bf16 v[94:97], v[126:129], v[220:223], v[94:97]
	v_mfma_f32_16x16x32_bf16 v[90:93], v[142:145], v[220:223], v[90:93]
	v_mfma_f32_16x16x32_bf16 v[78:81], v[126:129], v[228:231], v[78:81]
	v_mfma_f32_16x16x32_bf16 v[74:77], v[142:145], v[228:231], v[74:77]
	s_setprio 0
	s_setprio 1
	v_mfma_f32_16x16x32_bf16 v[122:125], v[146:149], v[176:179], v[122:125]
	v_mfma_f32_16x16x32_bf16 v[114:117], v[154:157], v[176:179], v[114:117]
	v_mfma_f32_16x16x32_bf16 v[102:105], v[146:149], v[208:211], v[102:105]
	v_mfma_f32_16x16x32_bf16 v[98:101], v[154:157], v[208:211], v[98:101]
	v_mfma_f32_16x16x32_bf16 v[86:89], v[146:149], v[216:219], v[86:89]
	v_mfma_f32_16x16x32_bf16 v[82:85], v[154:157], v[216:219], v[82:85]
	v_mfma_f32_16x16x32_bf16 v[70:73], v[146:149], v[224:227], v[70:73]
	v_mfma_f32_16x16x32_bf16 v[66:69], v[154:157], v[224:227], v[66:69]
	v_mfma_f32_16x16x32_bf16 v[122:125], v[150:153], v[184:187], v[122:125]
	v_mfma_f32_16x16x32_bf16 v[114:117], v[172:175], v[184:187], v[114:117]
	v_mfma_f32_16x16x32_bf16 v[102:105], v[150:153], v[212:215], v[102:105]
	v_mfma_f32_16x16x32_bf16 v[98:101], v[172:175], v[212:215], v[98:101]
	v_mfma_f32_16x16x32_bf16 v[86:89], v[150:153], v[220:223], v[86:89]
	v_mfma_f32_16x16x32_bf16 v[82:85], v[172:175], v[220:223], v[82:85]
	v_mfma_f32_16x16x32_bf16 v[70:73], v[150:153], v[228:231], v[70:73]
	v_mfma_f32_16x16x32_bf16 v[66:69], v[172:175], v[228:231], v[66:69]
	s_setprio 0
	s_barrier
	s_mov_b32 m0, s37
	v_lshl_add_u64 v[232:233], vcc, 0, v[160:161]
	ds_read_b128 v[176:179], v182 offset:16384
	ds_read_b128 v[184:187], v182 offset:17408
	ds_read_b128 v[208:211], v182 offset:18432
	ds_read_b128 v[212:215], v182 offset:19456
	ds_read_b128 v[216:219], v182 offset:20480
	ds_read_b128 v[220:223], v182 offset:21504
	ds_read_b128 v[224:227], v182 offset:22528
	ds_read_b128 v[228:231], v182 offset:23552
	global_load_lds_dwordx4 v[232:233], off sc0
	v_lshl_add_u64 v[234:235], vcc, 0, v[170:171]
	s_mov_b32 m0, s34
	v_lshl_add_u64 v[236:237], s[8:9], 0, v[160:161]
	global_load_lds_dwordx4 v[234:235], off sc0
	s_mov_b32 m0, s36
	v_lshl_add_u64 v[238:239], s[6:7], 0, v[168:169]
	global_load_lds_dwordx4 v[236:237], off sc0
	v_lshl_add_u64 v[236:237], s[8:9], 0, v[170:171]
	s_mov_b32 m0, s35
	s_nop 0
	global_load_lds_dwordx4 v[236:237], off sc0
	v_lshl_add_u64 v[236:237], s[6:7], 0, v[158:159]
	s_mov_b32 m0, s59
	s_nop 0
	global_load_lds_dwordx4 v[236:237], off sc0
	s_mov_b32 m0, s97
	s_nop 0
	global_load_lds_dwordx4 v[238:239], off sc0
	s_waitcnt vmcnt(8)
	s_waitcnt lgkmcnt(0)
	s_barrier
; #define PG8_STAGE(bufoff, gbase, voff) do { _Pragma("unroll") for (int _i = 0; _i < 2; ++_i) \
;         __builtin_amdgcn_global_load_lds((const unsigned*)((const char*)(gbase) + (voff)[_i]), (LAS unsigned*)(lds + (bufoff) + ldsw + _i * 8192), 16, 0, 0); } while (0)
; #define PG8_LDA(dst, b, h) do { _Pragma("unroll") for (int m = 0; m < 4; ++m) _Pragma("unroll") for (int k = 0; k < 2; ++k) dst[m][k] = *(const LAS bf16x8*)(lds + PG8_SA(b, h) + aoff + m * 2048 + k * 1024); } while (0)
; #define PG8_LDB(dst, b, h) do { _Pragma("unroll") for (int n = 0; n < 2; ++n) _Pragma("unroll") for (int k = 0; k < 2; ++k) dst[n][k] = *(const LAS bf16x8*)(lds + PG8_SB(b, h) + boff + n * 2048 + k * 1024); } while (0)
; #define PG8_MMA(ai, bj, At, Bt) do { __builtin_amdgcn_s_setprio(1); _Pragma("unroll") for (int m = 0; m < 4; ++m) _Pragma("unroll") for (int n = 0; n < 2; ++n) _Pragma("unroll") for (int k = 0; k < 2; ++k) \
;         acc[ai][bj][m][n] = __builtin_amdgcn_mfma_f32_16x16x32_bf16(Bt[n][k], At[m][k], acc[ai][bj][m][n], 0, 0, 0); __builtin_amdgcn_s_setprio(0); } while (0)
; #define PG8_WAIT_V(n) asm volatile("s_waitcnt vmcnt(" #n ")" ::: "memory")
; #define PG8_WAIT_L(n) asm volatile("s_waitcnt lgkmcnt(" #n ")" ::: "memory")
; #define PG8_BAR __builtin_amdgcn_s_barrier()
; #define PG8_SCHED __builtin_amdgcn_sched_barrier(0)
; template <class Epi, class Order = StaticOrder, bool HALFN = false>
; __device__ __forceinline__ void gemm_phase(LAS unsigned char* lds, const Gemm g, const Epi& E) {
;     ...
;             PG8_WAIT_V(8); PG8_WAIT_L(0); PG8_BAR; PG8_MMA(1, 0, At, B0); if constexpr (!HALFN) PG8_MMA(1, 1, At, B1); PG8_BAR; PG8_SCHED;
;             PG8_LDB(B0, 1, 0); if constexpr (!HALFN) PG8_LDB(B1, 1, 1); PG8_SCHED; PG8_LDA(At, 1, 0); PG8_STAGE(PG8_SA(0, 1), a2 + hstepA, voffA);
;             PG8_WAIT_V(8); PG8_WAIT_L(0); PG8_BAR; PG8_MMA(0, 0, At, B0); if constexpr (!HALFN) PG8_MMA(0, 1, At, B1); PG8_BAR; PG8_SCHED;
	s_setprio 1
	s_waitcnt lgkmcnt(0)
	v_mfma_f32_16x16x32_bf16 v[62:65], v[118:121], v[176:179], v[62:65]
	v_mfma_f32_16x16x32_bf16 v[58:61], v[138:141], v[176:179], v[58:61]
	v_mfma_f32_16x16x32_bf16 v[46:49], v[118:121], v[208:211], v[46:49]
	v_mfma_f32_16x16x32_bf16 v[42:45], v[138:141], v[208:211], v[42:45]
	v_mfma_f32_16x16x32_bf16 v[30:33], v[118:121], v[216:219], v[30:33]
	v_mfma_f32_16x16x32_bf16 v[26:29], v[138:141], v[216:219], v[26:29]
	v_mfma_f32_16x16x32_bf16 v[14:17], v[118:121], v[224:227], v[14:17]
	v_mfma_f32_16x16x32_bf16 v[10:13], v[138:141], v[224:227], v[10:13]
	v_mfma_f32_16x16x32_bf16 v[62:65], v[126:129], v[184:187], v[62:65]
	v_mfma_f32_16x16x32_bf16 v[58:61], v[142:145], v[184:187], v[58:61]
	v_mfma_f32_16x16x32_bf16 v[46:49], v[126:129], v[212:215], v[46:49]
	v_mfma_f32_16x16x32_bf16 v[42:45], v[142:145], v[212:215], v[42:45]
	v_mfma_f32_16x16x32_bf16 v[30:33], v[126:129], v[220:223], v[30:33]
	v_mfma_f32_16x16x32_bf16 v[26:29], v[142:145], v[220:223], v[26:29]
	v_mfma_f32_16x16x32_bf16 v[14:17], v[126:129], v[228:231], v[14:17]
	v_mfma_f32_16x16x32_bf16 v[10:13], v[142:145], v[228:231], v[10:13]
	s_setprio 0
	s_setprio 1
	v_mfma_f32_16x16x32_bf16 v[54:57], v[146:149], v[176:179], v[54:57]
	v_mfma_f32_16x16x32_bf16 v[50:53], v[154:157], v[176:179], v[50:53]
	v_mfma_f32_16x16x32_bf16 v[38:41], v[146:149], v[208:211], v[38:41]
	v_mfma_f32_16x16x32_bf16 v[34:37], v[154:157], v[208:211], v[34:37]
	v_mfma_f32_16x16x32_bf16 v[22:25], v[146:149], v[216:219], v[22:25]
	v_mfma_f32_16x16x32_bf16 v[18:21], v[154:157], v[216:219], v[18:21]
	v_mfma_f32_16x16x32_bf16 v[6:9], v[146:149], v[224:227], v[6:9]
	v_mfma_f32_16x16x32_bf16 v[2:5], v[154:157], v[224:227], v[2:5]
	v_mfma_f32_16x16x32_bf16 v[54:57], v[150:153], v[184:187], v[54:57]
	v_mfma_f32_16x16x32_bf16 v[50:53], v[172:175], v[184:187], v[50:53]
	v_mfma_f32_16x16x32_bf16 v[38:41], v[150:153], v[212:215], v[38:41]
	v_mfma_f32_16x16x32_bf16 v[34:37], v[172:175], v[212:215], v[34:37]
	v_mfma_f32_16x16x32_bf16 v[22:25], v[150:153], v[220:223], v[22:25]
	v_mfma_f32_16x16x32_bf16 v[18:21], v[172:175], v[220:223], v[18:21]
	v_mfma_f32_16x16x32_bf16 v[6:9], v[150:153], v[228:231], v[6:9]
	v_mfma_f32_16x16x32_bf16 v[2:5], v[172:175], v[228:231], v[2:5]
	s_setprio 0
	s_barrier
	v_add_u32_e32 v142, s31, v181
	v_add_u32_e32 v172, s30, v181
	ds_read_b128 v[118:121], v142
	ds_read_b128 v[126:129], v142 offset:1024
	ds_read_b128 v[138:141], v142 offset:2048
	ds_read_b128 v[142:145], v142 offset:3072
	ds_read_b128 v[146:149], v172
	ds_read_b128 v[150:153], v172 offset:1024
	ds_read_b128 v[154:157], v172 offset:2048
	ds_read_b128 v[172:175], v172 offset:3072
	s_mov_b32 m0, s78
	v_lshl_add_u64 v[240:241], s[42:43], 0, v[158:159]
	ds_read_b128 v[176:179], v182 offset:32768
	ds_read_b128 v[184:187], v182 offset:33792
	ds_read_b128 v[208:211], v182 offset:34816
	ds_read_b128 v[212:215], v182 offset:35840
	ds_read_b128 v[216:219], v182 offset:36864
	ds_read_b128 v[220:223], v182 offset:37888
	ds_read_b128 v[224:227], v182 offset:38912
	ds_read_b128 v[228:231], v182 offset:39936
	global_load_lds_dwordx4 v[240:241], off sc0
	v_lshl_add_u64 v[240:241], s[42:43], 0, v[168:169]
	s_mov_b32 m0, s79
	s_nop 0
	global_load_lds_dwordx4 v[240:241], off sc0
	s_waitcnt vmcnt(8)
	s_waitcnt lgkmcnt(0)
	s_barrier
	s_setprio 1
	s_waitcnt lgkmcnt(0)
	v_mfma_f32_16x16x32_bf16 v[134:137], v[118:121], v[176:179], v[134:137]
	v_mfma_f32_16x16x32_bf16 v[130:133], v[138:141], v[176:179], v[130:133]
	v_mfma_f32_16x16x32_bf16 v[110:113], v[118:121], v[208:211], v[110:113]
	v_mfma_f32_16x16x32_bf16 v[106:109], v[138:141], v[208:211], v[106:109]
	v_mfma_f32_16x16x32_bf16 v[94:97], v[118:121], v[216:219], v[94:97]
	v_mfma_f32_16x16x32_bf16 v[90:93], v[138:141], v[216:219], v[90:93]
	v_mfma_f32_16x16x32_bf16 v[78:81], v[118:121], v[224:227], v[78:81]
	v_mfma_f32_16x16x32_bf16 v[74:77], v[138:141], v[224:227], v[74:77]
	v_mfma_f32_16x16x32_bf16 v[134:137], v[126:129], v[184:187], v[134:137]
	v_mfma_f32_16x16x32_bf16 v[130:133], v[142:145], v[184:187], v[130:133]
	v_mfma_f32_16x16x32_bf16 v[110:113], v[126:129], v[212:215], v[110:113]
	v_mfma_f32_16x16x32_bf16 v[106:109], v[142:145], v[212:215], v[106:109]
	v_mfma_f32_16x16x32_bf16 v[94:97], v[126:129], v[220:223], v[94:97]
	v_mfma_f32_16x16x32_bf16 v[90:93], v[142:145], v[220:223], v[90:93]
	v_mfma_f32_16x16x32_bf16 v[78:81], v[126:129], v[228:231], v[78:81]
	v_mfma_f32_16x16x32_bf16 v[74:77], v[142:145], v[228:231], v[74:77]
	s_setprio 0
	s_setprio 1
	v_mfma_f32_16x16x32_bf16 v[122:125], v[146:149], v[176:179], v[122:125]
	v_mfma_f32_16x16x32_bf16 v[114:117], v[154:157], v[176:179], v[114:117]
	v_mfma_f32_16x16x32_bf16 v[102:105], v[146:149], v[208:211], v[102:105]
	v_mfma_f32_16x16x32_bf16 v[98:101], v[154:157], v[208:211], v[98:101]
	v_mfma_f32_16x16x32_bf16 v[86:89], v[146:149], v[216:219], v[86:89]
	v_mfma_f32_16x16x32_bf16 v[82:85], v[154:157], v[216:219], v[82:85]
	v_mfma_f32_16x16x32_bf16 v[70:73], v[146:149], v[224:227], v[70:73]
	v_mfma_f32_16x16x32_bf16 v[66:69], v[154:157], v[224:227], v[66:69]
	v_mfma_f32_16x16x32_bf16 v[122:125], v[150:153], v[184:187], v[122:125]
	v_mfma_f32_16x16x32_bf16 v[114:117], v[172:175], v[184:187], v[114:117]
	v_mfma_f32_16x16x32_bf16 v[102:105], v[150:153], v[212:215], v[102:105]
	v_mfma_f32_16x16x32_bf16 v[98:101], v[172:175], v[212:215], v[98:101]
	v_mfma_f32_16x16x32_bf16 v[86:89], v[150:153], v[220:223], v[86:89]
	v_mfma_f32_16x16x32_bf16 v[82:85], v[172:175], v[220:223], v[82:85]
	v_mfma_f32_16x16x32_bf16 v[70:73], v[150:153], v[228:231], v[70:73]
	v_mfma_f32_16x16x32_bf16 v[66:69], v[172:175], v[228:231], v[66:69]
	s_setprio 0
	s_barrier
; #define PG8_STAGE(bufoff, gbase, voff) do { _Pragma("unroll") for (int _i = 0; _i < 2; ++_i) \
;         __builtin_amdgcn_global_load_lds((const unsigned*)((const char*)(gbase) + (voff)[_i]), (LAS unsigned*)(lds + (bufoff) + ldsw + _i * 8192), 16, 0, 0); } while (0)
; #define PG8_LDA(dst, b, h) do { _Pragma("unroll") for (int m = 0; m < 4; ++m) _Pragma("unroll") for (int k = 0; k < 2; ++k) dst[m][k] = *(const LAS bf16x8*)(lds + PG8_SA(b, h) + aoff + m * 2048 + k * 1024); } while (0)
; #define PG8_MMA(ai, bj, At, Bt) do { __builtin_amdgcn_s_setprio(1); _Pragma("unroll") for (int m = 0; m < 4; ++m) _Pragma("unroll") for (int n = 0; n < 2; ++n) _Pragma("unroll") for (int k = 0; k < 2; ++k) \
;         acc[ai][bj][m][n] = __builtin_amdgcn_mfma_f32_16x16x32_bf16(Bt[n][k], At[m][k], acc[ai][bj][m][n], 0, 0, 0); __builtin_amdgcn_s_setprio(0); } while (0)
; #define PG8_WAIT_V(n) asm volatile("s_waitcnt vmcnt(" #n ")" ::: "memory")
; #define PG8_WAIT_L(n) asm volatile("s_waitcnt lgkmcnt(" #n ")" ::: "memory")
; #define PG8_BAR __builtin_amdgcn_s_barrier()
; #define PG8_SCHED __builtin_amdgcn_sched_barrier(0)
; template <class Epi, class Order = StaticOrder, bool HALFN = false>
; __device__ __forceinline__ void gemm_phase(LAS unsigned char* lds, const Gemm g, const Epi& E) {
;     ...
;             PG8_LDA(At, 1, 1); PG8_STAGE(PG8_SB(1, 0), b3, voffB); PG8_STAGE(PG8_SB(1, 1), b3 + hstepB, voffB); PG8_STAGE(PG8_SA(1, 0), a3, voffA);
;             PG8_WAIT_V(8); PG8_WAIT_L(0); PG8_BAR; PG8_MMA(1, 0, At, B0); if constexpr (!HALFN) PG8_MMA(1, 1, At, B1); PG8_BAR; PG8_SCHED;
;         }
;         if (wr == 0) PG8_BAR;
	s_mov_b32 m0, s29
	v_lshl_add_u64 v[232:233], v[232:233], 0, s[60:61]
	ds_read_b128 v[176:179], v182 offset:49152
	ds_read_b128 v[184:187], v182 offset:50176
	ds_read_b128 v[208:211], v182 offset:51200
	ds_read_b128 v[212:215], v182 offset:52224
	ds_read_b128 v[216:219], v182 offset:53248
	ds_read_b128 v[220:223], v182 offset:54272
	ds_read_b128 v[224:227], v182 offset:55296
	ds_read_b128 v[228:231], v182 offset:56320
	global_load_lds_dwordx4 v[232:233], off sc0
	v_lshl_add_u64 v[232:233], v[234:235], 0, s[60:61]
	s_mov_b32 m0, s28
	s_nop 0
	global_load_lds_dwordx4 v[232:233], off sc0
	v_lshl_add_u64 v[232:233], s[4:5], 0, v[160:161]
	s_mov_b32 m0, s93
	s_nop 0
	global_load_lds_dwordx4 v[232:233], off sc0
	v_lshl_add_u64 v[232:233], s[4:5], 0, v[170:171]
	s_mov_b32 m0, s83
	s_nop 0
	global_load_lds_dwordx4 v[232:233], off sc0
	v_lshl_add_u64 v[232:233], v[236:237], 0, s[60:61]
	s_mov_b32 m0, s24
	s_nop 0
	global_load_lds_dwordx4 v[232:233], off sc0
	v_lshl_add_u64 v[232:233], v[238:239], 0, s[60:61]
	s_mov_b32 m0, s25
	s_nop 0
	global_load_lds_dwordx4 v[232:233], off sc0
	s_waitcnt vmcnt(8)
	s_waitcnt lgkmcnt(0)
	s_barrier
	s_setprio 1
	s_waitcnt lgkmcnt(0)
	v_mfma_f32_16x16x32_bf16 v[62:65], v[118:121], v[176:179], v[62:65]
	v_mfma_f32_16x16x32_bf16 v[58:61], v[138:141], v[176:179], v[58:61]
	v_mfma_f32_16x16x32_bf16 v[46:49], v[118:121], v[208:211], v[46:49]
	v_mfma_f32_16x16x32_bf16 v[42:45], v[138:141], v[208:211], v[42:45]
	v_mfma_f32_16x16x32_bf16 v[30:33], v[118:121], v[216:219], v[30:33]
	v_mfma_f32_16x16x32_bf16 v[26:29], v[138:141], v[216:219], v[26:29]
	v_mfma_f32_16x16x32_bf16 v[14:17], v[118:121], v[224:227], v[14:17]
	v_mfma_f32_16x16x32_bf16 v[10:13], v[138:141], v[224:227], v[10:13]
	v_mfma_f32_16x16x32_bf16 v[62:65], v[126:129], v[184:187], v[62:65]
	v_mfma_f32_16x16x32_bf16 v[58:61], v[142:145], v[184:187], v[58:61]
	v_mfma_f32_16x16x32_bf16 v[46:49], v[126:129], v[212:215], v[46:49]
	v_mfma_f32_16x16x32_bf16 v[42:45], v[142:145], v[212:215], v[42:45]
	v_mfma_f32_16x16x32_bf16 v[30:33], v[126:129], v[220:223], v[30:33]
	v_mfma_f32_16x16x32_bf16 v[26:29], v[142:145], v[220:223], v[26:29]
	v_mfma_f32_16x16x32_bf16 v[14:17], v[126:129], v[228:231], v[14:17]
	v_mfma_f32_16x16x32_bf16 v[10:13], v[142:145], v[228:231], v[10:13]
	s_setprio 0
	s_setprio 1
	v_mfma_f32_16x16x32_bf16 v[54:57], v[146:149], v[176:179], v[54:57]
	v_mfma_f32_16x16x32_bf16 v[50:53], v[154:157], v[176:179], v[50:53]
	v_mfma_f32_16x16x32_bf16 v[38:41], v[146:149], v[208:211], v[38:41]
	v_mfma_f32_16x16x32_bf16 v[34:37], v[154:157], v[208:211], v[34:37]
	v_mfma_f32_16x16x32_bf16 v[22:25], v[146:149], v[216:219], v[22:25]
	v_mfma_f32_16x16x32_bf16 v[18:21], v[154:157], v[216:219], v[18:21]
	v_mfma_f32_16x16x32_bf16 v[6:9], v[146:149], v[224:227], v[6:9]
	v_mfma_f32_16x16x32_bf16 v[2:5], v[154:157], v[224:227], v[2:5]
	v_mfma_f32_16x16x32_bf16 v[54:57], v[150:153], v[184:187], v[54:57]
	v_mfma_f32_16x16x32_bf16 v[50:53], v[172:175], v[184:187], v[50:53]
	v_mfma_f32_16x16x32_bf16 v[38:41], v[150:153], v[212:215], v[38:41]
	v_mfma_f32_16x16x32_bf16 v[34:37], v[172:175], v[212:215], v[34:37]
	v_mfma_f32_16x16x32_bf16 v[22:25], v[150:153], v[220:223], v[22:25]
	v_mfma_f32_16x16x32_bf16 v[18:21], v[172:175], v[220:223], v[18:21]
	v_mfma_f32_16x16x32_bf16 v[6:9], v[150:153], v[228:231], v[6:9]
	v_mfma_f32_16x16x32_bf16 v[2:5], v[172:175], v[228:231], v[2:5]
	s_setprio 0
	s_barrier
	s_andn2_b64 vcc, exec, s[62:63]
	s_mov_b64 s[42:43], -1
	s_mov_b64 s[62:63], 0
	s_mov_b64 s[4:5], 0x100
	s_cbranch_vccz .LBB0_489
	s_and_b64 vcc, exec, s[46:47]
	s_cbranch_vccz .LBB0_492
	s_barrier

; #define PG8_STAGE(bufoff, gbase, voff) do { _Pragma("unroll") for (int _i = 0; _i < 2; ++_i) \
;         __builtin_amdgcn_global_load_lds((const unsigned*)((const char*)(gbase) + (voff)[_i]), (LAS unsigned*)(lds + (bufoff) + ldsw + _i * 8192), 16, 0, 0); } while (0)
; #define PG8_WAIT_V(n) asm volatile("s_waitcnt vmcnt(" #n ")" ::: "memory")
; #define PG8_BAR __builtin_amdgcn_s_barrier()
; template <class Epi, class Order = StaticOrder, bool HALFN = false>
; __device__ __forceinline__ void gemm_phase(LAS unsigned char* lds, const Gemm g, const Epi& E) {
;     ...
;     const int wid = __builtin_amdgcn_readfirstlane(tid >> 6), lane = tid & 63, wr = wid >> 2, wc = wid & 3, fr = lane & 15, fq = lane >> 4;
;     const int K = g.K, nt = K / BK;
;     Order S; S.init(g.nM, g.nN, (int)gridDim.x, (int)blockIdx.x); S.lx = g.lx; S.lr = g.lr;
;     unsigned voffA[2], voffB[2];
; #pragma unroll
;     for (int i = 0; i < 2; ++i) { int R, C; stage_rc(tid * 16 + i * 8192, R, C); const int Rb = (R & ~31) + perm32(R & 31);
;         voffA[i] = (unsigned)(R * g.lda + C) * 2u; voffB[i] = (unsigned)(Rb * g.ldb + C) * 2u; }
;     const size_t kstep = (size_t)(BK * 2);
;     const size_t hstepA = (size_t)HALF * g.lda * 2, hstepB = (size_t)HALF * g.ldb * 2;
;     const size_t tstepA = 2 * hstepA, tstepB = 2 * hstepB;
;     const unsigned ldsw = (unsigned)wid * 1024u;
;     const int aoff = lds_byte(wr * 64 + fr, fq * 8), boff = lds_byte(wc * 32 + fr, fq * 8);
;     ...
;     const char* cA = (const char*)g.A + (size_t)cur.pm * tstepA + (size_t)cur.pn * g.a_pn_off * 2; const char* cB = (const char*)g.Bt + (size_t)cur.pn * tstepB + (HALFN ? (size_t)(cur.half - 1) * hstepB : (size_t)0);
;     PG8_STAGE(PG8_SB(0, 0), cB, voffB); PG8_STAGE(PG8_SB(0, 1), cB + hstepB, voffB); PG8_STAGE(PG8_SA(0, 0), cA, voffA); PG8_STAGE(PG8_SA(0, 1), cA + hstepA, voffA);
;     if (wr == 1) PG8_BAR;
;     PG8_WAIT_V(2); PG8_BAR;
;     PG8_STAGE(PG8_SB(1, 0), cB + kstep, voffB); PG8_STAGE(PG8_SA(1, 0), cA + kstep, voffA); PG8_STAGE(PG8_SB(1, 1), cB + hstepB + kstep, voffB);
;     PG8_WAIT_V(6); PG8_BAR;
.LBB0_501:
	s_andn2_b64 vcc, exec, s[4:5]
	s_cbranch_vccnz .LBB0_528
	s_waitcnt lgkmcnt(0)
	v_bfe_i32 v3, v10, 27, 1
	v_lshlrev_b32_e32 v1, 4, v10
	v_lshrrev_b32_e32 v3, 22, v3
	v_add_u32_e32 v3, v1, v3
	v_and_b32_e32 v3, 0xfffffc00, v3
	v_sub_u32_e32 v3, v1, v3
	v_ashrrev_i32_e32 v2, 31, v10
	v_lshrrev_b32_e32 v4, 4, v3
	v_lshrrev_b32_e32 v2, 26, v2
	v_bitop3_b32 v3, v4, v3, 32 bitop3:0x6c
	v_add_u32_e32 v2, v10, v2
	v_ashrrev_i32_e32 v5, 31, v3
	v_ashrrev_i32_e32 v2, 6, v2
	v_lshrrev_b32_e32 v5, 26, v5
	v_lshlrev_b32_e32 v4, 3, v2
	v_add_u32_e32 v5, v3, v5
	v_and_b32_e32 v4, -16, v4
	v_ashrrev_i32_e32 v6, 6, v5
	v_and_b32_e32 v5, 0xc0, v5
	v_add_u32_e32 v4, v6, v4
	v_sub_u32_e32 v3, v3, v5
	v_lshlrev_b32_e32 v2, 5, v2
	v_ashrrev_i16_sdwa v3, v190, sext(v3) dst_sel:DWORD dst_unused:UNUSED_PAD src0_sel:DWORD src1_sel:BYTE_0
	v_lshlrev_b32_e32 v5, 1, v4
	v_lshrrev_b32_e32 v7, 2, v4
	v_and_b32_e32 v6, 3, v6
	v_and_b32_e32 v2, 32, v2
	v_bfe_i32 v3, v3, 0, 16
	v_and_b32_e32 v5, 24, v5
	v_and_b32_e32 v7, 4, v7
	v_and_or_b32 v6, v4, s59, v6
	v_or3_b32 v5, v6, v7, v5
	v_add_lshl_u32 v2, v2, v3, 1
	v_add_u32_e32 v1, 0x2000, v1
	v_lshl_add_u32 v130, v4, 9, v2
	v_lshl_add_u32 v132, v5, 9, v2
	v_ashrrev_i32_e32 v2, 31, v1
	v_lshrrev_b32_e32 v2, 22, v2
	v_add_u32_e32 v2, v1, v2
	v_ashrrev_i32_e32 v2, 10, v2
	v_mul_i32_i24_e32 v3, 0x400, v2
	v_sub_u32_e32 v1, v1, v3
	s_lshl_b64 s[4:5], s[78:79], 22
	v_readlane_b32 s6, v251, 17
	v_lshrrev_b32_e32 v3, 4, v1
	s_add_u32 s15, s6, s4
	v_readlane_b32 s4, v251, 18
	v_bitop3_b32 v1, v3, v1, 32 bitop3:0x6c
	s_addc_u32 s16, s4, s5
	s_lshl_b64 s[4:5], s[78:79], 20
	v_readlane_b32 s6, v251, 19
	v_ashrrev_i32_e32 v4, 31, v1
	s_add_u32 s17, s6, s4
	v_readlane_b32 s4, v251, 20
	v_lshrrev_b32_e32 v4, 26, v4
	s_addc_u32 s18, s4, s5
	v_lshlrev_b32_e32 v3, 3, v2
	v_add_u32_e32 v4, v1, v4
	s_ashr_i32 s5, s8, 6
	s_mov_b32 s47, s57
	s_ashr_i32 s4, s8, 8
	v_and_b32_e32 v3, -16, v3
	v_ashrrev_i32_e32 v5, 6, v4
	v_and_b32_e32 v4, 0xc0, v4
	s_lshl_b32 s19, s5, 10
	s_lshl_b64 s[6:7], s[56:57], 17
	s_lshl_b64 s[10:11], s[46:47], 17
	v_add_u32_e32 v3, v5, v3
	v_sub_u32_e32 v1, v1, v4
	v_and_b32_e32 v5, 3, v5
	s_add_u32 s54, s17, s10
	v_lshlrev_b32_e32 v2, 5, v2
	v_ashrrev_i16_sdwa v1, v190, sext(v1) dst_sel:DWORD dst_unused:UNUSED_PAD src0_sel:DWORD src1_sel:BYTE_0
	v_lshlrev_b32_e32 v4, 1, v3
	v_lshrrev_b32_e32 v6, 2, v3
	v_and_or_b32 v5, v3, s59, v5
	s_addc_u32 s55, s18, s11
	s_add_i32 s59, s19, 0
	v_and_b32_e32 v2, 32, v2
	v_bfe_i32 v1, v1, 0, 16
	v_and_b32_e32 v4, 24, v4
	v_and_b32_e32 v6, 4, v6
	s_add_i32 m0, s59, 0x10000
	v_or3_b32 v4, v5, v6, v4
	v_add_lshl_u32 v1, v2, v1, 1
	global_load_lds_dwordx4 v132, s[54:55] sc0
	s_add_i32 m0, s59, 0x12000
	v_lshl_add_u32 v136, v4, 9, v1
	s_add_u32 s10, s54, 0x10000
	global_load_lds_dwordx4 v136, s[54:55] sc0
	s_addc_u32 s11, s55, 0
	s_add_i32 m0, s59, 0x14000
	v_lshl_add_u32 v134, v3, 9, v1
	global_load_lds_dwordx4 v132, s[10:11] sc0
	s_add_i32 m0, s59, 0x16000
	s_add_u32 s74, s15, s6
	s_addc_u32 s75, s16, s7
	s_add_i32 s21, s59, 0x2000
	global_load_lds_dwordx4 v136, s[10:11] sc0
	s_mov_b32 m0, s59
	s_add_u32 s6, s74, 0x10000
	global_load_lds_dwordx4 v130, s[74:75] sc0
	s_mov_b32 m0, s21
	s_addc_u32 s7, s75, 0
	s_add_i32 s22, s59, 0x4000
	global_load_lds_dwordx4 v134, s[74:75] sc0
	s_mov_b32 m0, s22
	s_add_i32 s23, s59, 0x6000
	global_load_lds_dwordx4 v130, s[6:7] sc0
	s_mov_b32 m0, s23
	v_mov_b32_e32 v133, v0
	global_load_lds_dwordx4 v134, s[6:7] sc0
	v_mov_b32_e32 v137, v0
	v_mov_b32_e32 v131, v0
	v_mov_b32_e32 v135, v0
	s_cmp_eq_u32 s4, 1
	v_lshl_add_u64 v[8:9], s[54:55], 0, v[132:133]
	v_lshl_add_u64 v[6:7], s[54:55], 0, v[136:137]
	v_lshl_add_u64 v[2:3], s[74:75], 0, v[130:131]
	s_cselect_b64 s[40:41], -1, 0
	s_cmp_lg_u32 s4, 1
	v_lshl_add_u64 v[4:5], s[74:75], 0, v[134:135]
	s_cbranch_scc1 .LBB0_504
	s_barrier
.LBB0_504:
	s_lshl_b64 s[6:7], s[78:79], 25
	v_readlane_b32 s9, v251, 21
	v_bfe_u32 v138, v10, 4, 2
	s_add_u32 s44, s9, s6
	v_readlane_b32 s6, v251, 22
	v_and_b32_e32 v1, 15, v10
	v_lshlrev_b32_e32 v11, 4, v138
	v_lshlrev_b32_e32 v10, 2, v10
	s_addc_u32 s45, s6, s7
	s_lshl_b32 s24, s4, 6
	v_lshl_or_b32 v11, v1, 6, v11
	s_lshl_b32 s4, s4, 13
	v_and_b32_e32 v10, 32, v10
	v_bitop3_b32 v12, v11, s4, v10 bitop3:0xde
	s_lshl_b32 s4, s5, 5
	s_and_b32 s25, s4, 0x60
	s_add_i32 m0, s59, 0x18000
	v_lshl_add_u64 v[8:9], v[8:9], 0, s[60:61]
	s_lshl_b32 s4, s25, 7
	s_waitcnt vmcnt(2)
	s_barrier
	global_load_lds_dwordx4 v[8:9], off sc0
	v_lshl_add_u64 v[6:7], v[6:7], 0, s[60:61]
	s_add_i32 m0, s59, 0x1a000
	s_add_i32 s47, s59, 0x8000
	s_add_i32 s89, s59, 0xa000
	v_bitop3_b32 v139, v11, s4, v10 bitop3:0xde
	global_load_lds_dwordx4 v[6:7], off sc0
	v_lshl_add_u64 v[2:3], v[2:3], 0, s[60:61]
	s_mov_b32 m0, s47
	s_add_u32 s4, s54, 0x10080
	global_load_lds_dwordx4 v[2:3], off sc0
	v_lshl_add_u64 v[2:3], v[4:5], 0, s[60:61]
	s_mov_b32 m0, s89
	s_addc_u32 s5, s55, 0
	global_load_lds_dwordx4 v[2:3], off sc0
	s_add_i32 m0, s59, 0x1c000
	v_lshl_add_u64 v[2:3], s[4:5], 0, v[132:133]
	global_load_lds_dwordx4 v[2:3], off sc0
	v_lshl_add_u64 v[2:3], s[4:5], 0, v[136:137]
	s_add_i32 m0, s59, 0x1e000
	s_cmpk_lt_u32 s8, 0x100
	global_load_lds_dwordx4 v[2:3], off sc0
	s_waitcnt vmcnt(6)
	s_mov_b32 s26, 0
	s_cselect_b64 s[48:49], -1, 0
	v_add_u32_e32 v140, 0, v12
	s_barrier
	s_branch .LBB0_507

; #define PG8_STAGE(bufoff, gbase, voff) do { _Pragma("unroll") for (int _i = 0; _i < 2; ++_i) \
;         __builtin_amdgcn_global_load_lds((const unsigned*)((const char*)(gbase) + (voff)[_i]), (LAS unsigned*)(lds + (bufoff) + ldsw + _i * 8192), 16, 0, 0); } while (0)
; #define PG8_LDA(dst, b, h) do { _Pragma("unroll") for (int m = 0; m < 4; ++m) _Pragma("unroll") for (int k = 0; k < 2; ++k) dst[m][k] = *(const LAS bf16x8*)(lds + PG8_SA(b, h) + aoff + m * 2048 + k * 1024); } while (0)
; #define PG8_LDB(dst, b, h) do { _Pragma("unroll") for (int n = 0; n < 2; ++n) _Pragma("unroll") for (int k = 0; k < 2; ++k) dst[n][k] = *(const LAS bf16x8*)(lds + PG8_SB(b, h) + boff + n * 2048 + k * 1024); } while (0)
; #define PG8_MMA(ai, bj, At, Bt) do { __builtin_amdgcn_s_setprio(1); _Pragma("unroll") for (int m = 0; m < 4; ++m) _Pragma("unroll") for (int n = 0; n < 2; ++n) _Pragma("unroll") for (int k = 0; k < 2; ++k) \
;         acc[ai][bj][m][n] = __builtin_amdgcn_mfma_f32_16x16x32_bf16(Bt[n][k], At[m][k], acc[ai][bj][m][n], 0, 0, 0); __builtin_amdgcn_s_setprio(0); } while (0)
; #define PG8_WAIT_V(n) asm volatile("s_waitcnt vmcnt(" #n ")" ::: "memory")
; #define PG8_WAIT_L(n) asm volatile("s_waitcnt lgkmcnt(" #n ")" ::: "memory")
; #define PG8_BAR __builtin_amdgcn_s_barrier()
; #define PG8_SCHED __builtin_amdgcn_sched_barrier(0)
; template <class Epi, class Order = StaticOrder, bool HALFN = false>
; __device__ __forceinline__ void gemm_phase(LAS unsigned char* lds, const Gemm g, const Epi& E) {
;     ...
;             const char* a1 = cA + (size_t)(t + 1) * kstep;
;             const char* a2 = last ? nA : cA + (size_t)(t + 2) * kstep; const char* b2 = last ? nB : cB + (size_t)(t + 2) * kstep;
;             const char* a3 = a2 + kstep; const char* b3 = b2 + kstep;
;             PG8_LDB(B0, 0, 0); if constexpr (!HALFN) PG8_LDB(B1, 0, 1); PG8_SCHED; PG8_LDA(At, 0, 0); PG8_STAGE(PG8_SA(1, 1), a1 + hstepA, voffA);
;             PG8_WAIT_V(8); PG8_WAIT_L(0); PG8_BAR; PG8_MMA(0, 0, At, B0); if constexpr (!HALFN) PG8_MMA(0, 1, At, B1); PG8_BAR; PG8_SCHED;
;             PG8_LDA(At, 0, 1); PG8_STAGE(PG8_SB(0, 0), b2, voffB); PG8_STAGE(PG8_SB(0, 1), b2 + hstepB, voffB); PG8_STAGE(PG8_SA(0, 0), a2, voffA);
;             PG8_WAIT_V(8); PG8_WAIT_L(0); PG8_BAR; PG8_MMA(1, 0, At, B0); if constexpr (!HALFN) PG8_MMA(1, 1, At, B1); PG8_BAR; PG8_SCHED;
.LBB0_521:
	s_add_u32 s8, s74, s4
	s_addc_u32 s9, s75, s5
	s_add_u32 s10, s8, 0x100
	s_addc_u32 s11, s9, 0
	s_and_b64 s[6:7], s[42:43], exec
	s_cselect_b32 s7, s27, s11
	s_cselect_b32 s6, s53, s10
	s_add_u32 s4, s54, s4
	s_addc_u32 s5, s55, s5
	s_add_u32 s10, s4, 0x100
	s_addc_u32 s11, s5, 0
	s_add_i32 s88, 0, 0x10000
	s_and_b64 s[4:5], s[42:43], exec
	s_cselect_b32 s95, s51, s11
	s_cselect_b32 s94, s28, s10
	s_add_i32 s5, 0, 0x14000
	s_add_u32 s10, s8, 0x10080
	s_addc_u32 s11, s9, 0
	s_add_i32 vcc_lo, s88, s19
	s_add_i32 m0, s59, 0xc000
	s_add_i32 s20, s59, 0xe000
	s_add_i32 s35, vcc_lo, 0x2000
	v_add_u32_e32 v141, s88, v139
	s_add_u32 s8, s94, 0x10000
	ds_read_b128 v[142:145], v141
	ds_read_b128 v[146:149], v141 offset:1024
	ds_read_b128 v[150:153], v141 offset:2048
	ds_read_b128 v[154:157], v141 offset:3072
	v_add_u32_e32 v141, s5, v139
	s_addc_u32 s9, s95, 0
	s_add_i32 s37, s5, s19
	ds_read_b128 v[158:161], v141
	ds_read_b128 v[168:171], v141 offset:1024
	ds_read_b128 v[172:175], v141 offset:2048
	ds_read_b128 v[176:179], v141 offset:3072
	s_add_i32 s36, s37, 0x2000
	s_add_i32 s34, 0, 0x18000
	s_add_i32 s31, 0, 0x1c000
	s_add_u32 s42, s6, 0x10000
	s_addc_u32 s43, s7, 0
	s_add_i32 s30, s34, s19
	s_add_i32 s29, s30, 0x2000
	s_add_u32 s4, s94, 0x10080
	s_addc_u32 s5, s95, 0
	s_add_i32 vcc_hi, s31, s19
	s_add_i32 s88, vcc_hi, 0x2000
	v_lshl_add_u64 v[232:233], s[10:11], 0, v[130:131]
	ds_read_b128 v[180:183], v140
	ds_read_b128 v[184:187], v140 offset:1024
	ds_read_b128 v[208:211], v140 offset:2048
	ds_read_b128 v[212:215], v140 offset:3072
	ds_read_b128 v[216:219], v140 offset:4096
	ds_read_b128 v[220:223], v140 offset:5120
	ds_read_b128 v[224:227], v140 offset:6144
	ds_read_b128 v[228:231], v140 offset:7168
	global_load_lds_dwordx4 v[232:233], off sc0
	v_lshl_add_u64 v[232:233], s[10:11], 0, v[134:135]
	s_mov_b32 m0, s20
	s_nop 0
	global_load_lds_dwordx4 v[232:233], off sc0
	s_waitcnt vmcnt(8)
	s_waitcnt lgkmcnt(0)
	s_barrier
	s_setprio 1
	s_waitcnt lgkmcnt(0)
	v_mfma_f32_16x16x32_bf16 v[126:129], v[142:145], v[180:183], v[126:129]
	v_mfma_f32_16x16x32_bf16 v[122:125], v[150:153], v[180:183], v[122:125]
	v_mfma_f32_16x16x32_bf16 v[118:121], v[142:145], v[208:211], v[118:121]
	v_mfma_f32_16x16x32_bf16 v[114:117], v[150:153], v[208:211], v[114:117]
	v_mfma_f32_16x16x32_bf16 v[102:105], v[142:145], v[216:219], v[102:105]
	v_mfma_f32_16x16x32_bf16 v[98:101], v[150:153], v[216:219], v[98:101]
	v_mfma_f32_16x16x32_bf16 v[86:89], v[142:145], v[224:227], v[86:89]
	v_mfma_f32_16x16x32_bf16 v[82:85], v[150:153], v[224:227], v[82:85]
	v_mfma_f32_16x16x32_bf16 v[126:129], v[146:149], v[184:187], v[126:129]
	v_mfma_f32_16x16x32_bf16 v[122:125], v[154:157], v[184:187], v[122:125]
	v_mfma_f32_16x16x32_bf16 v[118:121], v[146:149], v[212:215], v[118:121]
	v_mfma_f32_16x16x32_bf16 v[114:117], v[154:157], v[212:215], v[114:117]
	v_mfma_f32_16x16x32_bf16 v[102:105], v[146:149], v[220:223], v[102:105]
	v_mfma_f32_16x16x32_bf16 v[98:101], v[154:157], v[220:223], v[98:101]
	v_mfma_f32_16x16x32_bf16 v[86:89], v[146:149], v[228:231], v[86:89]
	v_mfma_f32_16x16x32_bf16 v[82:85], v[154:157], v[228:231], v[82:85]
	s_setprio 0
	s_setprio 1
	v_mfma_f32_16x16x32_bf16 v[110:113], v[158:161], v[180:183], v[110:113]
	v_mfma_f32_16x16x32_bf16 v[106:109], v[172:175], v[180:183], v[106:109]
	v_mfma_f32_16x16x32_bf16 v[94:97], v[158:161], v[208:211], v[94:97]
	v_mfma_f32_16x16x32_bf16 v[90:93], v[172:175], v[208:211], v[90:93]
	v_mfma_f32_16x16x32_bf16 v[78:81], v[158:161], v[216:219], v[78:81]
	v_mfma_f32_16x16x32_bf16 v[74:77], v[172:175], v[216:219], v[74:77]
	v_mfma_f32_16x16x32_bf16 v[70:73], v[158:161], v[224:227], v[70:73]
	v_mfma_f32_16x16x32_bf16 v[66:69], v[172:175], v[224:227], v[66:69]
	v_mfma_f32_16x16x32_bf16 v[110:113], v[168:171], v[184:187], v[110:113]
	v_mfma_f32_16x16x32_bf16 v[106:109], v[176:179], v[184:187], v[106:109]
	v_mfma_f32_16x16x32_bf16 v[94:97], v[168:171], v[212:215], v[94:97]
	v_mfma_f32_16x16x32_bf16 v[90:93], v[176:179], v[212:215], v[90:93]
	v_mfma_f32_16x16x32_bf16 v[78:81], v[168:171], v[220:223], v[78:81]
	v_mfma_f32_16x16x32_bf16 v[74:77], v[176:179], v[220:223], v[74:77]
	v_mfma_f32_16x16x32_bf16 v[70:73], v[168:171], v[228:231], v[70:73]
	v_mfma_f32_16x16x32_bf16 v[66:69], v[176:179], v[228:231], v[66:69]
	s_setprio 0
	s_barrier
	s_mov_b32 m0, vcc_lo
	v_lshl_add_u64 v[232:233], s[94:95], 0, v[132:133]
	ds_read_b128 v[180:183], v140 offset:16384
	ds_read_b128 v[184:187], v140 offset:17408
	ds_read_b128 v[208:211], v140 offset:18432
	ds_read_b128 v[212:215], v140 offset:19456
	ds_read_b128 v[216:219], v140 offset:20480
	ds_read_b128 v[220:223], v140 offset:21504
	ds_read_b128 v[224:227], v140 offset:22528
	ds_read_b128 v[228:231], v140 offset:23552
	global_load_lds_dwordx4 v[232:233], off sc0
	v_lshl_add_u64 v[234:235], s[94:95], 0, v[136:137]
	s_mov_b32 m0, s35
	v_lshl_add_u64 v[236:237], s[8:9], 0, v[132:133]
	global_load_lds_dwordx4 v[234:235], off sc0
	s_mov_b32 m0, s37
	v_lshl_add_u64 v[238:239], s[6:7], 0, v[134:135]
	global_load_lds_dwordx4 v[236:237], off sc0
	v_lshl_add_u64 v[236:237], s[8:9], 0, v[136:137]
	s_mov_b32 m0, s36
	s_nop 0
	global_load_lds_dwordx4 v[236:237], off sc0
	v_lshl_add_u64 v[236:237], s[6:7], 0, v[130:131]
	s_mov_b32 m0, s59
	s_nop 0
	global_load_lds_dwordx4 v[236:237], off sc0
	s_mov_b32 m0, s21
	s_nop 0
	global_load_lds_dwordx4 v[238:239], off sc0
	s_waitcnt vmcnt(8)
	s_waitcnt lgkmcnt(0)
	s_barrier
; #define PG8_STAGE(bufoff, gbase, voff) do { _Pragma("unroll") for (int _i = 0; _i < 2; ++_i) \
;         __builtin_amdgcn_global_load_lds((const unsigned*)((const char*)(gbase) + (voff)[_i]), (LAS unsigned*)(lds + (bufoff) + ldsw + _i * 8192), 16, 0, 0); } while (0)
; #define PG8_LDA(dst, b, h) do { _Pragma("unroll") for (int m = 0; m < 4; ++m) _Pragma("unroll") for (int k = 0; k < 2; ++k) dst[m][k] = *(const LAS bf16x8*)(lds + PG8_SA(b, h) + aoff + m * 2048 + k * 1024); } while (0)
; #define PG8_LDB(dst, b, h) do { _Pragma("unroll") for (int n = 0; n < 2; ++n) _Pragma("unroll") for (int k = 0; k < 2; ++k) dst[n][k] = *(const LAS bf16x8*)(lds + PG8_SB(b, h) + boff + n * 2048 + k * 1024); } while (0)
; #define PG8_MMA(ai, bj, At, Bt) do { __builtin_amdgcn_s_setprio(1); _Pragma("unroll") for (int m = 0; m < 4; ++m) _Pragma("unroll") for (int n = 0; n < 2; ++n) _Pragma("unroll") for (int k = 0; k < 2; ++k) \
;         acc[ai][bj][m][n] = __builtin_amdgcn_mfma_f32_16x16x32_bf16(Bt[n][k], At[m][k], acc[ai][bj][m][n], 0, 0, 0); __builtin_amdgcn_s_setprio(0); } while (0)
; #define PG8_WAIT_V(n) asm volatile("s_waitcnt vmcnt(" #n ")" ::: "memory")
; #define PG8_WAIT_L(n) asm volatile("s_waitcnt lgkmcnt(" #n ")" ::: "memory")
; #define PG8_BAR __builtin_amdgcn_s_barrier()
; #define PG8_SCHED __builtin_amdgcn_sched_barrier(0)
; template <class Epi, class Order = StaticOrder, bool HALFN = false>
; __device__ __forceinline__ void gemm_phase(LAS unsigned char* lds, const Gemm g, const Epi& E) {
;     ...
;             PG8_WAIT_V(8); PG8_WAIT_L(0); PG8_BAR; PG8_MMA(1, 0, At, B0); if constexpr (!HALFN) PG8_MMA(1, 1, At, B1); PG8_BAR; PG8_SCHED;
;             PG8_LDB(B0, 1, 0); if constexpr (!HALFN) PG8_LDB(B1, 1, 1); PG8_SCHED; PG8_LDA(At, 1, 0); PG8_STAGE(PG8_SA(0, 1), a2 + hstepA, voffA);
;             PG8_WAIT_V(8); PG8_WAIT_L(0); PG8_BAR; PG8_MMA(0, 0, At, B0); if constexpr (!HALFN) PG8_MMA(0, 1, At, B1); PG8_BAR; PG8_SCHED;
	s_setprio 1
	s_waitcnt lgkmcnt(0)
	v_mfma_f32_16x16x32_bf16 v[62:65], v[142:145], v[180:183], v[62:65]
	v_mfma_f32_16x16x32_bf16 v[58:61], v[150:153], v[180:183], v[58:61]
	v_mfma_f32_16x16x32_bf16 v[54:57], v[142:145], v[208:211], v[54:57]
	v_mfma_f32_16x16x32_bf16 v[50:53], v[150:153], v[208:211], v[50:53]
	v_mfma_f32_16x16x32_bf16 v[38:41], v[142:145], v[216:219], v[38:41]
	v_mfma_f32_16x16x32_bf16 v[34:37], v[150:153], v[216:219], v[34:37]
	v_mfma_f32_16x16x32_bf16 v[22:25], v[142:145], v[224:227], v[22:25]
	v_mfma_f32_16x16x32_bf16 v[18:21], v[150:153], v[224:227], v[18:21]
	v_mfma_f32_16x16x32_bf16 v[62:65], v[146:149], v[184:187], v[62:65]
	v_mfma_f32_16x16x32_bf16 v[58:61], v[154:157], v[184:187], v[58:61]
	v_mfma_f32_16x16x32_bf16 v[54:57], v[146:149], v[212:215], v[54:57]
	v_mfma_f32_16x16x32_bf16 v[50:53], v[154:157], v[212:215], v[50:53]
	v_mfma_f32_16x16x32_bf16 v[38:41], v[146:149], v[220:223], v[38:41]
	v_mfma_f32_16x16x32_bf16 v[34:37], v[154:157], v[220:223], v[34:37]
	v_mfma_f32_16x16x32_bf16 v[22:25], v[146:149], v[228:231], v[22:25]
	v_mfma_f32_16x16x32_bf16 v[18:21], v[154:157], v[228:231], v[18:21]
	s_setprio 0
	s_setprio 1
	v_mfma_f32_16x16x32_bf16 v[46:49], v[158:161], v[180:183], v[46:49]
	v_mfma_f32_16x16x32_bf16 v[42:45], v[172:175], v[180:183], v[42:45]
	v_mfma_f32_16x16x32_bf16 v[30:33], v[158:161], v[208:211], v[30:33]
	v_mfma_f32_16x16x32_bf16 v[26:29], v[172:175], v[208:211], v[26:29]
	v_mfma_f32_16x16x32_bf16 v[14:17], v[158:161], v[216:219], v[14:17]
	v_mfma_f32_16x16x32_bf16 v[10:13], v[172:175], v[216:219], v[10:13]
	v_mfma_f32_16x16x32_bf16 v[6:9], v[158:161], v[224:227], v[6:9]
	v_mfma_f32_16x16x32_bf16 v[2:5], v[172:175], v[224:227], v[2:5]
	v_mfma_f32_16x16x32_bf16 v[46:49], v[168:171], v[184:187], v[46:49]
	v_mfma_f32_16x16x32_bf16 v[42:45], v[176:179], v[184:187], v[42:45]
	v_mfma_f32_16x16x32_bf16 v[30:33], v[168:171], v[212:215], v[30:33]
	v_mfma_f32_16x16x32_bf16 v[26:29], v[176:179], v[212:215], v[26:29]
	v_mfma_f32_16x16x32_bf16 v[14:17], v[168:171], v[220:223], v[14:17]
	v_mfma_f32_16x16x32_bf16 v[10:13], v[176:179], v[220:223], v[10:13]
	v_mfma_f32_16x16x32_bf16 v[6:9], v[168:171], v[228:231], v[6:9]
	v_mfma_f32_16x16x32_bf16 v[2:5], v[176:179], v[228:231], v[2:5]
	s_setprio 0
	s_barrier
	v_add_u32_e32 v141, s34, v139
	ds_read_b128 v[142:145], v141
	ds_read_b128 v[146:149], v141 offset:1024
	ds_read_b128 v[150:153], v141 offset:2048
	ds_read_b128 v[154:157], v141 offset:3072
	v_add_u32_e32 v141, s31, v139
	ds_read_b128 v[158:161], v141
	ds_read_b128 v[168:171], v141 offset:1024
	ds_read_b128 v[172:175], v141 offset:2048
	ds_read_b128 v[176:179], v141 offset:3072
	s_mov_b32 m0, s22
	v_lshl_add_u64 v[240:241], s[42:43], 0, v[130:131]
	ds_read_b128 v[180:183], v140 offset:32768
	ds_read_b128 v[184:187], v140 offset:33792
	ds_read_b128 v[208:211], v140 offset:34816
	ds_read_b128 v[212:215], v140 offset:35840
	ds_read_b128 v[216:219], v140 offset:36864
	ds_read_b128 v[220:223], v140 offset:37888
	ds_read_b128 v[224:227], v140 offset:38912
	ds_read_b128 v[228:231], v140 offset:39936
	global_load_lds_dwordx4 v[240:241], off sc0
	v_lshl_add_u64 v[240:241], s[42:43], 0, v[134:135]
	s_mov_b32 m0, s23
	s_nop 0
	global_load_lds_dwordx4 v[240:241], off sc0
	s_waitcnt vmcnt(8)
	s_waitcnt lgkmcnt(0)
	s_barrier
	s_setprio 1
	s_waitcnt lgkmcnt(0)
	v_mfma_f32_16x16x32_bf16 v[126:129], v[142:145], v[180:183], v[126:129]
	v_mfma_f32_16x16x32_bf16 v[122:125], v[150:153], v[180:183], v[122:125]
	v_mfma_f32_16x16x32_bf16 v[118:121], v[142:145], v[208:211], v[118:121]
	v_mfma_f32_16x16x32_bf16 v[114:117], v[150:153], v[208:211], v[114:117]
	v_mfma_f32_16x16x32_bf16 v[102:105], v[142:145], v[216:219], v[102:105]
	v_mfma_f32_16x16x32_bf16 v[98:101], v[150:153], v[216:219], v[98:101]
	v_mfma_f32_16x16x32_bf16 v[86:89], v[142:145], v[224:227], v[86:89]
	v_mfma_f32_16x16x32_bf16 v[82:85], v[150:153], v[224:227], v[82:85]
	v_mfma_f32_16x16x32_bf16 v[126:129], v[146:149], v[184:187], v[126:129]
	v_mfma_f32_16x16x32_bf16 v[122:125], v[154:157], v[184:187], v[122:125]
	v_mfma_f32_16x16x32_bf16 v[118:121], v[146:149], v[212:215], v[118:121]
	v_mfma_f32_16x16x32_bf16 v[114:117], v[154:157], v[212:215], v[114:117]
	v_mfma_f32_16x16x32_bf16 v[102:105], v[146:149], v[220:223], v[102:105]
	v_mfma_f32_16x16x32_bf16 v[98:101], v[154:157], v[220:223], v[98:101]
	v_mfma_f32_16x16x32_bf16 v[86:89], v[146:149], v[228:231], v[86:89]
	v_mfma_f32_16x16x32_bf16 v[82:85], v[154:157], v[228:231], v[82:85]
	s_setprio 0
	s_setprio 1
	v_mfma_f32_16x16x32_bf16 v[110:113], v[158:161], v[180:183], v[110:113]
	v_mfma_f32_16x16x32_bf16 v[106:109], v[172:175], v[180:183], v[106:109]
	v_mfma_f32_16x16x32_bf16 v[94:97], v[158:161], v[208:211], v[94:97]
	v_mfma_f32_16x16x32_bf16 v[90:93], v[172:175], v[208:211], v[90:93]
	v_mfma_f32_16x16x32_bf16 v[78:81], v[158:161], v[216:219], v[78:81]
	v_mfma_f32_16x16x32_bf16 v[74:77], v[172:175], v[216:219], v[74:77]
	v_mfma_f32_16x16x32_bf16 v[70:73], v[158:161], v[224:227], v[70:73]
	v_mfma_f32_16x16x32_bf16 v[66:69], v[172:175], v[224:227], v[66:69]
	v_mfma_f32_16x16x32_bf16 v[110:113], v[168:171], v[184:187], v[110:113]
	v_mfma_f32_16x16x32_bf16 v[106:109], v[176:179], v[184:187], v[106:109]
	v_mfma_f32_16x16x32_bf16 v[94:97], v[168:171], v[212:215], v[94:97]
	v_mfma_f32_16x16x32_bf16 v[90:93], v[176:179], v[212:215], v[90:93]
	v_mfma_f32_16x16x32_bf16 v[78:81], v[168:171], v[220:223], v[78:81]
	v_mfma_f32_16x16x32_bf16 v[74:77], v[176:179], v[220:223], v[74:77]
	v_mfma_f32_16x16x32_bf16 v[70:73], v[168:171], v[228:231], v[70:73]
	v_mfma_f32_16x16x32_bf16 v[66:69], v[176:179], v[228:231], v[66:69]
	s_setprio 0
	s_barrier
; #define PG8_STAGE(bufoff, gbase, voff) do { _Pragma("unroll") for (int _i = 0; _i < 2; ++_i) \
;         __builtin_amdgcn_global_load_lds((const unsigned*)((const char*)(gbase) + (voff)[_i]), (LAS unsigned*)(lds + (bufoff) + ldsw + _i * 8192), 16, 0, 0); } while (0)
; #define PG8_LDA(dst, b, h) do { _Pragma("unroll") for (int m = 0; m < 4; ++m) _Pragma("unroll") for (int k = 0; k < 2; ++k) dst[m][k] = *(const LAS bf16x8*)(lds + PG8_SA(b, h) + aoff + m * 2048 + k * 1024); } while (0)
; #define PG8_MMA(ai, bj, At, Bt) do { __builtin_amdgcn_s_setprio(1); _Pragma("unroll") for (int m = 0; m < 4; ++m) _Pragma("unroll") for (int n = 0; n < 2; ++n) _Pragma("unroll") for (int k = 0; k < 2; ++k) \
;         acc[ai][bj][m][n] = __builtin_amdgcn_mfma_f32_16x16x32_bf16(Bt[n][k], At[m][k], acc[ai][bj][m][n], 0, 0, 0); __builtin_amdgcn_s_setprio(0); } while (0)
; #define PG8_WAIT_V(n) asm volatile("s_waitcnt vmcnt(" #n ")" ::: "memory")
; #define PG8_WAIT_L(n) asm volatile("s_waitcnt lgkmcnt(" #n ")" ::: "memory")
; #define PG8_BAR __builtin_amdgcn_s_barrier()
; #define PG8_SCHED __builtin_amdgcn_sched_barrier(0)
; template <class Epi, class Order = StaticOrder, bool HALFN = false>
; __device__ __forceinline__ void gemm_phase(LAS unsigned char* lds, const Gemm g, const Epi& E) {
;     ...
;             PG8_LDA(At, 1, 1); PG8_STAGE(PG8_SB(1, 0), b3, voffB); PG8_STAGE(PG8_SB(1, 1), b3 + hstepB, voffB); PG8_STAGE(PG8_SA(1, 0), a3, voffA);
;             PG8_WAIT_V(8); PG8_WAIT_L(0); PG8_BAR; PG8_MMA(1, 0, At, B0); if constexpr (!HALFN) PG8_MMA(1, 1, At, B1); PG8_BAR; PG8_SCHED;
;         }
;         if (wr == 0) PG8_BAR;
	s_mov_b32 m0, s30
	v_lshl_add_u64 v[232:233], v[232:233], 0, s[60:61]
	ds_read_b128 v[180:183], v140 offset:49152
	ds_read_b128 v[184:187], v140 offset:50176
	ds_read_b128 v[208:211], v140 offset:51200
	ds_read_b128 v[212:215], v140 offset:52224
	ds_read_b128 v[216:219], v140 offset:53248
	ds_read_b128 v[220:223], v140 offset:54272
	ds_read_b128 v[224:227], v140 offset:55296
	ds_read_b128 v[228:231], v140 offset:56320
	global_load_lds_dwordx4 v[232:233], off sc0
	v_lshl_add_u64 v[232:233], v[234:235], 0, s[60:61]
	s_mov_b32 m0, s29
	s_nop 0
	global_load_lds_dwordx4 v[232:233], off sc0
	v_lshl_add_u64 v[232:233], s[4:5], 0, v[132:133]
	s_mov_b32 m0, vcc_hi
	s_nop 0
	global_load_lds_dwordx4 v[232:233], off sc0
	v_lshl_add_u64 v[232:233], s[4:5], 0, v[136:137]
	s_mov_b32 m0, s88
	s_nop 0
	global_load_lds_dwordx4 v[232:233], off sc0
	v_lshl_add_u64 v[232:233], v[236:237], 0, s[60:61]
	s_mov_b32 m0, s47
	s_nop 0
	global_load_lds_dwordx4 v[232:233], off sc0
	v_lshl_add_u64 v[232:233], v[238:239], 0, s[60:61]
	s_mov_b32 m0, s89
	s_nop 0
	global_load_lds_dwordx4 v[232:233], off sc0
	s_waitcnt vmcnt(8)
	s_waitcnt lgkmcnt(0)
	s_barrier
	s_setprio 1
	s_waitcnt lgkmcnt(0)
	v_mfma_f32_16x16x32_bf16 v[62:65], v[142:145], v[180:183], v[62:65]
	v_mfma_f32_16x16x32_bf16 v[58:61], v[150:153], v[180:183], v[58:61]
	v_mfma_f32_16x16x32_bf16 v[54:57], v[142:145], v[208:211], v[54:57]
	v_mfma_f32_16x16x32_bf16 v[50:53], v[150:153], v[208:211], v[50:53]
	v_mfma_f32_16x16x32_bf16 v[38:41], v[142:145], v[216:219], v[38:41]
	v_mfma_f32_16x16x32_bf16 v[34:37], v[150:153], v[216:219], v[34:37]
	v_mfma_f32_16x16x32_bf16 v[22:25], v[142:145], v[224:227], v[22:25]
	v_mfma_f32_16x16x32_bf16 v[18:21], v[150:153], v[224:227], v[18:21]
	v_mfma_f32_16x16x32_bf16 v[62:65], v[146:149], v[184:187], v[62:65]
	v_mfma_f32_16x16x32_bf16 v[58:61], v[154:157], v[184:187], v[58:61]
	v_mfma_f32_16x16x32_bf16 v[54:57], v[146:149], v[212:215], v[54:57]
	v_mfma_f32_16x16x32_bf16 v[50:53], v[154:157], v[212:215], v[50:53]
	v_mfma_f32_16x16x32_bf16 v[38:41], v[146:149], v[220:223], v[38:41]
	v_mfma_f32_16x16x32_bf16 v[34:37], v[154:157], v[220:223], v[34:37]
	v_mfma_f32_16x16x32_bf16 v[22:25], v[146:149], v[228:231], v[22:25]
	v_mfma_f32_16x16x32_bf16 v[18:21], v[154:157], v[228:231], v[18:21]
	s_setprio 0
	s_setprio 1
	v_mfma_f32_16x16x32_bf16 v[46:49], v[158:161], v[180:183], v[46:49]
	v_mfma_f32_16x16x32_bf16 v[42:45], v[172:175], v[180:183], v[42:45]
	v_mfma_f32_16x16x32_bf16 v[30:33], v[158:161], v[208:211], v[30:33]
	v_mfma_f32_16x16x32_bf16 v[26:29], v[172:175], v[208:211], v[26:29]
	v_mfma_f32_16x16x32_bf16 v[14:17], v[158:161], v[216:219], v[14:17]
	v_mfma_f32_16x16x32_bf16 v[10:13], v[172:175], v[216:219], v[10:13]
	v_mfma_f32_16x16x32_bf16 v[6:9], v[158:161], v[224:227], v[6:9]
	v_mfma_f32_16x16x32_bf16 v[2:5], v[172:175], v[224:227], v[2:5]
	v_mfma_f32_16x16x32_bf16 v[46:49], v[168:171], v[184:187], v[46:49]
	v_mfma_f32_16x16x32_bf16 v[42:45], v[176:179], v[184:187], v[42:45]
	v_mfma_f32_16x16x32_bf16 v[30:33], v[168:171], v[212:215], v[30:33]
	v_mfma_f32_16x16x32_bf16 v[26:29], v[176:179], v[212:215], v[26:29]
	v_mfma_f32_16x16x32_bf16 v[14:17], v[168:171], v[220:223], v[14:17]
	v_mfma_f32_16x16x32_bf16 v[10:13], v[176:179], v[220:223], v[10:13]
	v_mfma_f32_16x16x32_bf16 v[6:9], v[168:171], v[228:231], v[6:9]
	v_mfma_f32_16x16x32_bf16 v[2:5], v[176:179], v[228:231], v[2:5]
	s_setprio 0
	s_barrier
	s_andn2_b64 vcc, exec, s[62:63]
	s_mov_b64 s[42:43], -1
	s_mov_b64 s[62:63], 0
	s_mov_b64 s[4:5], 0x100
	s_cbranch_vccz .LBB0_521
	s_and_b64 vcc, exec, s[48:49]
	s_cbranch_vccz .LBB0_524
	s_barrier

; #define PG8_STAGE(bufoff, gbase, voff) do { _Pragma("unroll") for (int _i = 0; _i < 2; ++_i) \
;         __builtin_amdgcn_global_load_lds((const unsigned*)((const char*)(gbase) + (voff)[_i]), (LAS unsigned*)(lds + (bufoff) + ldsw + _i * 8192), 16, 0, 0); } while (0)
; #define PG8_WAIT_V(n) asm volatile("s_waitcnt vmcnt(" #n ")" ::: "memory")
; #define PG8_BAR __builtin_amdgcn_s_barrier()
; template <class Epi, class Order = StaticOrder, bool HALFN = false>
; __device__ __forceinline__ void gemm_phase(LAS unsigned char* lds, const Gemm g, const Epi& E) {
;     ...
;     const int wid = __builtin_amdgcn_readfirstlane(tid >> 6), lane = tid & 63, wr = wid >> 2, wc = wid & 3, fr = lane & 15, fq = lane >> 4;
;     const int K = g.K, nt = K / BK;
;     Order S; S.init(g.nM, g.nN, (int)gridDim.x, (int)blockIdx.x); S.lx = g.lx; S.lr = g.lr;
;     unsigned voffA[2], voffB[2];
; #pragma unroll
;     for (int i = 0; i < 2; ++i) { int R, C; stage_rc(tid * 16 + i * 8192, R, C); const int Rb = (R & ~31) + perm32(R & 31);
;         voffA[i] = (unsigned)(R * g.lda + C) * 2u; voffB[i] = (unsigned)(Rb * g.ldb + C) * 2u; }
;     const size_t kstep = (size_t)(BK * 2);
;     const size_t hstepA = (size_t)HALF * g.lda * 2, hstepB = (size_t)HALF * g.ldb * 2;
;     const size_t tstepA = 2 * hstepA, tstepB = 2 * hstepB;
;     const unsigned ldsw = (unsigned)wid * 1024u;
;     const int aoff = lds_byte(wr * 64 + fr, fq * 8), boff = lds_byte(wc * 32 + fr, fq * 8);
;     ...
;     const char* cA = (const char*)g.A + (size_t)cur.pm * tstepA + (size_t)cur.pn * g.a_pn_off * 2; const char* cB = (const char*)g.Bt + (size_t)cur.pn * tstepB + (HALFN ? (size_t)(cur.half - 1) * hstepB : (size_t)0);
;     PG8_STAGE(PG8_SB(0, 0), cB, voffB); PG8_STAGE(PG8_SB(0, 1), cB + hstepB, voffB); PG8_STAGE(PG8_SA(0, 0), cA, voffA); PG8_STAGE(PG8_SA(0, 1), cA + hstepA, voffA);
;     if (wr == 1) PG8_BAR;
;     PG8_WAIT_V(2); PG8_BAR;
;     PG8_STAGE(PG8_SB(1, 0), cB + kstep, voffB); PG8_STAGE(PG8_SA(1, 0), cA + kstep, voffA); PG8_STAGE(PG8_SB(1, 1), cB + hstepB + kstep, voffB);
;     PG8_WAIT_V(6); PG8_BAR;
.LBB0_592:
	s_andn2_b64 vcc, exec, s[4:5]
	s_cbranch_vccnz .LBB0_627
	s_waitcnt lgkmcnt(0)
	v_bfe_i32 v3, v15, 27, 1
	v_lshlrev_b32_e32 v2, 4, v15
	v_lshrrev_b32_e32 v3, 22, v3
	v_add_u32_e32 v3, v2, v3
	v_and_b32_e32 v3, 0xfffffc00, v3
	v_sub_u32_e32 v3, v2, v3
	v_ashrrev_i32_e32 v1, 31, v15
	v_lshrrev_b32_e32 v4, 4, v3
	v_lshrrev_b32_e32 v1, 26, v1
	v_bitop3_b32 v3, v4, v3, 32 bitop3:0x6c
	v_add_u32_e32 v1, v15, v1
	v_ashrrev_i32_e32 v5, 31, v3
	v_ashrrev_i32_e32 v1, 6, v1
	v_lshrrev_b32_e32 v5, 26, v5
	v_lshlrev_b32_e32 v4, 3, v1
	v_add_u32_e32 v5, v3, v5
	v_and_b32_e32 v4, -16, v4
	v_ashrrev_i32_e32 v11, 6, v5
	v_and_b32_e32 v5, 0xc0, v5
	s_mul_i32 s4, s78, 0xc00000
	v_readlane_b32 s5, v251, 32
	v_add_u32_e32 v4, v11, v4
	v_lshlrev_b32_e32 v6, 5, v1
	v_sub_u32_e32 v3, v3, v5
	s_add_u32 s10, s5, s4
	v_and_b32_e32 v10, 32, v6
	v_ashrrev_i16_sdwa v3, v190, sext(v3) dst_sel:DWORD dst_unused:UNUSED_PAD src0_sel:DWORD src1_sel:BYTE_0
	v_lshlrev_b32_e32 v5, 1, v4
	v_lshrrev_b32_e32 v6, 2, v4
	v_and_b32_e32 v7, 3, v11
	s_mov_b32 s5, 0x3fffe0
	v_bfe_i32 v12, v3, 0, 16
	v_and_b32_e32 v5, 24, v5
	v_and_b32_e32 v6, 4, v6
	v_and_or_b32 v7, v4, s5, v7
	s_movk_i32 s6, 0xc00
	v_add_u32_e32 v3, v10, v12
	v_or3_b32 v5, v7, v6, v5
	v_mul_lo_u32 v4, v4, s6
	v_add_lshl_u32 v132, v3, v4, 1
	v_mul_u32_u24_e32 v4, 0xc00, v5
	v_add_u32_e32 v2, 0x2000, v2
	v_add_lshl_u32 v134, v4, v3, 1
	v_ashrrev_i32_e32 v3, 31, v2
	v_lshrrev_b32_e32 v3, 22, v3
	v_add_u32_e32 v3, v2, v3
	v_ashrrev_i32_e32 v13, 10, v3
	v_mul_i32_i24_e32 v3, 0x400, v13
	v_sub_u32_e32 v2, v2, v3
	v_lshrrev_b32_e32 v3, 4, v2
	v_bitop3_b32 v2, v3, v2, 32 bitop3:0x6c
	v_ashrrev_i32_e32 v4, 31, v2
	v_lshrrev_b32_e32 v4, 26, v4
	v_lshlrev_b32_e32 v3, 3, v13
	v_add_u32_e32 v4, v2, v4
	v_and_b32_e32 v3, -16, v3
	v_ashrrev_i32_e32 v16, 6, v4
	v_readlane_b32 s4, v251, 33
	v_add_u32_e32 v3, v16, v3
	v_and_b32_e32 v6, 3, v16
	s_addc_u32 s11, s4, 0
	v_and_b32_e32 v4, 0xc0, v4
	v_and_or_b32 v6, v3, s5, v6
	s_ashr_i32 s5, s8, 6
	s_ashr_i32 s4, s8, 8
	v_lshlrev_b32_e32 v5, 5, v13
	v_sub_u32_e32 v2, v2, v4
	s_lshl_b32 s15, s5, 10
	s_mul_i32 s7, s26, 0x180000
	v_and_b32_e32 v14, 32, v5
	v_ashrrev_i16_sdwa v2, v190, sext(v2) dst_sel:DWORD dst_unused:UNUSED_PAD src0_sel:DWORD src1_sel:BYTE_0
	v_lshlrev_b32_e32 v4, 1, v3
	v_lshrrev_b32_e32 v5, 2, v3
	v_mul_lo_u32 v3, v3, s6
	s_mul_hi_i32 s6, s26, 0x180000
	s_add_u32 s54, s10, s7
	v_bfe_i32 v17, v2, 0, 16
	v_and_b32_e32 v4, 24, v4
	v_and_b32_e32 v5, 4, v5
	s_addc_u32 s55, s11, s6
	s_add_i32 s16, s15, 0
	v_add_u32_e32 v2, v14, v17
	v_or3_b32 v4, v6, v5, v4
	s_add_i32 m0, s16, 0x10000
	v_add_lshl_u32 v136, v2, v3, 1
	v_mul_u32_u24_e32 v3, 0xc00, v4
	global_load_lds_dwordx4 v134, s[54:55] sc0
	s_add_i32 m0, s16, 0x12000
	v_add_lshl_u32 v138, v3, v2, 1
	s_add_u32 s6, s54, 0xc0000
	global_load_lds_dwordx4 v138, s[54:55] sc0
	s_addc_u32 s7, s55, 0
	s_add_i32 m0, s16, 0x14000
	s_mul_i32 s17, s27, 0x180000
	global_load_lds_dwordx4 v134, s[6:7] sc0
	s_add_i32 m0, s16, 0x16000
	s_mul_hi_i32 s9, s27, 0x180000
	s_add_u32 s52, s70, s17
	s_addc_u32 s53, s71, s9
	s_add_i32 s17, s16, 0x2000
	global_load_lds_dwordx4 v138, s[6:7] sc0
	s_mov_b32 m0, s16
	s_add_u32 s6, s52, 0xc0000
	global_load_lds_dwordx4 v132, s[52:53] sc0
	s_mov_b32 m0, s17
	s_addc_u32 s7, s53, 0
	s_add_i32 s18, s16, 0x4000
	global_load_lds_dwordx4 v136, s[52:53] sc0
	s_mov_b32 m0, s18
	s_add_i32 s19, s16, 0x6000
	global_load_lds_dwordx4 v132, s[6:7] sc0
	s_mov_b32 m0, s19
	v_mov_b32_e32 v135, v0
	global_load_lds_dwordx4 v136, s[6:7] sc0
	v_mov_b32_e32 v139, v0
	v_mov_b32_e32 v133, v0
	v_mov_b32_e32 v137, v0
	s_cmp_eq_u32 s4, 1
	v_lshl_add_u64 v[8:9], s[54:55], 0, v[134:135]
	v_lshl_add_u64 v[6:7], s[54:55], 0, v[138:139]
	v_lshl_add_u64 v[2:3], s[52:53], 0, v[132:133]
	s_cselect_b64 s[44:45], -1, 0
	s_cmp_lg_u32 s4, 1
	v_lshl_add_u64 v[4:5], s[52:53], 0, v[136:137]
	s_cbranch_scc1 .LBB0_595
	s_barrier
.LBB0_595:
	v_bfe_u32 v181, v15, 4, 2
	v_and_b32_e32 v180, 15, v15
	v_lshlrev_b32_e32 v18, 4, v181
	v_lshlrev_b32_e32 v15, 2, v15
	s_lshl_b32 s20, s4, 6
	v_lshl_or_b32 v18, v180, 6, v18
	s_lshl_b32 s4, s4, 13
	v_and_b32_e32 v15, 32, v15
	v_bitop3_b32 v19, v18, s4, v15 bitop3:0xde
	s_lshl_b32 s4, s5, 5
	s_and_b32 s21, s4, 0x60
	s_add_i32 m0, s16, 0x18000
	v_lshl_add_u64 v[8:9], v[8:9], 0, s[60:61]
	s_lshl_b32 s4, s21, 7
	s_waitcnt vmcnt(2)
	s_barrier
	global_load_lds_dwordx4 v[8:9], off sc0
	v_lshl_add_u64 v[6:7], v[6:7], 0, s[60:61]
	s_add_i32 m0, s16, 0x1a000
	s_add_i32 s22, s16, 0x8000
	s_add_i32 s23, s16, 0xa000
	v_bitop3_b32 v182, v18, s4, v15 bitop3:0xde
	global_load_lds_dwordx4 v[6:7], off sc0
	v_lshl_add_u64 v[2:3], v[2:3], 0, s[60:61]
	s_mov_b32 m0, s22
	s_add_u32 s4, s54, 0xc0080
	global_load_lds_dwordx4 v[2:3], off sc0
	v_lshl_add_u64 v[2:3], v[4:5], 0, s[60:61]
	s_mov_b32 m0, s23
	s_addc_u32 s5, s55, 0
	global_load_lds_dwordx4 v[2:3], off sc0
	s_add_i32 m0, s16, 0x1c000
	v_lshl_add_u64 v[2:3], s[4:5], 0, v[134:135]
	global_load_lds_dwordx4 v[2:3], off sc0
	v_lshl_add_u64 v[2:3], s[4:5], 0, v[138:139]
	s_add_i32 m0, s16, 0x1e000
	s_movk_i32 s7, 0xc00
	global_load_lds_dwordx4 v[2:3], off sc0
	v_lshrrev_b32_e32 v1, 1, v1
	v_mul_lo_u32 v2, v11, s7
	s_mov_b32 s6, 0xc000
	v_mad_u64_u32 v[2:3], s[4:5], v1, s6, v[2:3]
	v_or_b32_e32 v1, v2, v10
	v_add_lshl_u32 v140, v1, v12, 1
	v_lshrrev_b32_e32 v1, 1, v13
	v_mul_lo_u32 v2, v16, s7
	s_waitcnt vmcnt(6)
	v_mad_u64_u32 v[2:3], s[4:5], v1, s6, v[2:3]
	s_cmpk_lt_u32 s8, 0x100
	v_or_b32_e32 v1, v2, v14
	s_cselect_b64 s[46:47], -1, 0
	v_mov_b32_e32 v141, v0
	v_add_lshl_u32 v142, v1, v17, 1
	v_mov_b32_e32 v143, v0
	s_mov_b32 s24, 0
	v_add_u32_e32 v183, 0, v19
	s_barrier
	s_branch .LBB0_598

; #define PG8_STAGE(bufoff, gbase, voff) do { _Pragma("unroll") for (int _i = 0; _i < 2; ++_i) \
;         __builtin_amdgcn_global_load_lds((const unsigned*)((const char*)(gbase) + (voff)[_i]), (LAS unsigned*)(lds + (bufoff) + ldsw + _i * 8192), 16, 0, 0); } while (0)
; #define PG8_LDA(dst, b, h) do { _Pragma("unroll") for (int m = 0; m < 4; ++m) _Pragma("unroll") for (int k = 0; k < 2; ++k) dst[m][k] = *(const LAS bf16x8*)(lds + PG8_SA(b, h) + aoff + m * 2048 + k * 1024); } while (0)
; #define PG8_LDB(dst, b, h) do { _Pragma("unroll") for (int n = 0; n < 2; ++n) _Pragma("unroll") for (int k = 0; k < 2; ++k) dst[n][k] = *(const LAS bf16x8*)(lds + PG8_SB(b, h) + boff + n * 2048 + k * 1024); } while (0)
; #define PG8_MMA(ai, bj, At, Bt) do { __builtin_amdgcn_s_setprio(1); _Pragma("unroll") for (int m = 0; m < 4; ++m) _Pragma("unroll") for (int n = 0; n < 2; ++n) _Pragma("unroll") for (int k = 0; k < 2; ++k) \
;         acc[ai][bj][m][n] = __builtin_amdgcn_mfma_f32_16x16x32_bf16(Bt[n][k], At[m][k], acc[ai][bj][m][n], 0, 0, 0); __builtin_amdgcn_s_setprio(0); } while (0)
; #define PG8_WAIT_V(n) asm volatile("s_waitcnt vmcnt(" #n ")" ::: "memory")
; #define PG8_WAIT_L(n) asm volatile("s_waitcnt lgkmcnt(" #n ")" ::: "memory")
; #define PG8_BAR __builtin_amdgcn_s_barrier()
; #define PG8_SCHED __builtin_amdgcn_sched_barrier(0)
; template <class Epi, class Order = StaticOrder, bool HALFN = false>
; __device__ __forceinline__ void gemm_phase(LAS unsigned char* lds, const Gemm g, const Epi& E) {
;     ...
;             const char* a1 = cA + (size_t)(t + 1) * kstep;
;             const char* a2 = last ? nA : cA + (size_t)(t + 2) * kstep; const char* b2 = last ? nB : cB + (size_t)(t + 2) * kstep;
;             const char* a3 = a2 + kstep; const char* b3 = b2 + kstep;
;             PG8_LDB(B0, 0, 0); if constexpr (!HALFN) PG8_LDB(B1, 0, 1); PG8_SCHED; PG8_LDA(At, 0, 0); PG8_STAGE(PG8_SA(1, 1), a1 + hstepA, voffA);
;             PG8_WAIT_V(8); PG8_WAIT_L(0); PG8_BAR; PG8_MMA(0, 0, At, B0); if constexpr (!HALFN) PG8_MMA(0, 1, At, B1); PG8_BAR; PG8_SCHED;
;             PG8_LDA(At, 0, 1); PG8_STAGE(PG8_SB(0, 0), b2, voffB); PG8_STAGE(PG8_SB(0, 1), b2 + hstepB, voffB); PG8_STAGE(PG8_SA(0, 0), a2, voffA);
;             PG8_WAIT_V(8); PG8_WAIT_L(0); PG8_BAR; PG8_MMA(1, 0, At, B0); if constexpr (!HALFN) PG8_MMA(1, 1, At, B1); PG8_BAR; PG8_SCHED;
.Lsm_b:
.LBB0_619:
	s_add_u32 s4, s52, s54
	s_addc_u32 s5, s53, s55
	s_add_u32 s4, s4, 0x100
	s_addc_u32 s5, s5, 0
	s_add_u32 s26, s62, s54
	s_addc_u32 s27, s63, s55
	s_add_i32 s28, 0, 0x10000
	s_cmpk_eq_i32 s54, 0x1700
	s_cselect_b32 s7, s49, s5
	s_cselect_b32 s6, s48, s4
	v_add_u32_e32 v1, s28, v182
	s_cselect_b32 s5, s51, s27
	s_cselect_b32 s4, s50, s26
	s_add_i32 s29, 0, 0x14000
	ds_read_b128 v[148:151], v1
	ds_read_b128 v[152:155], v1 offset:1024
	ds_read_b128 v[156:159], v1 offset:2048
	ds_read_b128 v[168:171], v1 offset:3072
	v_add_u32_e32 v1, s29, v182
	ds_read_b128 v[172:175], v1
	ds_read_b128 v[176:179], v1 offset:1024
	ds_read_b128 v[184:187], v1 offset:2048
	ds_read_b128 v[208:211], v1 offset:3072
	v_lshl_add_u64 v[2:3], v[144:145], 0, s[54:55]
	s_add_i32 m0, s16, 0xc000
	ds_read_b128 v[212:215], v183
	ds_read_b128 v[216:219], v183 offset:1024
	ds_read_b128 v[220:223], v183 offset:2048
	ds_read_b128 v[224:227], v183 offset:3072
	ds_read_b128 v[228:231], v183 offset:4096
	ds_read_b128 v[232:235], v183 offset:5120
	ds_read_b128 v[236:239], v183 offset:6144
	ds_read_b128 v[240:243], v183 offset:7168
	global_load_lds_dwordx4 v[2:3], off sc0
	v_lshl_add_u64 v[2:3], v[146:147], 0, s[54:55]
	s_add_i32 m0, s16, 0xe000
	s_nop 0
	global_load_lds_dwordx4 v[2:3], off sc0
	s_waitcnt vmcnt(8)
	s_waitcnt lgkmcnt(0)
	s_barrier
	s_setprio 1
	s_waitcnt lgkmcnt(0)
	v_mfma_f32_16x16x32_bf16 v[128:131], v[148:151], v[212:215], v[128:131]
	v_mfma_f32_16x16x32_bf16 v[124:127], v[156:159], v[212:215], v[124:127]
	v_mfma_f32_16x16x32_bf16 v[112:115], v[148:151], v[220:223], v[112:115]
	v_mfma_f32_16x16x32_bf16 v[108:111], v[156:159], v[220:223], v[108:111]
	v_mfma_f32_16x16x32_bf16 v[96:99], v[148:151], v[228:231], v[96:99]
	v_mfma_f32_16x16x32_bf16 v[92:95], v[156:159], v[228:231], v[92:95]
	v_mfma_f32_16x16x32_bf16 v[80:83], v[148:151], v[236:239], v[80:83]
	v_mfma_f32_16x16x32_bf16 v[76:79], v[156:159], v[236:239], v[76:79]
	v_mfma_f32_16x16x32_bf16 v[128:131], v[152:155], v[216:219], v[128:131]
	v_mfma_f32_16x16x32_bf16 v[124:127], v[168:171], v[216:219], v[124:127]
	v_mfma_f32_16x16x32_bf16 v[112:115], v[152:155], v[224:227], v[112:115]
	v_mfma_f32_16x16x32_bf16 v[108:111], v[168:171], v[224:227], v[108:111]
	v_mfma_f32_16x16x32_bf16 v[96:99], v[152:155], v[232:235], v[96:99]
	v_mfma_f32_16x16x32_bf16 v[92:95], v[168:171], v[232:235], v[92:95]
	v_mfma_f32_16x16x32_bf16 v[80:83], v[152:155], v[240:243], v[80:83]
	v_mfma_f32_16x16x32_bf16 v[76:79], v[168:171], v[240:243], v[76:79]
	s_setprio 0
	s_setprio 1
	v_mfma_f32_16x16x32_bf16 v[120:123], v[172:175], v[212:215], v[120:123]
	v_mfma_f32_16x16x32_bf16 v[116:119], v[184:187], v[212:215], v[116:119]
	v_mfma_f32_16x16x32_bf16 v[104:107], v[172:175], v[220:223], v[104:107]
	v_mfma_f32_16x16x32_bf16 v[100:103], v[184:187], v[220:223], v[100:103]
	v_mfma_f32_16x16x32_bf16 v[88:91], v[172:175], v[228:231], v[88:91]
	v_mfma_f32_16x16x32_bf16 v[84:87], v[184:187], v[228:231], v[84:87]
	v_mfma_f32_16x16x32_bf16 v[72:75], v[172:175], v[236:239], v[72:75]
	v_mfma_f32_16x16x32_bf16 v[68:71], v[184:187], v[236:239], v[68:71]
	v_mfma_f32_16x16x32_bf16 v[120:123], v[176:179], v[216:219], v[120:123]
	v_mfma_f32_16x16x32_bf16 v[116:119], v[208:211], v[216:219], v[116:119]
	v_mfma_f32_16x16x32_bf16 v[104:107], v[176:179], v[224:227], v[104:107]
	v_mfma_f32_16x16x32_bf16 v[100:103], v[208:211], v[224:227], v[100:103]
	v_mfma_f32_16x16x32_bf16 v[88:91], v[176:179], v[232:235], v[88:91]
	v_mfma_f32_16x16x32_bf16 v[84:87], v[208:211], v[232:235], v[84:87]
	v_mfma_f32_16x16x32_bf16 v[72:75], v[176:179], v[240:243], v[72:75]
	v_mfma_f32_16x16x32_bf16 v[68:71], v[208:211], v[240:243], v[68:71]
	s_setprio 0
	s_barrier
	s_add_i32 s26, s28, s15
	v_lshl_add_u64 v[160:161], s[4:5], 0, v[134:135]
	s_mov_b32 m0, s26
	ds_read_b128 v[212:215], v183 offset:16384
	ds_read_b128 v[216:219], v183 offset:17408
	ds_read_b128 v[220:223], v183 offset:18432
	ds_read_b128 v[224:227], v183 offset:19456
	ds_read_b128 v[228:231], v183 offset:20480
	ds_read_b128 v[232:235], v183 offset:21504
	ds_read_b128 v[236:239], v183 offset:22528
	ds_read_b128 v[240:243], v183 offset:23552
	global_load_lds_dwordx4 v[160:161], off sc0
	s_add_i32 m0, s26, 0x2000
	s_add_u32 s26, s4, 0xc0000
	v_lshl_add_u64 v[244:245], s[4:5], 0, v[138:139]
	s_addc_u32 s27, s5, 0
	s_add_i32 s28, s29, s15
	global_load_lds_dwordx4 v[244:245], off sc0
	v_lshl_add_u64 v[2:3], s[26:27], 0, v[134:135]
	s_mov_b32 m0, s28
	v_lshl_add_u64 v[246:247], s[6:7], 0, v[132:133]
	global_load_lds_dwordx4 v[2:3], off sc0
	v_lshl_add_u64 v[2:3], s[26:27], 0, v[138:139]
	s_add_i32 m0, s28, 0x2000
	v_lshl_add_u64 v[248:249], s[6:7], 0, v[136:137]
	global_load_lds_dwordx4 v[2:3], off sc0
	s_mov_b32 m0, s16
	s_nop 0
	global_load_lds_dwordx4 v[246:247], off sc0
	s_mov_b32 m0, s17
	s_nop 0
	global_load_lds_dwordx4 v[248:249], off sc0
	s_waitcnt vmcnt(8)
	s_waitcnt lgkmcnt(0)
	s_barrier
; #define PG8_STAGE(bufoff, gbase, voff) do { _Pragma("unroll") for (int _i = 0; _i < 2; ++_i) \
;         __builtin_amdgcn_global_load_lds((const unsigned*)((const char*)(gbase) + (voff)[_i]), (LAS unsigned*)(lds + (bufoff) + ldsw + _i * 8192), 16, 0, 0); } while (0)
; #define PG8_LDA(dst, b, h) do { _Pragma("unroll") for (int m = 0; m < 4; ++m) _Pragma("unroll") for (int k = 0; k < 2; ++k) dst[m][k] = *(const LAS bf16x8*)(lds + PG8_SA(b, h) + aoff + m * 2048 + k * 1024); } while (0)
; #define PG8_LDB(dst, b, h) do { _Pragma("unroll") for (int n = 0; n < 2; ++n) _Pragma("unroll") for (int k = 0; k < 2; ++k) dst[n][k] = *(const LAS bf16x8*)(lds + PG8_SB(b, h) + boff + n * 2048 + k * 1024); } while (0)
; #define PG8_MMA(ai, bj, At, Bt) do { __builtin_amdgcn_s_setprio(1); _Pragma("unroll") for (int m = 0; m < 4; ++m) _Pragma("unroll") for (int n = 0; n < 2; ++n) _Pragma("unroll") for (int k = 0; k < 2; ++k) \
;         acc[ai][bj][m][n] = __builtin_amdgcn_mfma_f32_16x16x32_bf16(Bt[n][k], At[m][k], acc[ai][bj][m][n], 0, 0, 0); __builtin_amdgcn_s_setprio(0); } while (0)
; #define PG8_WAIT_V(n) asm volatile("s_waitcnt vmcnt(" #n ")" ::: "memory")
; #define PG8_WAIT_L(n) asm volatile("s_waitcnt lgkmcnt(" #n ")" ::: "memory")
; #define PG8_BAR __builtin_amdgcn_s_barrier()
; #define PG8_SCHED __builtin_amdgcn_sched_barrier(0)
; template <class Epi, class Order = StaticOrder, bool HALFN = false>
; __device__ __forceinline__ void gemm_phase(LAS unsigned char* lds, const Gemm g, const Epi& E) {
;     ...
;             PG8_WAIT_V(8); PG8_WAIT_L(0); PG8_BAR; PG8_MMA(1, 0, At, B0); if constexpr (!HALFN) PG8_MMA(1, 1, At, B1); PG8_BAR; PG8_SCHED;
;             PG8_LDB(B0, 1, 0); if constexpr (!HALFN) PG8_LDB(B1, 1, 1); PG8_SCHED; PG8_LDA(At, 1, 0); PG8_STAGE(PG8_SA(0, 1), a2 + hstepA, voffA);
;             PG8_WAIT_V(8); PG8_WAIT_L(0); PG8_BAR; PG8_MMA(0, 0, At, B0); if constexpr (!HALFN) PG8_MMA(0, 1, At, B1); PG8_BAR; PG8_SCHED;
	s_setprio 1
	s_waitcnt lgkmcnt(0)
	v_mfma_f32_16x16x32_bf16 v[64:67], v[148:151], v[212:215], v[64:67]
	v_mfma_f32_16x16x32_bf16 v[60:63], v[156:159], v[212:215], v[60:63]
	v_mfma_f32_16x16x32_bf16 v[48:51], v[148:151], v[220:223], v[48:51]
	v_mfma_f32_16x16x32_bf16 v[44:47], v[156:159], v[220:223], v[44:47]
	v_mfma_f32_16x16x32_bf16 v[32:35], v[148:151], v[228:231], v[32:35]
	v_mfma_f32_16x16x32_bf16 v[28:31], v[156:159], v[228:231], v[28:31]
	v_mfma_f32_16x16x32_bf16 v[16:19], v[148:151], v[236:239], v[16:19]
	v_mfma_f32_16x16x32_bf16 v[12:15], v[156:159], v[236:239], v[12:15]
	v_mfma_f32_16x16x32_bf16 v[64:67], v[152:155], v[216:219], v[64:67]
	v_mfma_f32_16x16x32_bf16 v[60:63], v[168:171], v[216:219], v[60:63]
	v_mfma_f32_16x16x32_bf16 v[48:51], v[152:155], v[224:227], v[48:51]
	v_mfma_f32_16x16x32_bf16 v[44:47], v[168:171], v[224:227], v[44:47]
	v_mfma_f32_16x16x32_bf16 v[32:35], v[152:155], v[232:235], v[32:35]
	v_mfma_f32_16x16x32_bf16 v[28:31], v[168:171], v[232:235], v[28:31]
	v_mfma_f32_16x16x32_bf16 v[16:19], v[152:155], v[240:243], v[16:19]
	v_mfma_f32_16x16x32_bf16 v[12:15], v[168:171], v[240:243], v[12:15]
	s_setprio 0
	s_setprio 1
	v_mfma_f32_16x16x32_bf16 v[56:59], v[172:175], v[212:215], v[56:59]
	v_mfma_f32_16x16x32_bf16 v[52:55], v[184:187], v[212:215], v[52:55]
	v_mfma_f32_16x16x32_bf16 v[40:43], v[172:175], v[220:223], v[40:43]
	v_mfma_f32_16x16x32_bf16 v[36:39], v[184:187], v[220:223], v[36:39]
	v_mfma_f32_16x16x32_bf16 v[24:27], v[172:175], v[228:231], v[24:27]
	v_mfma_f32_16x16x32_bf16 v[20:23], v[184:187], v[228:231], v[20:23]
	v_mfma_f32_16x16x32_bf16 v[8:11], v[172:175], v[236:239], v[8:11]
	v_mfma_f32_16x16x32_bf16 v[2:5], v[184:187], v[236:239], v[4:7]
	v_mfma_f32_16x16x32_bf16 v[56:59], v[176:179], v[216:219], v[56:59]
	v_mfma_f32_16x16x32_bf16 v[52:55], v[208:211], v[216:219], v[52:55]
	v_mfma_f32_16x16x32_bf16 v[40:43], v[176:179], v[224:227], v[40:43]
	v_mfma_f32_16x16x32_bf16 v[36:39], v[208:211], v[224:227], v[36:39]
	v_mfma_f32_16x16x32_bf16 v[24:27], v[176:179], v[232:235], v[24:27]
	v_mfma_f32_16x16x32_bf16 v[20:23], v[208:211], v[232:235], v[20:23]
	v_mfma_f32_16x16x32_bf16 v[8:11], v[176:179], v[240:243], v[8:11]
	v_mfma_f32_16x16x32_bf16 v[2:5], v[208:211], v[240:243], v[2:5]
	s_setprio 0
	s_barrier
	s_add_i32 s26, 0, 0x18000
	v_add_u32_e32 v1, s26, v182
	s_add_i32 s27, 0, 0x1c000
	ds_read_b128 v[148:151], v1
	ds_read_b128 v[152:155], v1 offset:1024
	ds_read_b128 v[156:159], v1 offset:2048
	ds_read_b128 v[168:171], v1 offset:3072
	v_add_u32_e32 v1, s27, v182
	ds_read_b128 v[172:175], v1
	ds_read_b128 v[176:179], v1 offset:1024
	ds_read_b128 v[184:187], v1 offset:2048
	ds_read_b128 v[208:211], v1 offset:3072
	s_add_u32 s6, s6, 0xc0000
	s_addc_u32 s7, s7, 0
	s_mov_b32 m0, s18
	v_lshl_add_u64 v[6:7], s[6:7], 0, v[132:133]
	ds_read_b128 v[212:215], v183 offset:32768
	ds_read_b128 v[216:219], v183 offset:33792
	ds_read_b128 v[220:223], v183 offset:34816
	ds_read_b128 v[224:227], v183 offset:35840
	ds_read_b128 v[228:231], v183 offset:36864
	ds_read_b128 v[232:235], v183 offset:37888
	ds_read_b128 v[236:239], v183 offset:38912
	ds_read_b128 v[240:243], v183 offset:39936
	global_load_lds_dwordx4 v[6:7], off sc0
	v_lshl_add_u64 v[6:7], s[6:7], 0, v[136:137]
	s_mov_b32 m0, s19
	s_nop 0
	global_load_lds_dwordx4 v[6:7], off sc0
	s_waitcnt vmcnt(8)
	s_waitcnt lgkmcnt(0)
	s_barrier
	s_setprio 1
	s_waitcnt lgkmcnt(0)
	v_mfma_f32_16x16x32_bf16 v[128:131], v[148:151], v[212:215], v[128:131]
	v_mfma_f32_16x16x32_bf16 v[124:127], v[156:159], v[212:215], v[124:127]
	v_mfma_f32_16x16x32_bf16 v[112:115], v[148:151], v[220:223], v[112:115]
	v_mfma_f32_16x16x32_bf16 v[108:111], v[156:159], v[220:223], v[108:111]
	v_mfma_f32_16x16x32_bf16 v[96:99], v[148:151], v[228:231], v[96:99]
	v_mfma_f32_16x16x32_bf16 v[92:95], v[156:159], v[228:231], v[92:95]
	v_mfma_f32_16x16x32_bf16 v[80:83], v[148:151], v[236:239], v[80:83]
	v_mfma_f32_16x16x32_bf16 v[76:79], v[156:159], v[236:239], v[76:79]
	v_mfma_f32_16x16x32_bf16 v[128:131], v[152:155], v[216:219], v[128:131]
	v_mfma_f32_16x16x32_bf16 v[124:127], v[168:171], v[216:219], v[124:127]
	v_mfma_f32_16x16x32_bf16 v[112:115], v[152:155], v[224:227], v[112:115]
	v_mfma_f32_16x16x32_bf16 v[108:111], v[168:171], v[224:227], v[108:111]
	v_mfma_f32_16x16x32_bf16 v[96:99], v[152:155], v[232:235], v[96:99]
	v_mfma_f32_16x16x32_bf16 v[92:95], v[168:171], v[232:235], v[92:95]
	v_mfma_f32_16x16x32_bf16 v[80:83], v[152:155], v[240:243], v[80:83]
	v_mfma_f32_16x16x32_bf16 v[76:79], v[168:171], v[240:243], v[76:79]
	s_setprio 0
	s_setprio 1
	v_mfma_f32_16x16x32_bf16 v[120:123], v[172:175], v[212:215], v[120:123]
	v_mfma_f32_16x16x32_bf16 v[116:119], v[184:187], v[212:215], v[116:119]
	v_mfma_f32_16x16x32_bf16 v[104:107], v[172:175], v[220:223], v[104:107]
	v_mfma_f32_16x16x32_bf16 v[100:103], v[184:187], v[220:223], v[100:103]
	v_mfma_f32_16x16x32_bf16 v[88:91], v[172:175], v[228:231], v[88:91]
	v_mfma_f32_16x16x32_bf16 v[84:87], v[184:187], v[228:231], v[84:87]
	v_mfma_f32_16x16x32_bf16 v[72:75], v[172:175], v[236:239], v[72:75]
	v_mfma_f32_16x16x32_bf16 v[68:71], v[184:187], v[236:239], v[68:71]
	v_mfma_f32_16x16x32_bf16 v[120:123], v[176:179], v[216:219], v[120:123]
	v_mfma_f32_16x16x32_bf16 v[116:119], v[208:211], v[216:219], v[116:119]
	v_mfma_f32_16x16x32_bf16 v[104:107], v[176:179], v[224:227], v[104:107]
	v_mfma_f32_16x16x32_bf16 v[100:103], v[208:211], v[224:227], v[100:103]
	v_mfma_f32_16x16x32_bf16 v[88:91], v[176:179], v[232:235], v[88:91]
	v_mfma_f32_16x16x32_bf16 v[84:87], v[208:211], v[232:235], v[84:87]
	v_mfma_f32_16x16x32_bf16 v[72:75], v[176:179], v[240:243], v[72:75]
	v_mfma_f32_16x16x32_bf16 v[68:71], v[208:211], v[240:243], v[68:71]
	s_setprio 0
	s_barrier
; #define PG8_STAGE(bufoff, gbase, voff) do { _Pragma("unroll") for (int _i = 0; _i < 2; ++_i) \
;         __builtin_amdgcn_global_load_lds((const unsigned*)((const char*)(gbase) + (voff)[_i]), (LAS unsigned*)(lds + (bufoff) + ldsw + _i * 8192), 16, 0, 0); } while (0)
; #define PG8_LDA(dst, b, h) do { _Pragma("unroll") for (int m = 0; m < 4; ++m) _Pragma("unroll") for (int k = 0; k < 2; ++k) dst[m][k] = *(const LAS bf16x8*)(lds + PG8_SA(b, h) + aoff + m * 2048 + k * 1024); } while (0)
; #define PG8_MMA(ai, bj, At, Bt) do { __builtin_amdgcn_s_setprio(1); _Pragma("unroll") for (int m = 0; m < 4; ++m) _Pragma("unroll") for (int n = 0; n < 2; ++n) _Pragma("unroll") for (int k = 0; k < 2; ++k) \
;         acc[ai][bj][m][n] = __builtin_amdgcn_mfma_f32_16x16x32_bf16(Bt[n][k], At[m][k], acc[ai][bj][m][n], 0, 0, 0); __builtin_amdgcn_s_setprio(0); } while (0)
; #define PG8_WAIT_V(n) asm volatile("s_waitcnt vmcnt(" #n ")" ::: "memory")
; #define PG8_WAIT_L(n) asm volatile("s_waitcnt lgkmcnt(" #n ")" ::: "memory")
; #define PG8_BAR __builtin_amdgcn_s_barrier()
; #define PG8_SCHED __builtin_amdgcn_sched_barrier(0)
; template <class Epi, class Order = StaticOrder, bool HALFN = false>
; __device__ __forceinline__ void gemm_phase(LAS unsigned char* lds, const Gemm g, const Epi& E) {
;     ...
;             PG8_LDA(At, 1, 1); PG8_STAGE(PG8_SB(1, 0), b3, voffB); PG8_STAGE(PG8_SB(1, 1), b3 + hstepB, voffB); PG8_STAGE(PG8_SA(1, 0), a3, voffA);
;             PG8_WAIT_V(8); PG8_WAIT_L(0); PG8_BAR; PG8_MMA(1, 0, At, B0); if constexpr (!HALFN) PG8_MMA(1, 1, At, B1); PG8_BAR; PG8_SCHED;
;         }
;         if (wr == 0) PG8_BAR;
	s_add_i32 s6, s26, s15
	v_lshl_add_u64 v[6:7], v[160:161], 0, s[60:61]
	s_mov_b32 m0, s6
	ds_read_b128 v[212:215], v183 offset:49152
	ds_read_b128 v[216:219], v183 offset:50176
	ds_read_b128 v[220:223], v183 offset:51200
	ds_read_b128 v[224:227], v183 offset:52224
	ds_read_b128 v[228:231], v183 offset:53248
	ds_read_b128 v[232:235], v183 offset:54272
	ds_read_b128 v[236:239], v183 offset:55296
	ds_read_b128 v[240:243], v183 offset:56320
	global_load_lds_dwordx4 v[6:7], off sc0
	s_add_i32 m0, s6, 0x2000
	s_add_u32 s4, s4, 0xc0080
	v_lshl_add_u64 v[6:7], v[244:245], 0, s[60:61]
	s_addc_u32 s5, s5, 0
	s_add_i32 s6, s27, s15
	global_load_lds_dwordx4 v[6:7], off sc0
	v_lshl_add_u64 v[6:7], s[4:5], 0, v[134:135]
	s_mov_b32 m0, s6
	s_nop 0
	global_load_lds_dwordx4 v[6:7], off sc0
	v_lshl_add_u64 v[6:7], s[4:5], 0, v[138:139]
	s_add_i32 m0, s6, 0x2000
	s_nop 0
	global_load_lds_dwordx4 v[6:7], off sc0
	v_lshl_add_u64 v[6:7], v[246:247], 0, s[60:61]
	s_mov_b32 m0, s22
	s_nop 0
	global_load_lds_dwordx4 v[6:7], off sc0
	v_lshl_add_u64 v[6:7], v[248:249], 0, s[60:61]
	s_mov_b32 m0, s23
	s_nop 0
	global_load_lds_dwordx4 v[6:7], off sc0
	s_waitcnt vmcnt(8)
	s_waitcnt lgkmcnt(0)
	s_barrier
	s_setprio 1
	s_waitcnt lgkmcnt(0)
	v_mfma_f32_16x16x32_bf16 v[64:67], v[148:151], v[212:215], v[64:67]
	v_mfma_f32_16x16x32_bf16 v[60:63], v[156:159], v[212:215], v[60:63]
	v_mfma_f32_16x16x32_bf16 v[48:51], v[148:151], v[220:223], v[48:51]
	v_mfma_f32_16x16x32_bf16 v[44:47], v[156:159], v[220:223], v[44:47]
	v_mfma_f32_16x16x32_bf16 v[32:35], v[148:151], v[228:231], v[32:35]
	v_mfma_f32_16x16x32_bf16 v[28:31], v[156:159], v[228:231], v[28:31]
	v_mfma_f32_16x16x32_bf16 v[16:19], v[148:151], v[236:239], v[16:19]
	v_mfma_f32_16x16x32_bf16 v[12:15], v[156:159], v[236:239], v[12:15]
	v_mfma_f32_16x16x32_bf16 v[64:67], v[152:155], v[216:219], v[64:67]
	v_mfma_f32_16x16x32_bf16 v[60:63], v[168:171], v[216:219], v[60:63]
	v_mfma_f32_16x16x32_bf16 v[48:51], v[152:155], v[224:227], v[48:51]
	v_mfma_f32_16x16x32_bf16 v[44:47], v[168:171], v[224:227], v[44:47]
	v_mfma_f32_16x16x32_bf16 v[32:35], v[152:155], v[232:235], v[32:35]
	v_mfma_f32_16x16x32_bf16 v[28:31], v[168:171], v[232:235], v[28:31]
	v_mfma_f32_16x16x32_bf16 v[16:19], v[152:155], v[240:243], v[16:19]
	v_mfma_f32_16x16x32_bf16 v[12:15], v[168:171], v[240:243], v[12:15]
	s_setprio 0
	s_setprio 1
	v_mfma_f32_16x16x32_bf16 v[56:59], v[172:175], v[212:215], v[56:59]
	v_mfma_f32_16x16x32_bf16 v[52:55], v[184:187], v[212:215], v[52:55]
	v_mfma_f32_16x16x32_bf16 v[40:43], v[172:175], v[220:223], v[40:43]
	v_mfma_f32_16x16x32_bf16 v[36:39], v[184:187], v[220:223], v[36:39]
	v_mfma_f32_16x16x32_bf16 v[24:27], v[172:175], v[228:231], v[24:27]
	v_mfma_f32_16x16x32_bf16 v[20:23], v[184:187], v[228:231], v[20:23]
	v_mfma_f32_16x16x32_bf16 v[6:9], v[172:175], v[236:239], v[8:11]
	v_mfma_f32_16x16x32_bf16 v[2:5], v[184:187], v[236:239], v[2:5]
	v_mfma_f32_16x16x32_bf16 v[56:59], v[176:179], v[216:219], v[56:59]
	v_mfma_f32_16x16x32_bf16 v[52:55], v[208:211], v[216:219], v[52:55]
	v_mfma_f32_16x16x32_bf16 v[40:43], v[176:179], v[224:227], v[40:43]
	v_mfma_f32_16x16x32_bf16 v[36:39], v[208:211], v[224:227], v[36:39]
	v_mfma_f32_16x16x32_bf16 v[24:27], v[176:179], v[232:235], v[24:27]
	v_mfma_f32_16x16x32_bf16 v[20:23], v[208:211], v[232:235], v[20:23]
	v_mfma_f32_16x16x32_bf16 v[8:11], v[176:179], v[240:243], v[6:9]
	v_mfma_f32_16x16x32_bf16 v[4:7], v[208:211], v[240:243], v[2:5]
	s_setprio 0
	s_barrier
	s_add_i32 s4, s74, 2
	s_add_u32 s54, s54, 0x100
	s_addc_u32 s55, s55, 0
	s_cmp_gt_u32 s74, 45
	s_cbranch_scc1 .LBB0_621
	s_mov_b32 s74, s4
	s_cmp_lt_i32 s74, 32
	s_cbranch_scc1 .LBB0_615
	s_branch .LBB0_614

; __device__ __forceinline__ void unpack8(u32x4 g, f32x4& a, f32x4& b) { a = (f32x4){bf_lo(g.x), bf_hi(g.x), bf_lo(g.y), bf_hi(g.y)}; b = (f32x4){bf_lo(g.z), bf_hi(g.z), bf_lo(g.w), bf_hi(g.w)}; }
; #define PG8_STAGE(bufoff, gbase, voff) do { _Pragma("unroll") for (int _i = 0; _i < 2; ++_i) \
;         __builtin_amdgcn_global_load_lds((const unsigned*)((const char*)(gbase) + (voff)[_i]), (LAS unsigned*)(lds + (bufoff) + ldsw + _i * 8192), 16, 0, 0); } while (0)
; #define PG8_WAIT_V(n) asm volatile("s_waitcnt vmcnt(" #n ")" ::: "memory")
; #define PG8_BAR __builtin_amdgcn_s_barrier()
; #define EPI_OPAQUE asm volatile("" : "+v"(fr), "+v"(fq));
; template <class Epi, class Order = StaticOrder, bool HALFN = false>
; __device__ __forceinline__ void gemm_phase(LAS unsigned char* lds, const Gemm g, const Epi& E) {
;     ...
;     const char* cA = (const char*)g.A + (size_t)cur.pm * tstepA + (size_t)cur.pn * g.a_pn_off * 2; const char* cB = (const char*)g.Bt + (size_t)cur.pn * tstepB + (HALFN ? (size_t)(cur.half - 1) * hstepB : (size_t)0);
;     PG8_STAGE(PG8_SB(0, 0), cB, voffB); PG8_STAGE(PG8_SB(0, 1), cB + hstepB, voffB); PG8_STAGE(PG8_SA(0, 0), cA, voffA); PG8_STAGE(PG8_SA(0, 1), cA + hstepA, voffA);
;     if (wr == 1) PG8_BAR;
;     PG8_WAIT_V(2); PG8_BAR;
;     __device__ __forceinline__ void init(f32x4 (&acc)[2][2][4][2], const Unit& u, int wr, int wc, int fr, int fq) const {
;         EPI_OPAQUE
;         if (basef) {
;             EPI_ROWS_BEGIN EPI_COLS_BEGIN
;                 const size_t off = (size_t)row * DM + col;
;                 acc[ai][bj][m][0] = *(const f32x4*)(basef + off); acc[ai][bj][m][1] = *(const f32x4*)(basef + off + 4);
;             EPI_END EPI_END
;         } else {
;             EPI_ROWS_BEGIN EPI_COLS_BEGIN
;                 unpack8(*(const u32x4*)(baseb + (size_t)row * DM + col), acc[ai][bj][m][0], acc[ai][bj][m][1]);
;             EPI_END EPI_END
;         }
.LBB0_691:
	s_andn2_b64 vcc, exec, s[4:5]
	s_cbranch_vccnz .LBB0_716
	s_waitcnt lgkmcnt(0)
	v_ashrrev_i32_e32 v3, 31, v2
	v_lshrrev_b32_e32 v3, 26, v3
	v_add_u32_e32 v3, v2, v3
	v_ashrrev_i32_e32 v138, 6, v3
	v_bfe_i32 v3, v2, 27, 1
	v_lshlrev_b32_e32 v1, 4, v2
	v_lshrrev_b32_e32 v3, 22, v3
	v_add_u32_e32 v3, v1, v3
	v_and_b32_e32 v3, 0xfffffc00, v3
	v_sub_u32_e32 v3, v1, v3
	v_lshrrev_b32_e32 v4, 4, v3
	v_bitop3_b32 v3, v4, v3, 32 bitop3:0x6c
	v_ashrrev_i32_e32 v5, 31, v3
	v_lshrrev_b32_e32 v5, 26, v5
	v_add_u32_e32 v5, v3, v5
	v_lshlrev_b32_e32 v4, 3, v138
	v_ashrrev_i32_e32 v139, 6, v5
	v_and_b32_e32 v5, 0xc0, v5
	v_and_b32_e32 v4, -16, v4
	v_sub_u32_e32 v3, v3, v5
	s_lshl_b32 s4, s78, 23
	v_readlane_b32 s5, v251, 36
	v_add_u32_e32 v4, v139, v4
	v_ashrrev_i16_sdwa v3, v190, sext(v3) dst_sel:DWORD dst_unused:UNUSED_PAD src0_sel:DWORD src1_sel:BYTE_0
	s_add_u32 s8, s5, s4
	v_lshlrev_b32_e32 v6, 5, v138
	v_bfe_i32 v140, v3, 0, 16
	v_lshlrev_b32_e32 v3, 1, v4
	v_lshrrev_b32_e32 v5, 2, v4
	v_and_b32_e32 v7, 3, v139
	s_mov_b32 s5, 0xfffe0
	v_and_b32_e32 v6, 32, v6
	v_and_b32_e32 v3, 24, v3
	v_and_b32_e32 v5, 4, v5
	v_and_or_b32 v7, v4, s5, v7
	v_or3_b32 v3, v7, v5, v3
	v_add_lshl_u32 v5, v6, v140, 1
	v_add_u32_e32 v1, 0x2000, v1
	v_lshl_add_u32 v132, v3, 12, v5
	v_ashrrev_i32_e32 v3, 31, v1
	v_lshrrev_b32_e32 v3, 22, v3
	v_add_u32_e32 v3, v1, v3
	v_ashrrev_i32_e32 v141, 10, v3
	v_mul_i32_i24_e32 v3, 0x400, v141
	v_sub_u32_e32 v1, v1, v3
	v_lshrrev_b32_e32 v3, 4, v1
	v_bitop3_b32 v1, v3, v1, 32 bitop3:0x6c
	v_lshl_add_u32 v130, v4, 12, v5
	v_ashrrev_i32_e32 v4, 31, v1
	v_lshrrev_b32_e32 v4, 26, v4
	v_add_u32_e32 v4, v1, v4
	v_lshlrev_b32_e32 v3, 3, v141
	v_ashrrev_i32_e32 v144, 6, v4
	v_and_b32_e32 v4, 0xc0, v4
	v_and_b32_e32 v3, -16, v3
	v_sub_u32_e32 v1, v1, v4
	v_add_u32_e32 v3, v144, v3
	v_ashrrev_i16_sdwa v1, v190, sext(v1) dst_sel:DWORD dst_unused:UNUSED_PAD src0_sel:DWORD src1_sel:BYTE_0
	v_lshlrev_b32_e32 v5, 5, v141
	v_bfe_i32 v145, v1, 0, 16
	v_lshlrev_b32_e32 v1, 1, v3
	v_lshrrev_b32_e32 v4, 2, v3
	v_and_b32_e32 v6, 3, v144
	v_readlane_b32 s4, v251, 37
	v_and_b32_e32 v5, 32, v5
	v_and_b32_e32 v1, 24, v1
	v_and_b32_e32 v4, 4, v4
	v_and_or_b32 v6, v3, s5, v6
	s_addc_u32 s9, s4, 0
	v_or3_b32 v1, v6, v4, v1
	v_add_lshl_u32 v4, v5, v145, 1
	s_ashr_i32 s5, s22, 6
	s_ashr_i32 s4, s22, 8
	v_lshl_add_u32 v136, v1, 12, v4
	v_and_b32_e32 v1, 15, v2
	v_bfe_u32 v142, v2, 4, 2
	s_lshl_b32 s10, s5, 10
	s_lshl_b32 s5, s5, 5
	s_lshl_b32 s11, s4, 6
	s_and_b32 s15, s5, 0x60
	v_mov_b32_e32 v2, v1
	v_mov_b32_e32 v6, v142
	s_lshl_b32 s5, s52, 8
	s_add_i32 s5, s5, s11
	v_add_u32_e32 v2, s5, v2
	s_lshl_b32 s5, s50, 8
	s_or_b32 s5, s5, s15
	v_lshl_add_u32 v6, v6, 3, s5
	v_ashrrev_i32_e32 v7, 31, v6
	v_lshl_add_u32 v134, v3, 12, v4
	v_ashrrev_i32_e32 v3, 31, v2
	v_lshlrev_b64 v[22:23], 1, v[6:7]
	v_add_u32_e32 v6, 0x80, v6
	v_lshlrev_b64 v[4:5], 12, v[2:3]
	v_ashrrev_i32_e32 v7, 31, v6
	v_lshl_add_u64 v[4:5], s[0:1], 0, v[4:5]
	v_lshlrev_b64 v[24:25], 1, v[6:7]
	v_lshl_add_u64 v[8:9], v[4:5], 0, v[22:23]
	v_lshl_add_u64 v[4:5], v[4:5], 0, v[24:25]
	global_load_dwordx4 v[6:9], v[8:9], off
	s_nop 0
	global_load_dwordx4 v[10:13], v[4:5], off
	v_add_u32_e32 v4, 16, v2
	v_ashrrev_i32_e32 v5, 31, v4
	v_lshlrev_b64 v[4:5], 12, v[4:5]
	v_lshl_add_u64 v[4:5], s[0:1], 0, v[4:5]
	v_lshl_add_u64 v[14:15], v[4:5], 0, v[22:23]
	v_lshl_add_u64 v[4:5], v[4:5], 0, v[24:25]
	global_load_dwordx4 v[14:17], v[14:15], off
	s_nop 0
	global_load_dwordx4 v[18:21], v[4:5], off
	v_add_u32_e32 v4, 32, v2
	v_ashrrev_i32_e32 v5, 31, v4
	v_lshlrev_b64 v[4:5], 12, v[4:5]
	v_lshl_add_u64 v[4:5], s[0:1], 0, v[4:5]
	v_lshl_add_u64 v[26:27], v[4:5], 0, v[22:23]
	v_lshl_add_u64 v[4:5], v[4:5], 0, v[24:25]
	global_load_dwordx4 v[26:29], v[26:27], off
	s_nop 0
	global_load_dwordx4 v[30:33], v[4:5], off
	v_add_u32_e32 v4, 48, v2
	v_ashrrev_i32_e32 v5, 31, v4
	v_lshlrev_b64 v[4:5], 12, v[4:5]
	v_lshl_add_u64 v[4:5], s[0:1], 0, v[4:5]
	v_lshl_add_u64 v[34:35], v[4:5], 0, v[22:23]
	v_lshl_add_u64 v[4:5], v[4:5], 0, v[24:25]
	global_load_dwordx4 v[42:45], v[34:35], off
	global_load_dwordx4 v[60:63], v[4:5], off
	v_add_u32_e32 v4, 0x80, v2
	v_ashrrev_i32_e32 v5, 31, v4
	v_lshlrev_b64 v[4:5], 12, v[4:5]
	v_lshl_add_u64 v[4:5], s[0:1], 0, v[4:5]
	v_lshl_add_u64 v[34:35], v[4:5], 0, v[22:23]
	v_lshl_add_u64 v[4:5], v[4:5], 0, v[24:25]
	global_load_dwordx4 v[70:73], v[34:35], off
	global_load_dwordx4 v[78:81], v[4:5], off
	v_add_u32_e32 v4, 0x90, v2
	v_ashrrev_i32_e32 v5, 31, v4
	v_lshlrev_b64 v[4:5], 12, v[4:5]
	v_lshl_add_u64 v[4:5], s[0:1], 0, v[4:5]
	v_lshl_add_u64 v[34:35], v[4:5], 0, v[22:23]
	v_lshl_add_u64 v[4:5], v[4:5], 0, v[24:25]
	global_load_dwordx4 v[86:89], v[34:35], off
	global_load_dwordx4 v[90:93], v[4:5], off
	v_add_u32_e32 v4, 0xa0, v2
	v_ashrrev_i32_e32 v5, 31, v4
	v_add_u32_e32 v2, 0xb0, v2
	s_ashr_i32 s53, s52, 31
	s_ashr_i32 s51, s50, 31
	v_lshlrev_b64 v[4:5], 12, v[4:5]
	v_ashrrev_i32_e32 v3, 31, v2
	s_lshl_b64 s[6:7], s[52:53], 20
	s_lshl_b64 s[16:17], s[50:51], 20
	v_lshl_add_u64 v[4:5], s[0:1], 0, v[4:5]
	v_lshlrev_b64 v[2:3], 12, v[2:3]
	s_add_u32 s80, s8, s16
	v_lshl_add_u64 v[34:35], v[4:5], 0, v[22:23]
	v_lshl_add_u64 v[4:5], v[4:5], 0, v[24:25]
	v_lshl_add_u64 v[2:3], s[0:1], 0, v[2:3]
	s_addc_u32 s81, s9, s17
	s_add_i32 s16, s10, 0
	global_load_dwordx4 v[94:97], v[34:35], off
	global_load_dwordx4 v[98:101], v[4:5], off
	v_lshl_add_u64 v[4:5], v[2:3], 0, v[22:23]
	s_add_i32 m0, s16, 0x10000
	v_lshl_add_u64 v[2:3], v[2:3], 0, v[24:25]
	global_load_dwordx4 v[106:109], v[4:5], off
	global_load_dwordx4 v[126:129], v[2:3], off
	s_nop 0
	global_load_lds_dwordx4 v132, s[80:81] sc0
	s_add_i32 m0, s16, 0x12000
	s_add_u32 s18, s80, 0x80000
	global_load_lds_dwordx4 v136, s[80:81] sc0
	s_addc_u32 s19, s81, 0
	s_add_i32 m0, s16, 0x14000
	s_nop 0
	global_load_lds_dwordx4 v132, s[18:19] sc0
	s_add_i32 m0, s16, 0x16000
	s_add_u32 s62, s72, s6
	s_addc_u32 s63, s73, s7
	s_add_i32 s17, s16, 0x2000
	global_load_lds_dwordx4 v136, s[18:19] sc0
	s_mov_b32 m0, s16
	s_add_u32 s6, s62, 0x80000
	global_load_lds_dwordx4 v130, s[62:63] sc0
	s_mov_b32 m0, s17
	s_addc_u32 s7, s63, 0
	s_add_i32 s18, s16, 0x4000
	global_load_lds_dwordx4 v134, s[62:63] sc0
	s_mov_b32 m0, s18
	s_add_i32 s19, s16, 0x6000
	global_load_lds_dwordx4 v130, s[6:7] sc0
	s_mov_b32 m0, s19
	s_cmp_eq_u32 s4, 1
	global_load_lds_dwordx4 v134, s[6:7] sc0
	s_cselect_b64 s[40:41], -1, 0
	s_cmp_lg_u32 s4, 1
	s_cbranch_scc1 .LBB0_694
	s_barrier
; __device__ __forceinline__ void unpack8(u32x4 g, f32x4& a, f32x4& b) { a = (f32x4){bf_lo(g.x), bf_hi(g.x), bf_lo(g.y), bf_hi(g.y)}; b = (f32x4){bf_lo(g.z), bf_hi(g.z), bf_lo(g.w), bf_hi(g.w)}; }
; #define PG8_STAGE(bufoff, gbase, voff) do { _Pragma("unroll") for (int _i = 0; _i < 2; ++_i) \
;         __builtin_amdgcn_global_load_lds((const unsigned*)((const char*)(gbase) + (voff)[_i]), (LAS unsigned*)(lds + (bufoff) + ldsw + _i * 8192), 16, 0, 0); } while (0)
; #define PG8_WAIT_V(n) asm volatile("s_waitcnt vmcnt(" #n ")" ::: "memory")
; #define PG8_BAR __builtin_amdgcn_s_barrier()
; template <class Epi, class Order = StaticOrder, bool HALFN = false>
; __device__ __forceinline__ void gemm_phase(LAS unsigned char* lds, const Gemm g, const Epi& E) {
;     ...
;     PG8_STAGE(PG8_SB(0, 0), cB, voffB); PG8_STAGE(PG8_SB(0, 1), cB + hstepB, voffB); PG8_STAGE(PG8_SA(0, 0), cA, voffA); PG8_STAGE(PG8_SA(0, 1), cA + hstepA, voffA);
;     if (wr == 1) PG8_BAR;
;     PG8_WAIT_V(2); PG8_BAR;
;     PG8_STAGE(PG8_SB(1, 0), cB + kstep, voffB); PG8_STAGE(PG8_SA(1, 0), cA + kstep, voffA); PG8_STAGE(PG8_SB(1, 1), cB + hstepB + kstep, voffB);
;     PG8_WAIT_V(6); PG8_BAR;
;     __device__ __forceinline__ void init(f32x4 (&acc)[2][2][4][2], const Unit& u, int wr, int wc, int fr, int fq) const {
;     ...
;             EPI_ROWS_BEGIN EPI_COLS_BEGIN
;                 unpack8(*(const u32x4*)(baseb + (size_t)row * DM + col), acc[ai][bj][m][0], acc[ai][bj][m][1]);
;             EPI_END EPI_END
.LBB0_694:
	v_mov_b32_e32 v133, v0
	v_lshl_add_u64 v[82:83], s[80:81], 0, v[132:133]
	v_mov_b32_e32 v137, v0
	v_lshl_add_u64 v[84:85], s[80:81], 0, v[136:137]
	v_mov_b32_e32 v131, v0
	s_add_i32 m0, s16, 0x18000
	v_lshl_add_u64 v[82:83], v[82:83], 0, s[60:61]
	v_lshl_add_u64 v[102:103], s[62:63], 0, v[130:131]
	v_mov_b32_e32 v135, v0
	s_lshl_b32 s6, s4, 13
	s_lshl_b32 s7, s15, 7
	s_waitcnt vmcnt(2)
	s_barrier
	global_load_lds_dwordx4 v[82:83], off sc0
	v_lshl_add_u64 v[82:83], v[84:85], 0, s[60:61]
	s_add_i32 m0, s16, 0x1a000
	s_add_i32 s20, s16, 0x8000
	s_add_i32 s21, s16, 0xa000
	v_lshl_add_u64 v[104:105], s[62:63], 0, v[134:135]
	global_load_lds_dwordx4 v[82:83], off sc0
	v_lshl_add_u64 v[82:83], v[102:103], 0, s[60:61]
	s_mov_b32 m0, s20
	s_add_u32 s4, s80, 0x80080
	global_load_lds_dwordx4 v[82:83], off sc0
	v_lshl_add_u64 v[82:83], v[104:105], 0, s[60:61]
	s_mov_b32 m0, s21
	s_addc_u32 s5, s81, 0
	global_load_lds_dwordx4 v[82:83], off sc0
	s_add_i32 m0, s16, 0x1c000
	v_lshl_add_u64 v[82:83], s[4:5], 0, v[132:133]
	global_load_lds_dwordx4 v[82:83], off sc0
	v_lshl_add_u64 v[82:83], s[4:5], 0, v[136:137]
	s_add_i32 m0, s16, 0x1e000
	v_or_b32_e32 v143, s11, v1
	global_load_lds_dwordx4 v[82:83], off sc0
	v_lshlrev_b32_e32 v146, 4, v142
	v_lshlrev_b32_e32 v147, 6, v143
	s_movk_i32 s4, 0x3c0
	v_lshlrev_b32_e32 v143, 2, v143
	v_and_or_b32 v147, v147, s4, v146
	v_and_b32_e32 v143, 32, v143
	v_bitop3_b32 v147, v147, s6, v143 bitop3:0xde
	v_lshl_or_b32 v143, v1, 6, v146
	v_lshlrev_b32_e32 v146, 2, v1
	v_and_b32_e32 v146, 32, v146
	v_bitop3_b32 v143, v143, s7, v146 bitop3:0xde
	v_lshlrev_b32_e32 v146, 15, v138
	v_and_b32_e32 v146, 0xffff0000, v146
	v_lshl_add_u32 v139, v139, 12, v146
	v_and_b32_e32 v138, 1, v138
	v_lshl_or_b32 v138, v138, 6, v139
	v_lshl_add_u32 v138, v140, 1, v138
	v_lshlrev_b32_e32 v140, 15, v141
	v_and_b32_e32 v140, 0xffff0000, v140
	s_waitcnt vmcnt(6)
	v_lshl_add_u32 v140, v144, 12, v140
	v_and_b32_e32 v141, 1, v141
	s_cmpk_lt_u32 s22, 0x100
	v_lshl_or_b32 v140, v141, 6, v140
	s_waitcnt vmcnt(0)
	v_lshlrev_b32_e32 v2, 16, v6
	v_and_b32_e32 v3, 0xffff0000, v6
	v_lshlrev_b32_e32 v4, 16, v7
	v_and_b32_e32 v5, 0xffff0000, v7
	v_lshlrev_b32_e32 v6, 16, v8
	v_and_b32_e32 v7, 0xffff0000, v8
	v_lshlrev_b32_e32 v8, 16, v9
	v_and_b32_e32 v9, 0xffff0000, v9
	v_lshlrev_b32_e32 v22, 16, v10
	v_and_b32_e32 v23, 0xffff0000, v10
	v_lshlrev_b32_e32 v24, 16, v11
	v_and_b32_e32 v25, 0xffff0000, v11
	v_lshlrev_b32_e32 v34, 16, v12
	v_and_b32_e32 v35, 0xffff0000, v12
	v_lshlrev_b32_e32 v36, 16, v13
	v_and_b32_e32 v37, 0xffff0000, v13
	v_lshlrev_b32_e32 v10, 16, v14
	v_and_b32_e32 v11, 0xffff0000, v14
	v_lshlrev_b32_e32 v12, 16, v15
	v_and_b32_e32 v13, 0xffff0000, v15
	v_lshlrev_b32_e32 v14, 16, v16
	v_and_b32_e32 v15, 0xffff0000, v16
	v_lshlrev_b32_e32 v16, 16, v17
	v_and_b32_e32 v17, 0xffff0000, v17
	v_lshlrev_b32_e32 v38, 16, v18
	v_and_b32_e32 v39, 0xffff0000, v18
	v_lshlrev_b32_e32 v40, 16, v19
	v_and_b32_e32 v41, 0xffff0000, v19
	v_lshlrev_b32_e32 v46, 16, v20
	v_and_b32_e32 v47, 0xffff0000, v20
	v_lshlrev_b32_e32 v48, 16, v21
	v_and_b32_e32 v49, 0xffff0000, v21
	v_lshlrev_b32_e32 v18, 16, v26
	v_and_b32_e32 v19, 0xffff0000, v26
	v_lshlrev_b32_e32 v20, 16, v27
	v_and_b32_e32 v21, 0xffff0000, v27
	v_lshlrev_b32_e32 v26, 16, v28
	v_and_b32_e32 v27, 0xffff0000, v28
	v_lshlrev_b32_e32 v28, 16, v29
	v_and_b32_e32 v29, 0xffff0000, v29
	v_lshlrev_b32_e32 v50, 16, v30
	v_and_b32_e32 v51, 0xffff0000, v30
	v_lshlrev_b32_e32 v52, 16, v31
	v_and_b32_e32 v53, 0xffff0000, v31
	v_lshlrev_b32_e32 v54, 16, v32
	v_and_b32_e32 v55, 0xffff0000, v32
	v_lshlrev_b32_e32 v56, 16, v33
	v_and_b32_e32 v57, 0xffff0000, v33
	v_lshlrev_b32_e32 v30, 16, v42
	v_and_b32_e32 v31, 0xffff0000, v42
	v_lshlrev_b32_e32 v32, 16, v43
	v_and_b32_e32 v33, 0xffff0000, v43
	v_lshlrev_b32_e32 v42, 16, v44
	v_and_b32_e32 v43, 0xffff0000, v44
	v_lshlrev_b32_e32 v44, 16, v45
	v_and_b32_e32 v45, 0xffff0000, v45
	v_lshlrev_b32_e32 v58, 16, v60
	v_and_b32_e32 v59, 0xffff0000, v60
	v_lshlrev_b32_e32 v60, 16, v61
	v_and_b32_e32 v61, 0xffff0000, v61
	v_lshlrev_b32_e32 v66, 16, v62
	v_and_b32_e32 v67, 0xffff0000, v62
	v_lshlrev_b32_e32 v68, 16, v63
	v_and_b32_e32 v69, 0xffff0000, v63
	v_lshlrev_b32_e32 v62, 16, v70
	v_and_b32_e32 v63, 0xffff0000, v70
	v_lshlrev_b32_e32 v64, 16, v71
	v_and_b32_e32 v65, 0xffff0000, v71
	v_lshlrev_b32_e32 v70, 16, v72
	v_and_b32_e32 v71, 0xffff0000, v72
	v_lshlrev_b32_e32 v72, 16, v73
	v_and_b32_e32 v73, 0xffff0000, v73
	v_lshlrev_b32_e32 v74, 16, v78
	v_and_b32_e32 v75, 0xffff0000, v78
	v_lshlrev_b32_e32 v76, 16, v79
	v_and_b32_e32 v77, 0xffff0000, v79
	v_lshlrev_b32_e32 v78, 16, v80
	v_and_b32_e32 v79, 0xffff0000, v80
	v_lshlrev_b32_e32 v80, 16, v81
	v_and_b32_e32 v81, 0xffff0000, v81
	v_lshlrev_b32_e32 v82, 16, v86
	v_and_b32_e32 v83, 0xffff0000, v86
	v_lshlrev_b32_e32 v84, 16, v87
	v_and_b32_e32 v85, 0xffff0000, v87
	v_lshlrev_b32_e32 v86, 16, v88
	v_and_b32_e32 v87, 0xffff0000, v88
	v_lshlrev_b32_e32 v88, 16, v89
	v_and_b32_e32 v89, 0xffff0000, v89
	v_lshlrev_b32_e32 v102, 16, v90
	v_and_b32_e32 v103, 0xffff0000, v90
	v_lshlrev_b32_e32 v104, 16, v91
	v_and_b32_e32 v105, 0xffff0000, v91
	v_lshlrev_b32_e32 v110, 16, v92
	v_and_b32_e32 v111, 0xffff0000, v92
	v_lshlrev_b32_e32 v112, 16, v93
	v_and_b32_e32 v113, 0xffff0000, v93
	v_lshlrev_b32_e32 v90, 16, v94
	v_and_b32_e32 v91, 0xffff0000, v94
	v_lshlrev_b32_e32 v92, 16, v95
	v_and_b32_e32 v93, 0xffff0000, v95
	v_lshlrev_b32_e32 v94, 16, v96
	v_and_b32_e32 v95, 0xffff0000, v96
	v_lshlrev_b32_e32 v96, 16, v97
	v_and_b32_e32 v97, 0xffff0000, v97
	v_lshlrev_b32_e32 v114, 16, v98
	v_and_b32_e32 v115, 0xffff0000, v98
	v_lshlrev_b32_e32 v116, 16, v99
	v_and_b32_e32 v117, 0xffff0000, v99
	v_lshlrev_b32_e32 v118, 16, v100
	v_and_b32_e32 v119, 0xffff0000, v100
	v_lshlrev_b32_e32 v120, 16, v101
	v_and_b32_e32 v121, 0xffff0000, v101
	v_lshlrev_b32_e32 v98, 16, v106
	v_and_b32_e32 v99, 0xffff0000, v106
	v_lshlrev_b32_e32 v100, 16, v107
	v_and_b32_e32 v101, 0xffff0000, v107
	v_lshlrev_b32_e32 v106, 16, v108
	v_and_b32_e32 v107, 0xffff0000, v108
	v_lshlrev_b32_e32 v108, 16, v109
	v_and_b32_e32 v109, 0xffff0000, v109
	v_lshlrev_b32_e32 v122, 16, v126
	v_and_b32_e32 v123, 0xffff0000, v126
	v_lshlrev_b32_e32 v124, 16, v127
	v_and_b32_e32 v125, 0xffff0000, v127
	v_lshlrev_b32_e32 v126, 16, v128
	v_and_b32_e32 v127, 0xffff0000, v128
	v_lshlrev_b32_e32 v128, 16, v129
	v_and_b32_e32 v129, 0xffff0000, v129
	s_cselect_b64 s[44:45], -1, 0
	v_mov_b32_e32 v139, v0
	v_lshl_add_u32 v140, v145, 1, v140
	v_mov_b32_e32 v141, v0
	s_mov_b32 s22, 0
	v_add_u32_e32 v144, 0, v147
	s_barrier
	s_branch .LBB0_697

; #define PG8_STAGE(bufoff, gbase, voff) do { _Pragma("unroll") for (int _i = 0; _i < 2; ++_i) \
;         __builtin_amdgcn_global_load_lds((const unsigned*)((const char*)(gbase) + (voff)[_i]), (LAS unsigned*)(lds + (bufoff) + ldsw + _i * 8192), 16, 0, 0); } while (0)
; #define PG8_LDA(dst, b, h) do { _Pragma("unroll") for (int m = 0; m < 4; ++m) _Pragma("unroll") for (int k = 0; k < 2; ++k) dst[m][k] = *(const LAS bf16x8*)(lds + PG8_SA(b, h) + aoff + m * 2048 + k * 1024); } while (0)
; #define PG8_LDB(dst, b, h) do { _Pragma("unroll") for (int n = 0; n < 2; ++n) _Pragma("unroll") for (int k = 0; k < 2; ++k) dst[n][k] = *(const LAS bf16x8*)(lds + PG8_SB(b, h) + boff + n * 2048 + k * 1024); } while (0)
; #define PG8_MMA(ai, bj, At, Bt) do { __builtin_amdgcn_s_setprio(1); _Pragma("unroll") for (int m = 0; m < 4; ++m) _Pragma("unroll") for (int n = 0; n < 2; ++n) _Pragma("unroll") for (int k = 0; k < 2; ++k) \
;         acc[ai][bj][m][n] = __builtin_amdgcn_mfma_f32_16x16x32_bf16(Bt[n][k], At[m][k], acc[ai][bj][m][n], 0, 0, 0); __builtin_amdgcn_s_setprio(0); } while (0)
; #define PG8_WAIT_V(n) asm volatile("s_waitcnt vmcnt(" #n ")" ::: "memory")
; #define PG8_WAIT_L(n) asm volatile("s_waitcnt lgkmcnt(" #n ")" ::: "memory")
; #define PG8_BAR __builtin_amdgcn_s_barrier()
; #define PG8_SCHED __builtin_amdgcn_sched_barrier(0)
; template <class Epi, class Order = StaticOrder, bool HALFN = false>
; __device__ __forceinline__ void gemm_phase(LAS unsigned char* lds, const Gemm g, const Epi& E) {
;     ...
;             const char* a1 = cA + (size_t)(t + 1) * kstep;
;             const char* a2 = last ? nA : cA + (size_t)(t + 2) * kstep; const char* b2 = last ? nB : cB + (size_t)(t + 2) * kstep;
;             const char* a3 = a2 + kstep; const char* b3 = b2 + kstep;
;             PG8_LDB(B0, 0, 0); if constexpr (!HALFN) PG8_LDB(B1, 0, 1); PG8_SCHED; PG8_LDA(At, 0, 0); PG8_STAGE(PG8_SA(1, 1), a1 + hstepA, voffA);
;             PG8_WAIT_V(8); PG8_WAIT_L(0); PG8_BAR; PG8_MMA(0, 0, At, B0); if constexpr (!HALFN) PG8_MMA(0, 1, At, B1); PG8_BAR; PG8_SCHED;
;             PG8_LDA(At, 0, 1); PG8_STAGE(PG8_SB(0, 0), b2, voffB); PG8_STAGE(PG8_SB(0, 1), b2 + hstepB, voffB); PG8_STAGE(PG8_SA(0, 0), a2, voffA);
;             PG8_WAIT_V(8); PG8_WAIT_L(0); PG8_BAR; PG8_MMA(1, 0, At, B0); if constexpr (!HALFN) PG8_MMA(1, 1, At, B1); PG8_BAR; PG8_SCHED;
.LBB0_709:
	s_add_u32 s4, s62, 0xfff80080
	s_addc_u32 s5, s63, -1
	s_add_i32 s30, 0, 0x10000
	s_cmp_eq_u32 s29, 28
	s_cselect_b32 s7, s23, s5
	s_cselect_b32 s6, s24, s4
	v_add_u32_e32 v145, s30, v143
	s_cselect_b32 s5, s25, s28
	s_cselect_b32 s4, s26, s27
	s_add_i32 s34, 0, 0x14000
	ds_read_b128 v[146:149], v145
	ds_read_b128 v[150:153], v145 offset:1024
	ds_read_b128 v[154:157], v145 offset:2048
	ds_read_b128 v[158:161], v145 offset:3072
	v_add_u32_e32 v145, s34, v143
	ds_read_b128 v[168:171], v145
	ds_read_b128 v[172:175], v145 offset:1024
	ds_read_b128 v[176:179], v145 offset:2048
	ds_read_b128 v[180:183], v145 offset:3072
	v_lshl_add_u64 v[236:237], s[62:63], 0, v[138:139]
	s_add_i32 m0, s16, 0xc000
	ds_read_b128 v[184:187], v144
	ds_read_b128 v[208:211], v144 offset:1024
	ds_read_b128 v[212:215], v144 offset:2048
	ds_read_b128 v[216:219], v144 offset:3072
	ds_read_b128 v[220:223], v144 offset:4096
	ds_read_b128 v[224:227], v144 offset:5120
	ds_read_b128 v[228:231], v144 offset:6144
	ds_read_b128 v[232:235], v144 offset:7168
	global_load_lds_dwordx4 v[236:237], off sc0
	v_lshl_add_u64 v[236:237], s[62:63], 0, v[140:141]
	s_add_i32 m0, s16, 0xe000
	s_nop 0
	global_load_lds_dwordx4 v[236:237], off sc0
	s_waitcnt vmcnt(8)
	s_waitcnt lgkmcnt(0)
	s_barrier
	s_setprio 1
	s_waitcnt lgkmcnt(0)
	v_mfma_f32_16x16x32_bf16 v[2:5], v[146:149], v[184:187], v[2:5]
	v_mfma_f32_16x16x32_bf16 v[6:9], v[154:157], v[184:187], v[6:9]
	v_mfma_f32_16x16x32_bf16 v[10:13], v[146:149], v[212:215], v[10:13]
	v_mfma_f32_16x16x32_bf16 v[14:17], v[154:157], v[212:215], v[14:17]
	v_mfma_f32_16x16x32_bf16 v[18:21], v[146:149], v[220:223], v[18:21]
	v_mfma_f32_16x16x32_bf16 v[26:29], v[154:157], v[220:223], v[26:29]
	v_mfma_f32_16x16x32_bf16 v[30:33], v[146:149], v[228:231], v[30:33]
	v_mfma_f32_16x16x32_bf16 v[42:45], v[154:157], v[228:231], v[42:45]
	v_mfma_f32_16x16x32_bf16 v[2:5], v[150:153], v[208:211], v[2:5]
	v_mfma_f32_16x16x32_bf16 v[6:9], v[158:161], v[208:211], v[6:9]
	v_mfma_f32_16x16x32_bf16 v[10:13], v[150:153], v[216:219], v[10:13]
	v_mfma_f32_16x16x32_bf16 v[14:17], v[158:161], v[216:219], v[14:17]
	v_mfma_f32_16x16x32_bf16 v[18:21], v[150:153], v[224:227], v[18:21]
	v_mfma_f32_16x16x32_bf16 v[26:29], v[158:161], v[224:227], v[26:29]
	v_mfma_f32_16x16x32_bf16 v[30:33], v[150:153], v[232:235], v[30:33]
	v_mfma_f32_16x16x32_bf16 v[42:45], v[158:161], v[232:235], v[42:45]
	s_setprio 0
	s_setprio 1
	v_mfma_f32_16x16x32_bf16 v[22:25], v[168:171], v[184:187], v[22:25]
	v_mfma_f32_16x16x32_bf16 v[34:37], v[176:179], v[184:187], v[34:37]
	v_mfma_f32_16x16x32_bf16 v[38:41], v[168:171], v[212:215], v[38:41]
	v_mfma_f32_16x16x32_bf16 v[46:49], v[176:179], v[212:215], v[46:49]
	v_mfma_f32_16x16x32_bf16 v[50:53], v[168:171], v[220:223], v[50:53]
	v_mfma_f32_16x16x32_bf16 v[54:57], v[176:179], v[220:223], v[54:57]
	v_mfma_f32_16x16x32_bf16 v[58:61], v[168:171], v[228:231], v[58:61]
	v_mfma_f32_16x16x32_bf16 v[66:69], v[176:179], v[228:231], v[66:69]
	v_mfma_f32_16x16x32_bf16 v[22:25], v[172:175], v[208:211], v[22:25]
	v_mfma_f32_16x16x32_bf16 v[34:37], v[180:183], v[208:211], v[34:37]
	v_mfma_f32_16x16x32_bf16 v[38:41], v[172:175], v[216:219], v[38:41]
	v_mfma_f32_16x16x32_bf16 v[46:49], v[180:183], v[216:219], v[46:49]
	v_mfma_f32_16x16x32_bf16 v[50:53], v[172:175], v[224:227], v[50:53]
	v_mfma_f32_16x16x32_bf16 v[54:57], v[180:183], v[224:227], v[54:57]
	v_mfma_f32_16x16x32_bf16 v[58:61], v[172:175], v[232:235], v[58:61]
	v_mfma_f32_16x16x32_bf16 v[66:69], v[180:183], v[232:235], v[66:69]
	s_setprio 0
	s_barrier
	s_add_i32 s30, s30, s10
	v_lshl_add_u64 v[236:237], s[4:5], 0, v[132:133]
	s_mov_b32 m0, s30
	ds_read_b128 v[184:187], v144 offset:16384
	ds_read_b128 v[208:211], v144 offset:17408
	ds_read_b128 v[212:215], v144 offset:18432
	ds_read_b128 v[216:219], v144 offset:19456
	ds_read_b128 v[220:223], v144 offset:20480
	ds_read_b128 v[224:227], v144 offset:21504
	ds_read_b128 v[228:231], v144 offset:22528
	ds_read_b128 v[232:235], v144 offset:23552
	global_load_lds_dwordx4 v[236:237], off sc0
	s_add_i32 m0, s30, 0x2000
	s_add_u32 s30, s4, 0x80000
	v_lshl_add_u64 v[238:239], s[4:5], 0, v[136:137]
	s_addc_u32 s31, s5, 0
	s_add_i32 s34, s34, s10
	global_load_lds_dwordx4 v[238:239], off sc0
	v_lshl_add_u64 v[240:241], s[30:31], 0, v[132:133]
	s_mov_b32 m0, s34
	v_lshl_add_u64 v[242:243], s[6:7], 0, v[134:135]
	global_load_lds_dwordx4 v[240:241], off sc0
	v_lshl_add_u64 v[240:241], s[30:31], 0, v[136:137]
	s_add_i32 m0, s34, 0x2000
	s_nop 0
	global_load_lds_dwordx4 v[240:241], off sc0
	v_lshl_add_u64 v[240:241], s[6:7], 0, v[130:131]
	s_mov_b32 m0, s16
	s_nop 0
	global_load_lds_dwordx4 v[240:241], off sc0
	s_mov_b32 m0, s17
	s_nop 0
	global_load_lds_dwordx4 v[242:243], off sc0
	s_waitcnt vmcnt(8)
	s_waitcnt lgkmcnt(0)
	s_barrier
; #define PG8_STAGE(bufoff, gbase, voff) do { _Pragma("unroll") for (int _i = 0; _i < 2; ++_i) \
;         __builtin_amdgcn_global_load_lds((const unsigned*)((const char*)(gbase) + (voff)[_i]), (LAS unsigned*)(lds + (bufoff) + ldsw + _i * 8192), 16, 0, 0); } while (0)
; #define PG8_LDA(dst, b, h) do { _Pragma("unroll") for (int m = 0; m < 4; ++m) _Pragma("unroll") for (int k = 0; k < 2; ++k) dst[m][k] = *(const LAS bf16x8*)(lds + PG8_SA(b, h) + aoff + m * 2048 + k * 1024); } while (0)
; #define PG8_LDB(dst, b, h) do { _Pragma("unroll") for (int n = 0; n < 2; ++n) _Pragma("unroll") for (int k = 0; k < 2; ++k) dst[n][k] = *(const LAS bf16x8*)(lds + PG8_SB(b, h) + boff + n * 2048 + k * 1024); } while (0)
; #define PG8_MMA(ai, bj, At, Bt) do { __builtin_amdgcn_s_setprio(1); _Pragma("unroll") for (int m = 0; m < 4; ++m) _Pragma("unroll") for (int n = 0; n < 2; ++n) _Pragma("unroll") for (int k = 0; k < 2; ++k) \
;         acc[ai][bj][m][n] = __builtin_amdgcn_mfma_f32_16x16x32_bf16(Bt[n][k], At[m][k], acc[ai][bj][m][n], 0, 0, 0); __builtin_amdgcn_s_setprio(0); } while (0)
; #define PG8_WAIT_V(n) asm volatile("s_waitcnt vmcnt(" #n ")" ::: "memory")
; #define PG8_WAIT_L(n) asm volatile("s_waitcnt lgkmcnt(" #n ")" ::: "memory")
; #define PG8_BAR __builtin_amdgcn_s_barrier()
; #define PG8_SCHED __builtin_amdgcn_sched_barrier(0)
; template <class Epi, class Order = StaticOrder, bool HALFN = false>
; __device__ __forceinline__ void gemm_phase(LAS unsigned char* lds, const Gemm g, const Epi& E) {
;     ...
;             PG8_WAIT_V(8); PG8_WAIT_L(0); PG8_BAR; PG8_MMA(1, 0, At, B0); if constexpr (!HALFN) PG8_MMA(1, 1, At, B1); PG8_BAR; PG8_SCHED;
;             PG8_LDB(B0, 1, 0); if constexpr (!HALFN) PG8_LDB(B1, 1, 1); PG8_SCHED; PG8_LDA(At, 1, 0); PG8_STAGE(PG8_SA(0, 1), a2 + hstepA, voffA);
;             PG8_WAIT_V(8); PG8_WAIT_L(0); PG8_BAR; PG8_MMA(0, 0, At, B0); if constexpr (!HALFN) PG8_MMA(0, 1, At, B1); PG8_BAR; PG8_SCHED;
	s_setprio 1
	s_waitcnt lgkmcnt(0)
	v_mfma_f32_16x16x32_bf16 v[62:65], v[146:149], v[184:187], v[62:65]
	v_mfma_f32_16x16x32_bf16 v[70:73], v[154:157], v[184:187], v[70:73]
	v_mfma_f32_16x16x32_bf16 v[82:85], v[146:149], v[212:215], v[82:85]
	v_mfma_f32_16x16x32_bf16 v[86:89], v[154:157], v[212:215], v[86:89]
	v_mfma_f32_16x16x32_bf16 v[90:93], v[146:149], v[220:223], v[90:93]
	v_mfma_f32_16x16x32_bf16 v[94:97], v[154:157], v[220:223], v[94:97]
	v_mfma_f32_16x16x32_bf16 v[98:101], v[146:149], v[228:231], v[98:101]
	v_mfma_f32_16x16x32_bf16 v[106:109], v[154:157], v[228:231], v[106:109]
	v_mfma_f32_16x16x32_bf16 v[62:65], v[150:153], v[208:211], v[62:65]
	v_mfma_f32_16x16x32_bf16 v[70:73], v[158:161], v[208:211], v[70:73]
	v_mfma_f32_16x16x32_bf16 v[82:85], v[150:153], v[216:219], v[82:85]
	v_mfma_f32_16x16x32_bf16 v[86:89], v[158:161], v[216:219], v[86:89]
	v_mfma_f32_16x16x32_bf16 v[90:93], v[150:153], v[224:227], v[90:93]
	v_mfma_f32_16x16x32_bf16 v[94:97], v[158:161], v[224:227], v[94:97]
	v_mfma_f32_16x16x32_bf16 v[98:101], v[150:153], v[232:235], v[98:101]
	v_mfma_f32_16x16x32_bf16 v[106:109], v[158:161], v[232:235], v[106:109]
	s_setprio 0
	s_setprio 1
	v_mfma_f32_16x16x32_bf16 v[74:77], v[168:171], v[184:187], v[74:77]
	v_mfma_f32_16x16x32_bf16 v[78:81], v[176:179], v[184:187], v[78:81]
	v_mfma_f32_16x16x32_bf16 v[102:105], v[168:171], v[212:215], v[102:105]
	v_mfma_f32_16x16x32_bf16 v[110:113], v[176:179], v[212:215], v[110:113]
	v_mfma_f32_16x16x32_bf16 v[114:117], v[168:171], v[220:223], v[114:117]
	v_mfma_f32_16x16x32_bf16 v[118:121], v[176:179], v[220:223], v[118:121]
	v_mfma_f32_16x16x32_bf16 v[122:125], v[168:171], v[228:231], v[122:125]
	v_mfma_f32_16x16x32_bf16 v[126:129], v[176:179], v[228:231], v[126:129]
	v_mfma_f32_16x16x32_bf16 v[74:77], v[172:175], v[208:211], v[74:77]
	v_mfma_f32_16x16x32_bf16 v[78:81], v[180:183], v[208:211], v[78:81]
	v_mfma_f32_16x16x32_bf16 v[102:105], v[172:175], v[216:219], v[102:105]
	v_mfma_f32_16x16x32_bf16 v[110:113], v[180:183], v[216:219], v[110:113]
	v_mfma_f32_16x16x32_bf16 v[114:117], v[172:175], v[224:227], v[114:117]
	v_mfma_f32_16x16x32_bf16 v[118:121], v[180:183], v[224:227], v[118:121]
	v_mfma_f32_16x16x32_bf16 v[122:125], v[172:175], v[232:235], v[122:125]
	v_mfma_f32_16x16x32_bf16 v[126:129], v[180:183], v[232:235], v[126:129]
	s_setprio 0
	s_barrier
	s_add_i32 s30, 0, 0x18000
	v_add_u32_e32 v145, s30, v143
	s_add_i32 s31, 0, 0x1c000
	ds_read_b128 v[146:149], v145
	ds_read_b128 v[150:153], v145 offset:1024
	ds_read_b128 v[154:157], v145 offset:2048
	ds_read_b128 v[158:161], v145 offset:3072
	v_add_u32_e32 v145, s31, v143
	ds_read_b128 v[168:171], v145
	ds_read_b128 v[172:175], v145 offset:1024
	ds_read_b128 v[176:179], v145 offset:2048
	ds_read_b128 v[180:183], v145 offset:3072
	s_add_u32 s6, s6, 0x80000
	s_addc_u32 s7, s7, 0
	s_mov_b32 m0, s18
	v_lshl_add_u64 v[244:245], s[6:7], 0, v[130:131]
	ds_read_b128 v[184:187], v144 offset:32768
	ds_read_b128 v[208:211], v144 offset:33792
	ds_read_b128 v[212:215], v144 offset:34816
	ds_read_b128 v[216:219], v144 offset:35840
	ds_read_b128 v[220:223], v144 offset:36864
	ds_read_b128 v[224:227], v144 offset:37888
	ds_read_b128 v[228:231], v144 offset:38912
	ds_read_b128 v[232:235], v144 offset:39936
	global_load_lds_dwordx4 v[244:245], off sc0
	v_lshl_add_u64 v[244:245], s[6:7], 0, v[134:135]
	s_mov_b32 m0, s19
	s_nop 0
	global_load_lds_dwordx4 v[244:245], off sc0
	s_waitcnt vmcnt(8)
	s_waitcnt lgkmcnt(0)
	s_barrier
	s_setprio 1
	s_waitcnt lgkmcnt(0)
	v_mfma_f32_16x16x32_bf16 v[2:5], v[146:149], v[184:187], v[2:5]
	v_mfma_f32_16x16x32_bf16 v[6:9], v[154:157], v[184:187], v[6:9]
	v_mfma_f32_16x16x32_bf16 v[10:13], v[146:149], v[212:215], v[10:13]
	v_mfma_f32_16x16x32_bf16 v[14:17], v[154:157], v[212:215], v[14:17]
	v_mfma_f32_16x16x32_bf16 v[18:21], v[146:149], v[220:223], v[18:21]
	v_mfma_f32_16x16x32_bf16 v[26:29], v[154:157], v[220:223], v[26:29]
	v_mfma_f32_16x16x32_bf16 v[30:33], v[146:149], v[228:231], v[30:33]
	v_mfma_f32_16x16x32_bf16 v[42:45], v[154:157], v[228:231], v[42:45]
	v_mfma_f32_16x16x32_bf16 v[2:5], v[150:153], v[208:211], v[2:5]
	v_mfma_f32_16x16x32_bf16 v[6:9], v[158:161], v[208:211], v[6:9]
	v_mfma_f32_16x16x32_bf16 v[10:13], v[150:153], v[216:219], v[10:13]
	v_mfma_f32_16x16x32_bf16 v[14:17], v[158:161], v[216:219], v[14:17]
	v_mfma_f32_16x16x32_bf16 v[18:21], v[150:153], v[224:227], v[18:21]
	v_mfma_f32_16x16x32_bf16 v[26:29], v[158:161], v[224:227], v[26:29]
	v_mfma_f32_16x16x32_bf16 v[30:33], v[150:153], v[232:235], v[30:33]
	v_mfma_f32_16x16x32_bf16 v[42:45], v[158:161], v[232:235], v[42:45]
	s_setprio 0
	s_setprio 1
	v_mfma_f32_16x16x32_bf16 v[22:25], v[168:171], v[184:187], v[22:25]
	v_mfma_f32_16x16x32_bf16 v[34:37], v[176:179], v[184:187], v[34:37]
	v_mfma_f32_16x16x32_bf16 v[38:41], v[168:171], v[212:215], v[38:41]
	v_mfma_f32_16x16x32_bf16 v[46:49], v[176:179], v[212:215], v[46:49]
	v_mfma_f32_16x16x32_bf16 v[50:53], v[168:171], v[220:223], v[50:53]
	v_mfma_f32_16x16x32_bf16 v[54:57], v[176:179], v[220:223], v[54:57]
	v_mfma_f32_16x16x32_bf16 v[58:61], v[168:171], v[228:231], v[58:61]
	v_mfma_f32_16x16x32_bf16 v[66:69], v[176:179], v[228:231], v[66:69]
	v_mfma_f32_16x16x32_bf16 v[22:25], v[172:175], v[208:211], v[22:25]
	v_mfma_f32_16x16x32_bf16 v[34:37], v[180:183], v[208:211], v[34:37]
	v_mfma_f32_16x16x32_bf16 v[38:41], v[172:175], v[216:219], v[38:41]
	v_mfma_f32_16x16x32_bf16 v[46:49], v[180:183], v[216:219], v[46:49]
	v_mfma_f32_16x16x32_bf16 v[50:53], v[172:175], v[224:227], v[50:53]
	v_mfma_f32_16x16x32_bf16 v[54:57], v[180:183], v[224:227], v[54:57]
	v_mfma_f32_16x16x32_bf16 v[58:61], v[172:175], v[232:235], v[58:61]
	v_mfma_f32_16x16x32_bf16 v[66:69], v[180:183], v[232:235], v[66:69]
	s_setprio 0
	s_barrier
; #define PG8_STAGE(bufoff, gbase, voff) do { _Pragma("unroll") for (int _i = 0; _i < 2; ++_i) \
;         __builtin_amdgcn_global_load_lds((const unsigned*)((const char*)(gbase) + (voff)[_i]), (LAS unsigned*)(lds + (bufoff) + ldsw + _i * 8192), 16, 0, 0); } while (0)
; #define PG8_LDA(dst, b, h) do { _Pragma("unroll") for (int m = 0; m < 4; ++m) _Pragma("unroll") for (int k = 0; k < 2; ++k) dst[m][k] = *(const LAS bf16x8*)(lds + PG8_SA(b, h) + aoff + m * 2048 + k * 1024); } while (0)
; #define PG8_MMA(ai, bj, At, Bt) do { __builtin_amdgcn_s_setprio(1); _Pragma("unroll") for (int m = 0; m < 4; ++m) _Pragma("unroll") for (int n = 0; n < 2; ++n) _Pragma("unroll") for (int k = 0; k < 2; ++k) \
;         acc[ai][bj][m][n] = __builtin_amdgcn_mfma_f32_16x16x32_bf16(Bt[n][k], At[m][k], acc[ai][bj][m][n], 0, 0, 0); __builtin_amdgcn_s_setprio(0); } while (0)
; #define PG8_WAIT_V(n) asm volatile("s_waitcnt vmcnt(" #n ")" ::: "memory")
; #define PG8_WAIT_L(n) asm volatile("s_waitcnt lgkmcnt(" #n ")" ::: "memory")
; #define PG8_BAR __builtin_amdgcn_s_barrier()
; #define PG8_SCHED __builtin_amdgcn_sched_barrier(0)
; template <class Epi, class Order = StaticOrder, bool HALFN = false>
; __device__ __forceinline__ void gemm_phase(LAS unsigned char* lds, const Gemm g, const Epi& E) {
;     ...
;             PG8_LDA(At, 1, 1); PG8_STAGE(PG8_SB(1, 0), b3, voffB); PG8_STAGE(PG8_SB(1, 1), b3 + hstepB, voffB); PG8_STAGE(PG8_SA(1, 0), a3, voffA);
;             PG8_WAIT_V(8); PG8_WAIT_L(0); PG8_BAR; PG8_MMA(1, 0, At, B0); if constexpr (!HALFN) PG8_MMA(1, 1, At, B1); PG8_BAR; PG8_SCHED;
;         }
;         if (wr == 0) PG8_BAR;
	s_add_i32 s6, s30, s10
	v_lshl_add_u64 v[236:237], v[236:237], 0, s[60:61]
	s_mov_b32 m0, s6
	ds_read_b128 v[184:187], v144 offset:49152
	ds_read_b128 v[208:211], v144 offset:50176
	ds_read_b128 v[212:215], v144 offset:51200
	ds_read_b128 v[216:219], v144 offset:52224
	ds_read_b128 v[220:223], v144 offset:53248
	ds_read_b128 v[224:227], v144 offset:54272
	ds_read_b128 v[228:231], v144 offset:55296
	ds_read_b128 v[232:235], v144 offset:56320
	global_load_lds_dwordx4 v[236:237], off sc0
	s_add_i32 m0, s6, 0x2000
	s_add_u32 s4, s4, 0x80080
	v_lshl_add_u64 v[236:237], v[238:239], 0, s[60:61]
	s_addc_u32 s5, s5, 0
	s_add_i32 s6, s31, s10
	global_load_lds_dwordx4 v[236:237], off sc0
	v_lshl_add_u64 v[236:237], s[4:5], 0, v[132:133]
	s_mov_b32 m0, s6
	s_nop 0
	global_load_lds_dwordx4 v[236:237], off sc0
	v_lshl_add_u64 v[236:237], s[4:5], 0, v[136:137]
	s_add_i32 m0, s6, 0x2000
	s_nop 0
	global_load_lds_dwordx4 v[236:237], off sc0
	v_lshl_add_u64 v[236:237], v[240:241], 0, s[60:61]
	s_mov_b32 m0, s20
	s_nop 0
	global_load_lds_dwordx4 v[236:237], off sc0
	v_lshl_add_u64 v[236:237], v[242:243], 0, s[60:61]
	s_mov_b32 m0, s21
	s_nop 0
	global_load_lds_dwordx4 v[236:237], off sc0
	s_waitcnt vmcnt(8)
	s_waitcnt lgkmcnt(0)
	s_barrier
	s_setprio 1
	s_waitcnt lgkmcnt(0)
	v_mfma_f32_16x16x32_bf16 v[62:65], v[146:149], v[184:187], v[62:65]
	v_mfma_f32_16x16x32_bf16 v[70:73], v[154:157], v[184:187], v[70:73]
	v_mfma_f32_16x16x32_bf16 v[82:85], v[146:149], v[212:215], v[82:85]
	v_mfma_f32_16x16x32_bf16 v[86:89], v[154:157], v[212:215], v[86:89]
	v_mfma_f32_16x16x32_bf16 v[90:93], v[146:149], v[220:223], v[90:93]
	v_mfma_f32_16x16x32_bf16 v[94:97], v[154:157], v[220:223], v[94:97]
	v_mfma_f32_16x16x32_bf16 v[98:101], v[146:149], v[228:231], v[98:101]
	v_mfma_f32_16x16x32_bf16 v[106:109], v[154:157], v[228:231], v[106:109]
	v_mfma_f32_16x16x32_bf16 v[62:65], v[150:153], v[208:211], v[62:65]
	v_mfma_f32_16x16x32_bf16 v[70:73], v[158:161], v[208:211], v[70:73]
	v_mfma_f32_16x16x32_bf16 v[82:85], v[150:153], v[216:219], v[82:85]
	v_mfma_f32_16x16x32_bf16 v[86:89], v[158:161], v[216:219], v[86:89]
	v_mfma_f32_16x16x32_bf16 v[90:93], v[150:153], v[224:227], v[90:93]
	v_mfma_f32_16x16x32_bf16 v[94:97], v[158:161], v[224:227], v[94:97]
	v_mfma_f32_16x16x32_bf16 v[98:101], v[150:153], v[232:235], v[98:101]
	v_mfma_f32_16x16x32_bf16 v[106:109], v[158:161], v[232:235], v[106:109]
	s_setprio 0
	s_setprio 1
	v_mfma_f32_16x16x32_bf16 v[74:77], v[168:171], v[184:187], v[74:77]
	v_mfma_f32_16x16x32_bf16 v[78:81], v[176:179], v[184:187], v[78:81]
	v_mfma_f32_16x16x32_bf16 v[102:105], v[168:171], v[212:215], v[102:105]
	v_mfma_f32_16x16x32_bf16 v[110:113], v[176:179], v[212:215], v[110:113]
	v_mfma_f32_16x16x32_bf16 v[114:117], v[168:171], v[220:223], v[114:117]
	v_mfma_f32_16x16x32_bf16 v[118:121], v[176:179], v[220:223], v[118:121]
	v_mfma_f32_16x16x32_bf16 v[122:125], v[168:171], v[228:231], v[122:125]
	v_mfma_f32_16x16x32_bf16 v[126:129], v[176:179], v[228:231], v[126:129]
	v_mfma_f32_16x16x32_bf16 v[74:77], v[172:175], v[208:211], v[74:77]
	v_mfma_f32_16x16x32_bf16 v[78:81], v[180:183], v[208:211], v[78:81]
	v_mfma_f32_16x16x32_bf16 v[102:105], v[172:175], v[216:219], v[102:105]
	v_mfma_f32_16x16x32_bf16 v[110:113], v[180:183], v[216:219], v[110:113]
	v_mfma_f32_16x16x32_bf16 v[114:117], v[172:175], v[224:227], v[114:117]
	v_mfma_f32_16x16x32_bf16 v[118:121], v[180:183], v[224:227], v[118:121]
	v_mfma_f32_16x16x32_bf16 v[122:125], v[172:175], v[232:235], v[122:125]
	v_mfma_f32_16x16x32_bf16 v[126:129], v[180:183], v[232:235], v[126:129]
	s_setprio 0
	s_barrier
	s_add_i32 s29, s29, 2
	s_add_u32 s62, s62, 0x100
	s_addc_u32 s63, s63, 0
	s_add_u32 s27, s27, 0x100
	s_addc_u32 s28, s28, 0
	s_cmp_gt_u32 s29, 29
	s_cbranch_scc0 .LBB0_709
	s_and_b64 vcc, exec, s[44:45]
	s_cbranch_vccz .LBB0_712
	s_barrier

; #define PG8_STAGE(bufoff, gbase, voff) do { _Pragma("unroll") for (int _i = 0; _i < 2; ++_i) \
;         __builtin_amdgcn_global_load_lds((const unsigned*)((const char*)(gbase) + (voff)[_i]), (LAS unsigned*)(lds + (bufoff) + ldsw + _i * 8192), 16, 0, 0); } while (0)
; #define PG8_WAIT_V(n) asm volatile("s_waitcnt vmcnt(" #n ")" ::: "memory")
; #define PG8_BAR __builtin_amdgcn_s_barrier()
; template <class Epi, class Order = StaticOrder, bool HALFN = false>
; __device__ __forceinline__ void gemm_phase(LAS unsigned char* lds, const Gemm g, const Epi& E) {
;     ...
;     const int wid = __builtin_amdgcn_readfirstlane(tid >> 6), lane = tid & 63, wr = wid >> 2, wc = wid & 3, fr = lane & 15, fq = lane >> 4;
;     const int K = g.K, nt = K / BK;
;     Order S; S.init(g.nM, g.nN, (int)gridDim.x, (int)blockIdx.x); S.lx = g.lx; S.lr = g.lr;
;     unsigned voffA[2], voffB[2];
; #pragma unroll
;     for (int i = 0; i < 2; ++i) { int R, C; stage_rc(tid * 16 + i * 8192, R, C); const int Rb = (R & ~31) + perm32(R & 31);
;         voffA[i] = (unsigned)(R * g.lda + C) * 2u; voffB[i] = (unsigned)(Rb * g.ldb + C) * 2u; }
;     const size_t kstep = (size_t)(BK * 2);
;     const size_t hstepA = (size_t)HALF * g.lda * 2, hstepB = (size_t)HALF * g.ldb * 2;
;     const size_t tstepA = 2 * hstepA, tstepB = 2 * hstepB;
;     const unsigned ldsw = (unsigned)wid * 1024u;
;     const int aoff = lds_byte(wr * 64 + fr, fq * 8), boff = lds_byte(wc * 32 + fr, fq * 8);
;     ...
;     const char* cA = (const char*)g.A + (size_t)cur.pm * tstepA + (size_t)cur.pn * g.a_pn_off * 2; const char* cB = (const char*)g.Bt + (size_t)cur.pn * tstepB + (HALFN ? (size_t)(cur.half - 1) * hstepB : (size_t)0);
;     PG8_STAGE(PG8_SB(0, 0), cB, voffB); PG8_STAGE(PG8_SB(0, 1), cB + hstepB, voffB); PG8_STAGE(PG8_SA(0, 0), cA, voffA); PG8_STAGE(PG8_SA(0, 1), cA + hstepA, voffA);
;     if (wr == 1) PG8_BAR;
;     PG8_WAIT_V(2); PG8_BAR;
;     PG8_STAGE(PG8_SB(1, 0), cB + kstep, voffB); PG8_STAGE(PG8_SA(1, 0), cA + kstep, voffA); PG8_STAGE(PG8_SB(1, 1), cB + hstepB + kstep, voffB);
;     PG8_WAIT_V(6); PG8_BAR;
.LBB0_782:
	v_ashrrev_i32_e32 v2, 31, v10
	v_lshrrev_b32_e32 v2, 26, v2
	v_add_u32_e32 v2, v10, v2
	v_ashrrev_i32_e32 v11, 6, v2
	v_bfe_i32 v2, v10, 27, 1
	v_lshlrev_b32_e32 v1, 4, v10
	v_lshrrev_b32_e32 v2, 22, v2
	v_add_u32_e32 v2, v1, v2
	v_and_b32_e32 v2, 0xfffffc00, v2
	v_sub_u32_e32 v2, v1, v2
	s_waitcnt lgkmcnt(0)
	v_lshrrev_b32_e32 v3, 4, v2
	v_bitop3_b32 v2, v3, v2, 32 bitop3:0x6c
	v_ashrrev_i32_e32 v4, 31, v2
	v_lshrrev_b32_e32 v4, 26, v4
	v_add_u32_e32 v4, v2, v4
	s_mov_b32 s79, s57
	v_lshlrev_b32_e32 v3, 3, v11
	v_ashrrev_i32_e32 v12, 6, v4
	v_and_b32_e32 v4, 0xc0, v4
	s_lshl_b64 s[4:5], s[78:79], 23
	v_readlane_b32 s6, v251, 38
	v_and_b32_e32 v3, -16, v3
	v_sub_u32_e32 v2, v2, v4
	s_add_u32 s8, s6, s4
	v_readlane_b32 s4, v251, 43
	v_add_u32_e32 v3, v12, v3
	v_ashrrev_i16_sdwa v2, v190, sext(v2) dst_sel:DWORD dst_unused:UNUSED_PAD src0_sel:DWORD src1_sel:BYTE_0
	s_addc_u32 s9, s4, s5
	v_lshlrev_b32_e32 v5, 5, v11
	v_bfe_i32 v13, v2, 0, 16
	v_lshlrev_b32_e32 v2, 1, v3
	v_lshrrev_b32_e32 v4, 2, v3
	v_and_b32_e32 v6, 3, v12
	s_mov_b32 s5, 0xfffe0
	v_and_b32_e32 v5, 32, v5
	v_and_b32_e32 v2, 24, v2
	v_and_b32_e32 v4, 4, v4
	v_and_or_b32 v6, v3, s5, v6
	v_or3_b32 v2, v6, v4, v2
	v_add_lshl_u32 v4, v5, v13, 1
	v_add_u32_e32 v1, 0x2000, v1
	v_lshl_add_u32 v170, v2, 12, v4
	v_ashrrev_i32_e32 v2, 31, v1
	v_lshrrev_b32_e32 v2, 22, v2
	v_add_u32_e32 v2, v1, v2
	v_ashrrev_i32_e32 v14, 10, v2
	v_mul_i32_i24_e32 v2, 0x400, v14
	v_sub_u32_e32 v1, v1, v2
	v_lshrrev_b32_e32 v2, 4, v1
	v_bitop3_b32 v1, v2, v1, 32 bitop3:0x6c
	v_lshl_add_u32 v168, v3, 12, v4
	v_ashrrev_i32_e32 v3, 31, v1
	v_lshrrev_b32_e32 v3, 26, v3
	v_lshlrev_b32_e32 v2, 3, v14
	v_add_u32_e32 v3, v1, v3
	v_and_b32_e32 v2, -16, v2
	v_ashrrev_i32_e32 v15, 6, v3
	v_add_u32_e32 v2, v15, v2
	v_and_b32_e32 v5, 3, v15
	v_and_b32_e32 v3, 0xc0, v3
	v_and_or_b32 v5, v2, s5, v5
	s_ashr_i32 s5, s22, 6
	s_ashr_i32 s95, s94, 31
	s_ashr_i32 s93, s92, 31
	s_ashr_i32 s4, s22, 8
	v_sub_u32_e32 v1, v1, v3
	s_lshl_b32 s10, s5, 10
	s_lshl_b64 s[6:7], s[94:95], 20
	s_lshl_b64 s[16:17], s[92:93], 20
	v_ashrrev_i16_sdwa v1, v190, sext(v1) dst_sel:DWORD dst_unused:UNUSED_PAD src0_sel:DWORD src1_sel:BYTE_0
	s_add_u32 s80, s8, s16
	v_lshlrev_b32_e32 v4, 5, v14
	v_bfe_i32 v16, v1, 0, 16
	v_lshlrev_b32_e32 v1, 1, v2
	v_lshrrev_b32_e32 v3, 2, v2
	s_addc_u32 s81, s9, s17
	s_add_i32 s11, s10, 0
	v_and_b32_e32 v4, 32, v4
	v_and_b32_e32 v1, 24, v1
	v_and_b32_e32 v3, 4, v3
	s_add_i32 m0, s11, 0x10000
	v_or3_b32 v1, v5, v3, v1
	v_add_lshl_u32 v3, v4, v16, 1
	global_load_lds_dwordx4 v170, s[80:81] sc0
	s_add_i32 m0, s11, 0x12000
	v_lshl_add_u32 v174, v1, 12, v3
	s_add_u32 s16, s80, 0x80000
	global_load_lds_dwordx4 v174, s[80:81] sc0
	s_addc_u32 s17, s81, 0
	s_add_i32 m0, s11, 0x14000
	v_lshl_add_u32 v172, v2, 12, v3
	global_load_lds_dwordx4 v170, s[16:17] sc0
	s_add_i32 m0, s11, 0x16000
	s_add_u32 s42, s66, s6
	s_addc_u32 s43, s67, s7
	s_add_i32 s15, s11, 0x2000
	global_load_lds_dwordx4 v174, s[16:17] sc0
	s_mov_b32 m0, s11
	s_add_u32 s6, s42, 0x80000
	global_load_lds_dwordx4 v168, s[42:43] sc0
	s_mov_b32 m0, s15
	s_addc_u32 s7, s43, 0
	s_add_i32 s16, s11, 0x4000
	global_load_lds_dwordx4 v172, s[42:43] sc0
	s_mov_b32 m0, s16
	s_add_i32 s17, s11, 0x6000
	global_load_lds_dwordx4 v168, s[6:7] sc0
	s_mov_b32 m0, s17
	v_mov_b32_e32 v171, v0
	global_load_lds_dwordx4 v172, s[6:7] sc0
	v_mov_b32_e32 v175, v0
	v_mov_b32_e32 v169, v0
	v_mov_b32_e32 v173, v0
	s_cmp_eq_u32 s4, 1
	v_lshl_add_u64 v[8:9], s[80:81], 0, v[170:171]
	v_lshl_add_u64 v[6:7], s[80:81], 0, v[174:175]
	v_lshl_add_u64 v[2:3], s[42:43], 0, v[168:169]
	s_cselect_b64 s[40:41], -1, 0
	s_cmp_lg_u32 s4, 1
	v_lshl_add_u64 v[4:5], s[42:43], 0, v[172:173]
	s_cbranch_scc1 .LBB0_784
	s_barrier
.LBB0_784:
	s_lshl_b64 s[6:7], s[78:79], 25
	v_readlane_b32 s18, v251, 21
	s_add_u32 s44, s18, s6
	v_readlane_b32 s6, v251, 22
	s_addc_u32 s45, s6, s7
	s_lshl_b32 s56, s78, 13
	v_readlane_b32 s24, v251, 39
	s_lshl_b64 s[6:7], s[56:57], 2
	v_readlane_b32 s26, v251, 41
	v_readlane_b32 s27, v251, 42
	s_add_u32 s6, s26, s6
	s_addc_u32 s7, s27, s7
	v_bfe_u32 v208, v10, 4, 2
	s_add_u32 s46, s6, 0x8000
	v_and_b32_e32 v1, 15, v10
	v_lshlrev_b32_e32 v17, 4, v208
	v_lshlrev_b32_e32 v10, 2, v10
	s_addc_u32 s47, s7, 0
	s_lshl_b32 s18, s4, 6
	v_lshl_or_b32 v17, v1, 6, v17
	s_lshl_b32 s4, s4, 13
	v_and_b32_e32 v10, 32, v10
	v_bitop3_b32 v18, v17, s4, v10 bitop3:0xde
	s_lshl_b32 s4, s5, 5
	s_and_b32 s19, s4, 0x60
	s_add_i32 m0, s11, 0x18000
	v_lshl_add_u64 v[8:9], v[8:9], 0, s[60:61]
	s_lshl_b32 s4, s19, 7
	s_waitcnt vmcnt(2)
	s_barrier
	global_load_lds_dwordx4 v[8:9], off sc0
	v_lshl_add_u64 v[6:7], v[6:7], 0, s[60:61]
	s_add_i32 m0, s11, 0x1a000
	s_add_i32 s20, s11, 0x8000
	s_add_i32 s21, s11, 0xa000
	v_bitop3_b32 v209, v17, s4, v10 bitop3:0xde
	global_load_lds_dwordx4 v[6:7], off sc0
	v_lshl_add_u64 v[2:3], v[2:3], 0, s[60:61]
	s_mov_b32 m0, s20
	s_add_u32 s4, s80, 0x80080
	global_load_lds_dwordx4 v[2:3], off sc0
	v_lshl_add_u64 v[2:3], v[4:5], 0, s[60:61]
	s_mov_b32 m0, s21
	s_addc_u32 s5, s81, 0
	global_load_lds_dwordx4 v[2:3], off sc0
	s_add_i32 m0, s11, 0x1c000
	v_lshl_add_u64 v[2:3], s[4:5], 0, v[170:171]
	global_load_lds_dwordx4 v[2:3], off sc0
	v_lshl_add_u64 v[2:3], s[4:5], 0, v[174:175]
	s_add_i32 m0, s11, 0x1e000
	s_cmpk_lt_u32 s22, 0x100
	global_load_lds_dwordx4 v[2:3], off sc0
	v_lshlrev_b32_e32 v2, 15, v11
	v_and_b32_e32 v2, 0xffff0000, v2
	v_lshl_add_u32 v2, v12, 12, v2
	v_and_b32_e32 v3, 1, v11
	v_lshl_or_b32 v2, v3, 6, v2
	v_lshl_add_u32 v176, v13, 1, v2
	v_lshlrev_b32_e32 v2, 15, v14
	v_and_b32_e32 v2, 0xffff0000, v2
	s_waitcnt vmcnt(6)
	v_lshl_add_u32 v2, v15, 12, v2
	v_and_b32_e32 v3, 1, v14
	v_lshl_or_b32 v2, v3, 6, v2
	s_cselect_b64 s[48:49], -1, 0
	v_mov_b32_e32 v177, v0
	v_lshl_add_u32 v178, v16, 1, v2
	v_mov_b32_e32 v179, v0
	s_mov_b32 s22, 0
	v_add_u32_e32 v210, 0, v18
	v_readlane_b32 s25, v251, 40
	s_barrier
	s_branch .LBB0_787

; #define PG8_STAGE(bufoff, gbase, voff) do { _Pragma("unroll") for (int _i = 0; _i < 2; ++_i) \
;         __builtin_amdgcn_global_load_lds((const unsigned*)((const char*)(gbase) + (voff)[_i]), (LAS unsigned*)(lds + (bufoff) + ldsw + _i * 8192), 16, 0, 0); } while (0)
; #define PG8_LDA(dst, b, h) do { _Pragma("unroll") for (int m = 0; m < 4; ++m) _Pragma("unroll") for (int k = 0; k < 2; ++k) dst[m][k] = *(const LAS bf16x8*)(lds + PG8_SA(b, h) + aoff + m * 2048 + k * 1024); } while (0)
; #define PG8_LDB(dst, b, h) do { _Pragma("unroll") for (int n = 0; n < 2; ++n) _Pragma("unroll") for (int k = 0; k < 2; ++k) dst[n][k] = *(const LAS bf16x8*)(lds + PG8_SB(b, h) + boff + n * 2048 + k * 1024); } while (0)
; #define PG8_MMA(ai, bj, At, Bt) do { __builtin_amdgcn_s_setprio(1); _Pragma("unroll") for (int m = 0; m < 4; ++m) _Pragma("unroll") for (int n = 0; n < 2; ++n) _Pragma("unroll") for (int k = 0; k < 2; ++k) \
;         acc[ai][bj][m][n] = __builtin_amdgcn_mfma_f32_16x16x32_bf16(Bt[n][k], At[m][k], acc[ai][bj][m][n], 0, 0, 0); __builtin_amdgcn_s_setprio(0); } while (0)
; #define PG8_WAIT_V(n) asm volatile("s_waitcnt vmcnt(" #n ")" ::: "memory")
; #define PG8_WAIT_L(n) asm volatile("s_waitcnt lgkmcnt(" #n ")" ::: "memory")
; #define PG8_BAR __builtin_amdgcn_s_barrier()
; #define PG8_SCHED __builtin_amdgcn_sched_barrier(0)
; template <class Epi, class Order = StaticOrder, bool HALFN = false>
; __device__ __forceinline__ void gemm_phase(LAS unsigned char* lds, const Gemm g, const Epi& E) {
;     ...
;             const char* a1 = cA + (size_t)(t + 1) * kstep;
;             const char* a2 = last ? nA : cA + (size_t)(t + 2) * kstep; const char* b2 = last ? nB : cB + (size_t)(t + 2) * kstep;
;             const char* a3 = a2 + kstep; const char* b3 = b2 + kstep;
;             PG8_LDB(B0, 0, 0); if constexpr (!HALFN) PG8_LDB(B1, 0, 1); PG8_SCHED; PG8_LDA(At, 0, 0); PG8_STAGE(PG8_SA(1, 1), a1 + hstepA, voffA);
;             PG8_WAIT_V(8); PG8_WAIT_L(0); PG8_BAR; PG8_MMA(0, 0, At, B0); if constexpr (!HALFN) PG8_MMA(0, 1, At, B1); PG8_BAR; PG8_SCHED;
;             PG8_LDA(At, 0, 1); PG8_STAGE(PG8_SB(0, 0), b2, voffB); PG8_STAGE(PG8_SB(0, 1), b2 + hstepB, voffB); PG8_STAGE(PG8_SA(0, 0), a2, voffA);
;             PG8_WAIT_V(8); PG8_WAIT_L(0); PG8_BAR; PG8_MMA(1, 0, At, B0); if constexpr (!HALFN) PG8_MMA(1, 1, At, B1); PG8_BAR; PG8_SCHED;
.LBB0_799:
	s_add_u32 s4, s62, 0xfff80080
	s_addc_u32 s5, s63, -1
	s_add_i32 s30, 0, 0x10000
	s_cmp_eq_u32 s29, 28
	s_cselect_b32 s7, s23, s5
	s_cselect_b32 s6, s24, s4
	s_cselect_b32 s5, s25, s28
	s_cselect_b32 s4, s26, s27
	s_add_i32 s34, 0, 0x14000
	v_add_u32_e32 v142, s30, v209
	v_add_u32_e32 v158, s34, v209
	ds_read_b128 v[122:125], v142
	ds_read_b128 v[130:133], v142 offset:1024
	ds_read_b128 v[138:141], v142 offset:2048
	ds_read_b128 v[142:145], v142 offset:3072
	ds_read_b128 v[146:149], v158
	ds_read_b128 v[150:153], v158 offset:1024
	ds_read_b128 v[154:157], v158 offset:2048
	ds_read_b128 v[158:161], v158 offset:3072
	v_lshl_add_u64 v[236:237], s[62:63], 0, v[176:177]
	s_add_i32 m0, s11, 0xc000
	ds_read_b128 v[180:183], v210
	ds_read_b128 v[184:187], v210 offset:1024
	ds_read_b128 v[212:215], v210 offset:2048
	ds_read_b128 v[216:219], v210 offset:3072
	ds_read_b128 v[220:223], v210 offset:4096
	ds_read_b128 v[224:227], v210 offset:5120
	ds_read_b128 v[228:231], v210 offset:6144
	ds_read_b128 v[232:235], v210 offset:7168
	global_load_lds_dwordx4 v[236:237], off sc0
	v_lshl_add_u64 v[236:237], s[62:63], 0, v[178:179]
	s_add_i32 m0, s11, 0xe000
	s_nop 0
	global_load_lds_dwordx4 v[236:237], off sc0
	s_waitcnt vmcnt(8)
	s_waitcnt lgkmcnt(0)
	s_barrier
	s_setprio 1
	s_waitcnt lgkmcnt(0)
	v_mfma_f32_16x16x32_bf16 v[134:137], v[122:125], v[180:183], v[134:137]
	v_mfma_f32_16x16x32_bf16 v[126:129], v[138:141], v[180:183], v[126:129]
	v_mfma_f32_16x16x32_bf16 v[110:113], v[122:125], v[212:215], v[110:113]
	v_mfma_f32_16x16x32_bf16 v[106:109], v[138:141], v[212:215], v[106:109]
	v_mfma_f32_16x16x32_bf16 v[94:97], v[122:125], v[220:223], v[94:97]
	v_mfma_f32_16x16x32_bf16 v[90:93], v[138:141], v[220:223], v[90:93]
	v_mfma_f32_16x16x32_bf16 v[78:81], v[122:125], v[228:231], v[78:81]
	v_mfma_f32_16x16x32_bf16 v[74:77], v[138:141], v[228:231], v[74:77]
	v_mfma_f32_16x16x32_bf16 v[134:137], v[130:133], v[184:187], v[134:137]
	v_mfma_f32_16x16x32_bf16 v[126:129], v[142:145], v[184:187], v[126:129]
	v_mfma_f32_16x16x32_bf16 v[110:113], v[130:133], v[216:219], v[110:113]
	v_mfma_f32_16x16x32_bf16 v[106:109], v[142:145], v[216:219], v[106:109]
	v_mfma_f32_16x16x32_bf16 v[94:97], v[130:133], v[224:227], v[94:97]
	v_mfma_f32_16x16x32_bf16 v[90:93], v[142:145], v[224:227], v[90:93]
	v_mfma_f32_16x16x32_bf16 v[78:81], v[130:133], v[232:235], v[78:81]
	v_mfma_f32_16x16x32_bf16 v[74:77], v[142:145], v[232:235], v[74:77]
	s_setprio 0
	s_setprio 1
	v_mfma_f32_16x16x32_bf16 v[118:121], v[146:149], v[180:183], v[118:121]
	v_mfma_f32_16x16x32_bf16 v[114:117], v[154:157], v[180:183], v[114:117]
	v_mfma_f32_16x16x32_bf16 v[102:105], v[146:149], v[212:215], v[102:105]
	v_mfma_f32_16x16x32_bf16 v[98:101], v[154:157], v[212:215], v[98:101]
	v_mfma_f32_16x16x32_bf16 v[86:89], v[146:149], v[220:223], v[86:89]
	v_mfma_f32_16x16x32_bf16 v[82:85], v[154:157], v[220:223], v[82:85]
	v_mfma_f32_16x16x32_bf16 v[70:73], v[146:149], v[228:231], v[70:73]
	v_mfma_f32_16x16x32_bf16 v[66:69], v[154:157], v[228:231], v[66:69]
	v_mfma_f32_16x16x32_bf16 v[118:121], v[150:153], v[184:187], v[118:121]
	v_mfma_f32_16x16x32_bf16 v[114:117], v[158:161], v[184:187], v[114:117]
	v_mfma_f32_16x16x32_bf16 v[102:105], v[150:153], v[216:219], v[102:105]
	v_mfma_f32_16x16x32_bf16 v[98:101], v[158:161], v[216:219], v[98:101]
	v_mfma_f32_16x16x32_bf16 v[86:89], v[150:153], v[224:227], v[86:89]
	v_mfma_f32_16x16x32_bf16 v[82:85], v[158:161], v[224:227], v[82:85]
	v_mfma_f32_16x16x32_bf16 v[70:73], v[150:153], v[232:235], v[70:73]
	v_mfma_f32_16x16x32_bf16 v[66:69], v[158:161], v[232:235], v[66:69]
	s_setprio 0
	s_barrier
	s_add_i32 s30, s30, s10
	v_lshl_add_u64 v[236:237], s[4:5], 0, v[170:171]
	s_mov_b32 m0, s30
	ds_read_b128 v[180:183], v210 offset:16384
	ds_read_b128 v[184:187], v210 offset:17408
	ds_read_b128 v[212:215], v210 offset:18432
	ds_read_b128 v[216:219], v210 offset:19456
	ds_read_b128 v[220:223], v210 offset:20480
	ds_read_b128 v[224:227], v210 offset:21504
	ds_read_b128 v[228:231], v210 offset:22528
	ds_read_b128 v[232:235], v210 offset:23552
	global_load_lds_dwordx4 v[236:237], off sc0
	s_add_i32 m0, s30, 0x2000
	s_add_u32 s30, s4, 0x80000
	v_lshl_add_u64 v[238:239], s[4:5], 0, v[174:175]
	s_addc_u32 s31, s5, 0
	s_add_i32 s34, s34, s10
	global_load_lds_dwordx4 v[238:239], off sc0
	v_lshl_add_u64 v[240:241], s[30:31], 0, v[170:171]
	s_mov_b32 m0, s34
	v_lshl_add_u64 v[242:243], s[6:7], 0, v[172:173]
	global_load_lds_dwordx4 v[240:241], off sc0
	v_lshl_add_u64 v[240:241], s[30:31], 0, v[174:175]
	s_add_i32 m0, s34, 0x2000
	s_nop 0
	global_load_lds_dwordx4 v[240:241], off sc0
	v_lshl_add_u64 v[240:241], s[6:7], 0, v[168:169]
	s_mov_b32 m0, s11
	s_nop 0
	global_load_lds_dwordx4 v[240:241], off sc0
	s_mov_b32 m0, s15
	s_nop 0
	global_load_lds_dwordx4 v[242:243], off sc0
	s_waitcnt vmcnt(8)
	s_waitcnt lgkmcnt(0)
	s_barrier
; #define PG8_STAGE(bufoff, gbase, voff) do { _Pragma("unroll") for (int _i = 0; _i < 2; ++_i) \
;         __builtin_amdgcn_global_load_lds((const unsigned*)((const char*)(gbase) + (voff)[_i]), (LAS unsigned*)(lds + (bufoff) + ldsw + _i * 8192), 16, 0, 0); } while (0)
; #define PG8_LDA(dst, b, h) do { _Pragma("unroll") for (int m = 0; m < 4; ++m) _Pragma("unroll") for (int k = 0; k < 2; ++k) dst[m][k] = *(const LAS bf16x8*)(lds + PG8_SA(b, h) + aoff + m * 2048 + k * 1024); } while (0)
; #define PG8_LDB(dst, b, h) do { _Pragma("unroll") for (int n = 0; n < 2; ++n) _Pragma("unroll") for (int k = 0; k < 2; ++k) dst[n][k] = *(const LAS bf16x8*)(lds + PG8_SB(b, h) + boff + n * 2048 + k * 1024); } while (0)
; #define PG8_MMA(ai, bj, At, Bt) do { __builtin_amdgcn_s_setprio(1); _Pragma("unroll") for (int m = 0; m < 4; ++m) _Pragma("unroll") for (int n = 0; n < 2; ++n) _Pragma("unroll") for (int k = 0; k < 2; ++k) \
;         acc[ai][bj][m][n] = __builtin_amdgcn_mfma_f32_16x16x32_bf16(Bt[n][k], At[m][k], acc[ai][bj][m][n], 0, 0, 0); __builtin_amdgcn_s_setprio(0); } while (0)
; #define PG8_WAIT_V(n) asm volatile("s_waitcnt vmcnt(" #n ")" ::: "memory")
; #define PG8_WAIT_L(n) asm volatile("s_waitcnt lgkmcnt(" #n ")" ::: "memory")
; #define PG8_BAR __builtin_amdgcn_s_barrier()
; #define PG8_SCHED __builtin_amdgcn_sched_barrier(0)
; template <class Epi, class Order = StaticOrder, bool HALFN = false>
; __device__ __forceinline__ void gemm_phase(LAS unsigned char* lds, const Gemm g, const Epi& E) {
;     ...
;             PG8_WAIT_V(8); PG8_WAIT_L(0); PG8_BAR; PG8_MMA(1, 0, At, B0); if constexpr (!HALFN) PG8_MMA(1, 1, At, B1); PG8_BAR; PG8_SCHED;
;             PG8_LDB(B0, 1, 0); if constexpr (!HALFN) PG8_LDB(B1, 1, 1); PG8_SCHED; PG8_LDA(At, 1, 0); PG8_STAGE(PG8_SA(0, 1), a2 + hstepA, voffA);
;             PG8_WAIT_V(8); PG8_WAIT_L(0); PG8_BAR; PG8_MMA(0, 0, At, B0); if constexpr (!HALFN) PG8_MMA(0, 1, At, B1); PG8_BAR; PG8_SCHED;
	s_setprio 1
	s_waitcnt lgkmcnt(0)
	v_mfma_f32_16x16x32_bf16 v[62:65], v[122:125], v[180:183], v[62:65]
	v_mfma_f32_16x16x32_bf16 v[58:61], v[138:141], v[180:183], v[58:61]
	v_mfma_f32_16x16x32_bf16 v[46:49], v[122:125], v[212:215], v[46:49]
	v_mfma_f32_16x16x32_bf16 v[42:45], v[138:141], v[212:215], v[42:45]
	v_mfma_f32_16x16x32_bf16 v[30:33], v[122:125], v[220:223], v[30:33]
	v_mfma_f32_16x16x32_bf16 v[26:29], v[138:141], v[220:223], v[26:29]
	v_mfma_f32_16x16x32_bf16 v[14:17], v[122:125], v[228:231], v[14:17]
	v_mfma_f32_16x16x32_bf16 v[10:13], v[138:141], v[228:231], v[10:13]
	v_mfma_f32_16x16x32_bf16 v[62:65], v[130:133], v[184:187], v[62:65]
	v_mfma_f32_16x16x32_bf16 v[58:61], v[142:145], v[184:187], v[58:61]
	v_mfma_f32_16x16x32_bf16 v[46:49], v[130:133], v[216:219], v[46:49]
	v_mfma_f32_16x16x32_bf16 v[42:45], v[142:145], v[216:219], v[42:45]
	v_mfma_f32_16x16x32_bf16 v[30:33], v[130:133], v[224:227], v[30:33]
	v_mfma_f32_16x16x32_bf16 v[26:29], v[142:145], v[224:227], v[26:29]
	v_mfma_f32_16x16x32_bf16 v[14:17], v[130:133], v[232:235], v[14:17]
	v_mfma_f32_16x16x32_bf16 v[10:13], v[142:145], v[232:235], v[10:13]
	s_setprio 0
	s_setprio 1
	v_mfma_f32_16x16x32_bf16 v[54:57], v[146:149], v[180:183], v[54:57]
	v_mfma_f32_16x16x32_bf16 v[50:53], v[154:157], v[180:183], v[50:53]
	v_mfma_f32_16x16x32_bf16 v[38:41], v[146:149], v[212:215], v[38:41]
	v_mfma_f32_16x16x32_bf16 v[34:37], v[154:157], v[212:215], v[34:37]
	v_mfma_f32_16x16x32_bf16 v[22:25], v[146:149], v[220:223], v[22:25]
	v_mfma_f32_16x16x32_bf16 v[18:21], v[154:157], v[220:223], v[18:21]
	v_mfma_f32_16x16x32_bf16 v[6:9], v[146:149], v[228:231], v[6:9]
	v_mfma_f32_16x16x32_bf16 v[2:5], v[154:157], v[228:231], v[2:5]
	v_mfma_f32_16x16x32_bf16 v[54:57], v[150:153], v[184:187], v[54:57]
	v_mfma_f32_16x16x32_bf16 v[50:53], v[158:161], v[184:187], v[50:53]
	v_mfma_f32_16x16x32_bf16 v[38:41], v[150:153], v[216:219], v[38:41]
	v_mfma_f32_16x16x32_bf16 v[34:37], v[158:161], v[216:219], v[34:37]
	v_mfma_f32_16x16x32_bf16 v[22:25], v[150:153], v[224:227], v[22:25]
	v_mfma_f32_16x16x32_bf16 v[18:21], v[158:161], v[224:227], v[18:21]
	v_mfma_f32_16x16x32_bf16 v[6:9], v[150:153], v[232:235], v[6:9]
	v_mfma_f32_16x16x32_bf16 v[2:5], v[158:161], v[232:235], v[2:5]
	s_setprio 0
	s_barrier
	s_add_i32 s30, 0, 0x18000
	s_add_i32 s31, 0, 0x1c000
	v_add_u32_e32 v142, s30, v209
	v_add_u32_e32 v158, s31, v209
	ds_read_b128 v[122:125], v142
	ds_read_b128 v[130:133], v142 offset:1024
	ds_read_b128 v[138:141], v142 offset:2048
	ds_read_b128 v[142:145], v142 offset:3072
	ds_read_b128 v[146:149], v158
	ds_read_b128 v[150:153], v158 offset:1024
	ds_read_b128 v[154:157], v158 offset:2048
	ds_read_b128 v[158:161], v158 offset:3072
	s_add_u32 s6, s6, 0x80000
	s_addc_u32 s7, s7, 0
	s_mov_b32 m0, s16
	v_lshl_add_u64 v[244:245], s[6:7], 0, v[168:169]
	ds_read_b128 v[180:183], v210 offset:32768
	ds_read_b128 v[184:187], v210 offset:33792
	ds_read_b128 v[212:215], v210 offset:34816
	ds_read_b128 v[216:219], v210 offset:35840
	ds_read_b128 v[220:223], v210 offset:36864
	ds_read_b128 v[224:227], v210 offset:37888
	ds_read_b128 v[228:231], v210 offset:38912
	ds_read_b128 v[232:235], v210 offset:39936
	global_load_lds_dwordx4 v[244:245], off sc0
	v_lshl_add_u64 v[244:245], s[6:7], 0, v[172:173]
	s_mov_b32 m0, s17
	s_nop 0
	global_load_lds_dwordx4 v[244:245], off sc0
	s_waitcnt vmcnt(8)
	s_waitcnt lgkmcnt(0)
	s_barrier
	s_setprio 1
	s_waitcnt lgkmcnt(0)
	v_mfma_f32_16x16x32_bf16 v[134:137], v[122:125], v[180:183], v[134:137]
	v_mfma_f32_16x16x32_bf16 v[126:129], v[138:141], v[180:183], v[126:129]
	v_mfma_f32_16x16x32_bf16 v[110:113], v[122:125], v[212:215], v[110:113]
	v_mfma_f32_16x16x32_bf16 v[106:109], v[138:141], v[212:215], v[106:109]
	v_mfma_f32_16x16x32_bf16 v[94:97], v[122:125], v[220:223], v[94:97]
	v_mfma_f32_16x16x32_bf16 v[90:93], v[138:141], v[220:223], v[90:93]
	v_mfma_f32_16x16x32_bf16 v[78:81], v[122:125], v[228:231], v[78:81]
	v_mfma_f32_16x16x32_bf16 v[74:77], v[138:141], v[228:231], v[74:77]
	v_mfma_f32_16x16x32_bf16 v[134:137], v[130:133], v[184:187], v[134:137]
	v_mfma_f32_16x16x32_bf16 v[126:129], v[142:145], v[184:187], v[126:129]
	v_mfma_f32_16x16x32_bf16 v[110:113], v[130:133], v[216:219], v[110:113]
	v_mfma_f32_16x16x32_bf16 v[106:109], v[142:145], v[216:219], v[106:109]
	v_mfma_f32_16x16x32_bf16 v[94:97], v[130:133], v[224:227], v[94:97]
	v_mfma_f32_16x16x32_bf16 v[90:93], v[142:145], v[224:227], v[90:93]
	v_mfma_f32_16x16x32_bf16 v[78:81], v[130:133], v[232:235], v[78:81]
	v_mfma_f32_16x16x32_bf16 v[74:77], v[142:145], v[232:235], v[74:77]
	s_setprio 0
	s_setprio 1
	v_mfma_f32_16x16x32_bf16 v[118:121], v[146:149], v[180:183], v[118:121]
	v_mfma_f32_16x16x32_bf16 v[114:117], v[154:157], v[180:183], v[114:117]
	v_mfma_f32_16x16x32_bf16 v[102:105], v[146:149], v[212:215], v[102:105]
	v_mfma_f32_16x16x32_bf16 v[98:101], v[154:157], v[212:215], v[98:101]
	v_mfma_f32_16x16x32_bf16 v[86:89], v[146:149], v[220:223], v[86:89]
	v_mfma_f32_16x16x32_bf16 v[82:85], v[154:157], v[220:223], v[82:85]
	v_mfma_f32_16x16x32_bf16 v[70:73], v[146:149], v[228:231], v[70:73]
	v_mfma_f32_16x16x32_bf16 v[66:69], v[154:157], v[228:231], v[66:69]
	v_mfma_f32_16x16x32_bf16 v[118:121], v[150:153], v[184:187], v[118:121]
	v_mfma_f32_16x16x32_bf16 v[114:117], v[158:161], v[184:187], v[114:117]
	v_mfma_f32_16x16x32_bf16 v[102:105], v[150:153], v[216:219], v[102:105]
	v_mfma_f32_16x16x32_bf16 v[98:101], v[158:161], v[216:219], v[98:101]
	v_mfma_f32_16x16x32_bf16 v[86:89], v[150:153], v[224:227], v[86:89]
	v_mfma_f32_16x16x32_bf16 v[82:85], v[158:161], v[224:227], v[82:85]
	v_mfma_f32_16x16x32_bf16 v[70:73], v[150:153], v[232:235], v[70:73]
	v_mfma_f32_16x16x32_bf16 v[66:69], v[158:161], v[232:235], v[66:69]
	s_setprio 0
	s_barrier
; #define PG8_STAGE(bufoff, gbase, voff) do { _Pragma("unroll") for (int _i = 0; _i < 2; ++_i) \
;         __builtin_amdgcn_global_load_lds((const unsigned*)((const char*)(gbase) + (voff)[_i]), (LAS unsigned*)(lds + (bufoff) + ldsw + _i * 8192), 16, 0, 0); } while (0)
; #define PG8_LDA(dst, b, h) do { _Pragma("unroll") for (int m = 0; m < 4; ++m) _Pragma("unroll") for (int k = 0; k < 2; ++k) dst[m][k] = *(const LAS bf16x8*)(lds + PG8_SA(b, h) + aoff + m * 2048 + k * 1024); } while (0)
; #define PG8_MMA(ai, bj, At, Bt) do { __builtin_amdgcn_s_setprio(1); _Pragma("unroll") for (int m = 0; m < 4; ++m) _Pragma("unroll") for (int n = 0; n < 2; ++n) _Pragma("unroll") for (int k = 0; k < 2; ++k) \
;         acc[ai][bj][m][n] = __builtin_amdgcn_mfma_f32_16x16x32_bf16(Bt[n][k], At[m][k], acc[ai][bj][m][n], 0, 0, 0); __builtin_amdgcn_s_setprio(0); } while (0)
; #define PG8_WAIT_V(n) asm volatile("s_waitcnt vmcnt(" #n ")" ::: "memory")
; #define PG8_WAIT_L(n) asm volatile("s_waitcnt lgkmcnt(" #n ")" ::: "memory")
; #define PG8_BAR __builtin_amdgcn_s_barrier()
; #define PG8_SCHED __builtin_amdgcn_sched_barrier(0)
; template <class Epi, class Order = StaticOrder, bool HALFN = false>
; __device__ __forceinline__ void gemm_phase(LAS unsigned char* lds, const Gemm g, const Epi& E) {
;     ...
;             PG8_LDA(At, 1, 1); PG8_STAGE(PG8_SB(1, 0), b3, voffB); PG8_STAGE(PG8_SB(1, 1), b3 + hstepB, voffB); PG8_STAGE(PG8_SA(1, 0), a3, voffA);
;             PG8_WAIT_V(8); PG8_WAIT_L(0); PG8_BAR; PG8_MMA(1, 0, At, B0); if constexpr (!HALFN) PG8_MMA(1, 1, At, B1); PG8_BAR; PG8_SCHED;
;         }
;         if (wr == 0) PG8_BAR;
	s_add_i32 s6, s30, s10
	v_lshl_add_u64 v[236:237], v[236:237], 0, s[60:61]
	s_mov_b32 m0, s6
	ds_read_b128 v[180:183], v210 offset:49152
	ds_read_b128 v[184:187], v210 offset:50176
	ds_read_b128 v[212:215], v210 offset:51200
	ds_read_b128 v[216:219], v210 offset:52224
	ds_read_b128 v[220:223], v210 offset:53248
	ds_read_b128 v[224:227], v210 offset:54272
	ds_read_b128 v[228:231], v210 offset:55296
	ds_read_b128 v[232:235], v210 offset:56320
	global_load_lds_dwordx4 v[236:237], off sc0
	s_add_i32 m0, s6, 0x2000
	s_add_u32 s4, s4, 0x80080
	v_lshl_add_u64 v[236:237], v[238:239], 0, s[60:61]
	s_addc_u32 s5, s5, 0
	s_add_i32 s6, s31, s10
	global_load_lds_dwordx4 v[236:237], off sc0
	v_lshl_add_u64 v[236:237], s[4:5], 0, v[170:171]
	s_mov_b32 m0, s6
	s_nop 0
	global_load_lds_dwordx4 v[236:237], off sc0
	v_lshl_add_u64 v[236:237], s[4:5], 0, v[174:175]
	s_add_i32 m0, s6, 0x2000
	s_nop 0
	global_load_lds_dwordx4 v[236:237], off sc0
	v_lshl_add_u64 v[236:237], v[240:241], 0, s[60:61]
	s_mov_b32 m0, s20
	s_nop 0
	global_load_lds_dwordx4 v[236:237], off sc0
	v_lshl_add_u64 v[236:237], v[242:243], 0, s[60:61]
	s_mov_b32 m0, s21
	s_nop 0
	global_load_lds_dwordx4 v[236:237], off sc0
	s_waitcnt vmcnt(8)
	s_waitcnt lgkmcnt(0)
	s_barrier
	s_setprio 1
	s_waitcnt lgkmcnt(0)
	v_mfma_f32_16x16x32_bf16 v[62:65], v[122:125], v[180:183], v[62:65]
	v_mfma_f32_16x16x32_bf16 v[58:61], v[138:141], v[180:183], v[58:61]
	v_mfma_f32_16x16x32_bf16 v[46:49], v[122:125], v[212:215], v[46:49]
	v_mfma_f32_16x16x32_bf16 v[42:45], v[138:141], v[212:215], v[42:45]
	v_mfma_f32_16x16x32_bf16 v[30:33], v[122:125], v[220:223], v[30:33]
	v_mfma_f32_16x16x32_bf16 v[26:29], v[138:141], v[220:223], v[26:29]
	v_mfma_f32_16x16x32_bf16 v[14:17], v[122:125], v[228:231], v[14:17]
	v_mfma_f32_16x16x32_bf16 v[10:13], v[138:141], v[228:231], v[10:13]
	v_mfma_f32_16x16x32_bf16 v[62:65], v[130:133], v[184:187], v[62:65]
	v_mfma_f32_16x16x32_bf16 v[58:61], v[142:145], v[184:187], v[58:61]
	v_mfma_f32_16x16x32_bf16 v[46:49], v[130:133], v[216:219], v[46:49]
	v_mfma_f32_16x16x32_bf16 v[42:45], v[142:145], v[216:219], v[42:45]
	v_mfma_f32_16x16x32_bf16 v[30:33], v[130:133], v[224:227], v[30:33]
	v_mfma_f32_16x16x32_bf16 v[26:29], v[142:145], v[224:227], v[26:29]
	v_mfma_f32_16x16x32_bf16 v[14:17], v[130:133], v[232:235], v[14:17]
	v_mfma_f32_16x16x32_bf16 v[10:13], v[142:145], v[232:235], v[10:13]
	s_setprio 0
	s_setprio 1
	v_mfma_f32_16x16x32_bf16 v[54:57], v[146:149], v[180:183], v[54:57]
	v_mfma_f32_16x16x32_bf16 v[50:53], v[154:157], v[180:183], v[50:53]
	v_mfma_f32_16x16x32_bf16 v[38:41], v[146:149], v[212:215], v[38:41]
	v_mfma_f32_16x16x32_bf16 v[34:37], v[154:157], v[212:215], v[34:37]
	v_mfma_f32_16x16x32_bf16 v[22:25], v[146:149], v[220:223], v[22:25]
	v_mfma_f32_16x16x32_bf16 v[18:21], v[154:157], v[220:223], v[18:21]
	v_mfma_f32_16x16x32_bf16 v[6:9], v[146:149], v[228:231], v[6:9]
	v_mfma_f32_16x16x32_bf16 v[2:5], v[154:157], v[228:231], v[2:5]
	v_mfma_f32_16x16x32_bf16 v[54:57], v[150:153], v[184:187], v[54:57]
	v_mfma_f32_16x16x32_bf16 v[50:53], v[158:161], v[184:187], v[50:53]
	v_mfma_f32_16x16x32_bf16 v[38:41], v[150:153], v[216:219], v[38:41]
	v_mfma_f32_16x16x32_bf16 v[34:37], v[158:161], v[216:219], v[34:37]
	v_mfma_f32_16x16x32_bf16 v[22:25], v[150:153], v[224:227], v[22:25]
	v_mfma_f32_16x16x32_bf16 v[18:21], v[158:161], v[224:227], v[18:21]
	v_mfma_f32_16x16x32_bf16 v[6:9], v[150:153], v[232:235], v[6:9]
	v_mfma_f32_16x16x32_bf16 v[2:5], v[158:161], v[232:235], v[2:5]
	s_setprio 0
	s_barrier
	s_add_i32 s29, s29, 2
	s_add_u32 s62, s62, 0x100
	s_addc_u32 s63, s63, 0
	s_add_u32 s27, s27, 0x100
	s_addc_u32 s28, s28, 0
	s_cmp_gt_u32 s29, 29
	s_cbranch_scc0 .LBB0_799
	s_and_b64 vcc, exec, s[48:49]
	s_cbranch_vccz .LBB0_802
	s_barrier
